# NSA: every v_pk_mul_f32 (online-softmax rescale of the O accumulators) split into two v_mul_f32 (bit-identical; packed f32 beside MFMAs is an issue-stall anti-lever)
# speedup vs baseline: 1.0030x; 1.0030x over previous
; DI unsigned pk2(float lo, float hi) { f32x2 v = {lo, hi}; bf16x2_t b = __builtin_convertvector(v, bf16x2_t); return __builtin_bit_cast(unsigned, b); }
; DI float lo16(unsigned u) { return __uint_as_float(u << 16); }
; DI float hi16(unsigned u) { return __uint_as_float(u & 0xffff0000u); }
; DI float siluf_(float x) { return x * __builtin_amdgcn_rcpf(1.f + __expf(-x)); }
; DI int opaque_i(int v) { asm volatile("" : "+v"(v)); return v; }
; DI void nsa_block_item(const Params& P, unsigned char* smem_g, int b, int g, int tb, int tid_in) {
;     ...
;     {
;         const int lane2 = opaque_i(lane); const int hh = lane2 >> 5, head = g * 8 + (lane2 & 7); const unsigned tok = (unsigned)(b * TT + t0 + ((lane2 & 31) >> 3));
;         const unsigned poff = tok * (unsigned)LDP, ooff = tok * 4096u + 2048u + (unsigned)head * 128u;
;         const float inv = st.l > 0.f ? g1 / st.l : 0.f;
; #pragma unroll
;         for (int dt = 0; dt < 4; ++dt)
; #pragma unroll
;             for (int ig = 0; ig < 4; ++ig) { const int d0 = 32 * dt + 8 * ig + 4 * hh;
;                 const u32x2 zz = *(const u32x2*)(P_proj + (poff + C_ZNSA + head * 128 + d0)); const u32x2 pv = totw[(dt * 4 + ig) * 64 + lane];
;                 const float o0 = st.acc[dt][4 * ig + 0] * inv + lo16(pv.x), o1 = st.acc[dt][4 * ig + 1] * inv + hi16(pv.x), o2 = st.acc[dt][4 * ig + 2] * inv + lo16(pv.y), o3 = st.acc[dt][4 * ig + 3] * inv + hi16(pv.y);
;                 u32x2 w; w.x = pk2(o0 * siluf_(lo16(zz.x)), o1 * siluf_(hi16(zz.x))); w.y = pk2(o2 * siluf_(lo16(zz.y)), o3 * siluf_(hi16(zz.y)));
;                 *(u32x2*)(P_onsa + (ooff + d0)) = w; }
.LBB0_379:
	s_add_i32 s59, s59, s60
	v_lshrrev_b32_e32 v2, 3, v155
	v_and_or_b32 v0, v155, 7, s58
	v_and_or_b32 v6, v2, 3, s59
	v_mul_lo_u32 v2, v6, s44
	v_lshlrev_b32_e32 v9, 7, v0
	v_ashrrev_i32_e32 v0, 3, v155
	v_and_b32_e32 v8, -4, v0
	v_add3_u32 v7, v9, v2, s55
	v_add_u32_e32 v0, v7, v8
	v_lshl_add_u64 v[2:3], v[0:1], 1, s[30:31]
	global_load_dwordx2 v[14:15], v[2:3], off
	v_and_b32_e32 v0, 0xffff0000, v154
	v_mul_f32_e32 v0, 0xbfb8aa3b, v0
	v_exp_f32_e32 v0, v0
	v_lshlrev_b32_e32 v6, 12, v6
	v_or3_b32 v9, v6, v9, s56
	v_add_u32_e32 v28, 8, v8
	v_add_f32_e32 v6, 1.0, v0
	v_rcp_f32_e32 v6, v6
	v_add_u32_e32 v0, v9, v8
	v_lshl_add_u64 v[18:19], v[0:1], 1, s[28:29]
	v_add_u32_e32 v0, v7, v28
	v_div_scale_f32 v22, s[0:1], v163, v163, v6
	v_rcp_f32_e32 v23, v22
	v_lshl_add_u64 v[20:21], v[0:1], 1, s[30:31]
	v_div_scale_f32 v0, vcc, v6, v163, v6
	v_fma_f32 v24, -v22, v23, 1.0
	v_fmac_f32_e32 v23, v24, v23
	v_mul_f32_e32 v24, v0, v23
	v_fma_f32 v25, -v22, v24, v0
	v_fmac_f32_e32 v24, v25, v23
	v_fma_f32 v0, -v22, v24, v0
	v_div_fmas_f32 v0, v0, v23, v24
	v_div_fixup_f32 v0, v0, v163, v6
	v_cmp_lt_f32_e32 vcc, 0, v163
	ds_read2st64_b64 v[10:13], v157 offset1:1
	ds_read2st64_b64 v[2:5], v157 offset0:2 offset1:3
	v_cndmask_b32_e32 v6, 0, v0, vcc
	s_add_i32 s57, s57, s10
	s_cmpk_lt_i32 s57, 0x800
	s_waitcnt lgkmcnt(0)
	v_lshlrev_b32_e32 v16, 16, v10
	v_and_b32_e32 v17, 0xffff0000, v10
	v_lshlrev_b32_e32 v10, 16, v11
	v_and_b32_e32 v11, 0xffff0000, v11
	v_pk_fma_f32 v[16:17], v[80:81], v[6:7], v[16:17] op_sel_hi:[1,0,1]
	v_pk_fma_f32 v[10:11], v[82:83], v[6:7], v[10:11] op_sel_hi:[1,0,1]
	s_waitcnt vmcnt(0)
	v_lshlrev_b32_e32 v22, 16, v14
	v_and_b32_e32 v23, 0xffff0000, v14
	v_lshlrev_b32_e32 v14, 16, v15
	v_and_b32_e32 v15, 0xffff0000, v15
	v_mul_f32_e32 v0, 0xbfb8aa3b, v22
	v_mul_f32_e32 v24, 0xbfb8aa3b, v23
	v_mul_f32_e32 v25, 0xbfb8aa3b, v14
	v_mul_f32_e32 v26, 0xbfb8aa3b, v15
	v_exp_f32_e32 v0, v0
	v_exp_f32_e32 v24, v24
	v_exp_f32_e32 v25, v25
	v_exp_f32_e32 v26, v26
	v_add_f32_e32 v0, 1.0, v0
	v_add_f32_e32 v27, 1.0, v24
	v_add_f32_e32 v29, 1.0, v25
	v_add_f32_e32 v30, 1.0, v26
	v_rcp_f32_e32 v24, v0
	v_rcp_f32_e32 v25, v27
	v_rcp_f32_e32 v26, v29
	v_rcp_f32_e32 v27, v30
	v_add_u32_e32 v0, v9, v28
	v_mul_f32_e32 v22, v24, v22
	v_mul_f32_e32 v23, v25, v23
	v_mul_f32_e32 v14, v26, v14
	v_mul_f32_e32 v15, v27, v15
	v_mul_f32_e32 v16, v16, v22
	v_mul_f32_e32 v17, v17, v23
	v_mul_f32_e32 v10, v10, v14
	v_mul_f32_e32 v11, v11, v15
	v_cvt_pk_bf16_f32 v14, v16, v17
	v_cvt_pk_bf16_f32 v15, v10, v11
	global_store_dwordx2 v[18:19], v[14:15], off
	global_load_dwordx2 v[10:11], v[20:21], off
	v_add_u32_e32 v26, 16, v8
	v_lshl_add_u64 v[16:17], v[0:1], 1, s[28:29]
	v_add_u32_e32 v0, v7, v26
	v_lshl_add_u64 v[18:19], v[0:1], 1, s[30:31]
	v_lshlrev_b32_e32 v14, 16, v12
	v_and_b32_e32 v15, 0xffff0000, v12
	v_lshlrev_b32_e32 v12, 16, v13
	v_and_b32_e32 v13, 0xffff0000, v13
	v_pk_fma_f32 v[14:15], v[84:85], v[6:7], v[14:15] op_sel_hi:[1,0,1]
	v_pk_fma_f32 v[12:13], v[86:87], v[6:7], v[12:13] op_sel_hi:[1,0,1]
	s_waitcnt vmcnt(0)
	v_lshlrev_b32_e32 v20, 16, v10
	v_and_b32_e32 v21, 0xffff0000, v10
	v_lshlrev_b32_e32 v10, 16, v11
	v_and_b32_e32 v11, 0xffff0000, v11
	v_mul_f32_e32 v0, 0xbfb8aa3b, v20
	v_mul_f32_e32 v22, 0xbfb8aa3b, v21
	v_mul_f32_e32 v23, 0xbfb8aa3b, v10
	v_mul_f32_e32 v24, 0xbfb8aa3b, v11
	v_exp_f32_e32 v0, v0
	v_exp_f32_e32 v22, v22
	v_exp_f32_e32 v23, v23
	v_exp_f32_e32 v24, v24
	v_add_f32_e32 v0, 1.0, v0
	v_add_f32_e32 v25, 1.0, v22
	v_add_f32_e32 v27, 1.0, v23
	v_add_f32_e32 v28, 1.0, v24
	v_rcp_f32_e32 v22, v0
	v_rcp_f32_e32 v23, v25
	v_rcp_f32_e32 v24, v27
	v_rcp_f32_e32 v25, v28
	v_add_u32_e32 v0, v9, v26
	v_mul_f32_e32 v20, v22, v20
	v_mul_f32_e32 v21, v23, v21
	v_add_u32_e32 v28, 40, v8
	v_mul_f32_e32 v10, v24, v10
	v_mul_f32_e32 v11, v25, v11
	v_mul_f32_e32 v14, v14, v20
	v_mul_f32_e32 v15, v15, v21
	v_mul_f32_e32 v10, v12, v10
	v_mul_f32_e32 v11, v13, v11
	v_cvt_pk_bf16_f32 v12, v14, v15
	v_cvt_pk_bf16_f32 v13, v10, v11
	global_store_dwordx2 v[16:17], v[12:13], off
	global_load_dwordx2 v[10:11], v[18:19], off
	v_add_u32_e32 v24, 24, v8
	v_lshl_add_u64 v[14:15], v[0:1], 1, s[28:29]
	v_add_u32_e32 v0, v7, v24
	v_lshl_add_u64 v[16:17], v[0:1], 1, s[30:31]
	v_lshlrev_b32_e32 v12, 16, v2
	v_and_b32_e32 v13, 0xffff0000, v2
	v_lshlrev_b32_e32 v2, 16, v3
	v_and_b32_e32 v3, 0xffff0000, v3
	v_pk_fma_f32 v[12:13], v[88:89], v[6:7], v[12:13] op_sel_hi:[1,0,1]
	v_pk_fma_f32 v[2:3], v[90:91], v[6:7], v[2:3] op_sel_hi:[1,0,1]
	s_waitcnt vmcnt(0)
	v_lshlrev_b32_e32 v18, 16, v10
	v_and_b32_e32 v19, 0xffff0000, v10
	v_lshlrev_b32_e32 v10, 16, v11
	v_and_b32_e32 v11, 0xffff0000, v11
	v_mul_f32_e32 v0, 0xbfb8aa3b, v18
	v_mul_f32_e32 v20, 0xbfb8aa3b, v19
	v_mul_f32_e32 v21, 0xbfb8aa3b, v10
	v_mul_f32_e32 v22, 0xbfb8aa3b, v11
	v_exp_f32_e32 v0, v0
	v_exp_f32_e32 v20, v20
	v_exp_f32_e32 v21, v21
	v_exp_f32_e32 v22, v22
	v_add_f32_e32 v0, 1.0, v0
	v_add_f32_e32 v23, 1.0, v20
	v_add_f32_e32 v25, 1.0, v21
	v_add_f32_e32 v26, 1.0, v22
	v_rcp_f32_e32 v20, v0
	v_rcp_f32_e32 v21, v23
	v_rcp_f32_e32 v22, v25
	v_rcp_f32_e32 v23, v26
	v_add_u32_e32 v0, v9, v24
	v_mul_f32_e32 v18, v20, v18
	v_mul_f32_e32 v19, v21, v19
	v_mul_f32_e32 v10, v22, v10
	v_mul_f32_e32 v11, v23, v11
	v_mul_f32_e32 v12, v12, v18
	v_mul_f32_e32 v13, v13, v19
	v_mul_f32_e32 v2, v2, v10
	v_mul_f32_e32 v3, v3, v11
	v_cvt_pk_bf16_f32 v10, v12, v13
	v_cvt_pk_bf16_f32 v11, v2, v3
	global_store_dwordx2 v[14:15], v[10:11], off
	global_load_dwordx2 v[2:3], v[16:17], off
	v_add_u32_e32 v22, 32, v8
	v_lshl_add_u64 v[12:13], v[0:1], 1, s[28:29]
	v_add_u32_e32 v0, v7, v22
	v_lshl_add_u64 v[14:15], v[0:1], 1, s[30:31]
	v_lshlrev_b32_e32 v10, 16, v4
	v_and_b32_e32 v11, 0xffff0000, v4
	v_lshlrev_b32_e32 v4, 16, v5
	v_and_b32_e32 v5, 0xffff0000, v5
	v_pk_fma_f32 v[10:11], v[92:93], v[6:7], v[10:11] op_sel_hi:[1,0,1]
	v_pk_fma_f32 v[4:5], v[94:95], v[6:7], v[4:5] op_sel_hi:[1,0,1]
	s_waitcnt vmcnt(0)
; DI unsigned pk2(float lo, float hi) { f32x2 v = {lo, hi}; bf16x2_t b = __builtin_convertvector(v, bf16x2_t); return __builtin_bit_cast(unsigned, b); }
; DI float lo16(unsigned u) { return __uint_as_float(u << 16); }
; DI float hi16(unsigned u) { return __uint_as_float(u & 0xffff0000u); }
; DI float siluf_(float x) { return x * __builtin_amdgcn_rcpf(1.f + __expf(-x)); }
; DI int opaque_i(int v) { asm volatile("" : "+v"(v)); return v; }
; DI void nsa_block_item(const Params& P, unsigned char* smem_g, int b, int g, int tb, int tid_in) {
;     ...
;     {
;         const int lane2 = opaque_i(lane); const int hh = lane2 >> 5, head = g * 8 + (lane2 & 7); const unsigned tok = (unsigned)(b * TT + t0 + ((lane2 & 31) >> 3));
;         const unsigned poff = tok * (unsigned)LDP, ooff = tok * 4096u + 2048u + (unsigned)head * 128u;
;         const float inv = st.l > 0.f ? g1 / st.l : 0.f;
; #pragma unroll
;         for (int dt = 0; dt < 4; ++dt)
; #pragma unroll
;             for (int ig = 0; ig < 4; ++ig) { const int d0 = 32 * dt + 8 * ig + 4 * hh;
;                 const u32x2 zz = *(const u32x2*)(P_proj + (poff + C_ZNSA + head * 128 + d0)); const u32x2 pv = totw[(dt * 4 + ig) * 64 + lane];
;                 const float o0 = st.acc[dt][4 * ig + 0] * inv + lo16(pv.x), o1 = st.acc[dt][4 * ig + 1] * inv + hi16(pv.x), o2 = st.acc[dt][4 * ig + 2] * inv + lo16(pv.y), o3 = st.acc[dt][4 * ig + 3] * inv + hi16(pv.y);
;                 u32x2 w; w.x = pk2(o0 * siluf_(lo16(zz.x)), o1 * siluf_(hi16(zz.x))); w.y = pk2(o2 * siluf_(lo16(zz.y)), o3 * siluf_(hi16(zz.y)));
;                 *(u32x2*)(P_onsa + (ooff + d0)) = w; }
	v_lshlrev_b32_e32 v16, 16, v2
	v_and_b32_e32 v17, 0xffff0000, v2
	v_lshlrev_b32_e32 v2, 16, v3
	v_and_b32_e32 v3, 0xffff0000, v3
	v_mul_f32_e32 v0, 0xbfb8aa3b, v16
	v_mul_f32_e32 v18, 0xbfb8aa3b, v17
	v_mul_f32_e32 v19, 0xbfb8aa3b, v2
	v_mul_f32_e32 v20, 0xbfb8aa3b, v3
	v_exp_f32_e32 v0, v0
	v_exp_f32_e32 v18, v18
	v_exp_f32_e32 v19, v19
	v_exp_f32_e32 v20, v20
	v_add_f32_e32 v0, 1.0, v0
	v_add_f32_e32 v21, 1.0, v18
	v_add_f32_e32 v23, 1.0, v19
	v_add_f32_e32 v24, 1.0, v20
	v_rcp_f32_e32 v18, v0
	v_rcp_f32_e32 v19, v21
	v_rcp_f32_e32 v20, v23
	v_rcp_f32_e32 v21, v24
	v_add_u32_e32 v0, v9, v22
	v_mul_f32_e32 v16, v18, v16
	v_mul_f32_e32 v17, v19, v17
	v_lshl_add_u64 v[18:19], v[0:1], 1, s[28:29]
	v_mul_f32_e32 v2, v20, v2
	v_mul_f32_e32 v3, v21, v3
	v_mul_f32_e32 v10, v10, v16
	v_mul_f32_e32 v11, v11, v17
	v_mul_f32_e32 v2, v4, v2
	v_mul_f32_e32 v3, v5, v3
	v_cvt_pk_bf16_f32 v4, v10, v11
	v_cvt_pk_bf16_f32 v5, v2, v3
	global_store_dwordx2 v[12:13], v[4:5], off
	global_load_dwordx2 v[14:15], v[14:15], off
	v_add_u32_e32 v0, v7, v28
	v_lshl_add_u64 v[20:21], v[0:1], 1, s[30:31]
	ds_read2st64_b64 v[2:5], v157 offset0:4 offset1:5
	ds_read2st64_b64 v[10:13], v157 offset0:6 offset1:7
	s_waitcnt lgkmcnt(1)
	v_lshlrev_b32_e32 v16, 16, v2
	v_and_b32_e32 v17, 0xffff0000, v2
	v_lshlrev_b32_e32 v2, 16, v3
	v_and_b32_e32 v3, 0xffff0000, v3
	v_pk_fma_f32 v[16:17], v[64:65], v[6:7], v[16:17] op_sel_hi:[1,0,1]
	v_pk_fma_f32 v[2:3], v[66:67], v[6:7], v[2:3] op_sel_hi:[1,0,1]
	s_waitcnt vmcnt(0)
	v_lshlrev_b32_e32 v22, 16, v14
	v_and_b32_e32 v23, 0xffff0000, v14
	v_lshlrev_b32_e32 v14, 16, v15
	v_and_b32_e32 v15, 0xffff0000, v15
	v_mul_f32_e32 v0, 0xbfb8aa3b, v22
	v_mul_f32_e32 v24, 0xbfb8aa3b, v23
	v_mul_f32_e32 v25, 0xbfb8aa3b, v14
	v_mul_f32_e32 v26, 0xbfb8aa3b, v15
	v_exp_f32_e32 v0, v0
	v_exp_f32_e32 v24, v24
	v_exp_f32_e32 v25, v25
	v_exp_f32_e32 v26, v26
	v_add_f32_e32 v0, 1.0, v0
	v_add_f32_e32 v27, 1.0, v24
	v_add_f32_e32 v29, 1.0, v25
	v_add_f32_e32 v30, 1.0, v26
	v_rcp_f32_e32 v24, v0
	v_rcp_f32_e32 v25, v27
	v_rcp_f32_e32 v26, v29
	v_rcp_f32_e32 v27, v30
	v_add_u32_e32 v0, v9, v28
	v_mul_f32_e32 v22, v24, v22
	v_mul_f32_e32 v23, v25, v23
	v_mul_f32_e32 v14, v26, v14
	v_mul_f32_e32 v15, v27, v15
	v_mul_f32_e32 v16, v16, v22
	v_mul_f32_e32 v17, v17, v23
	v_mul_f32_e32 v2, v2, v14
	v_mul_f32_e32 v3, v3, v15
	v_cvt_pk_bf16_f32 v14, v16, v17
	v_cvt_pk_bf16_f32 v15, v2, v3
	global_store_dwordx2 v[18:19], v[14:15], off
	global_load_dwordx2 v[2:3], v[20:21], off
	v_add_u32_e32 v26, 48, v8
	v_lshl_add_u64 v[16:17], v[0:1], 1, s[28:29]
	v_add_u32_e32 v0, v7, v26
	v_lshl_add_u64 v[18:19], v[0:1], 1, s[30:31]
	v_lshlrev_b32_e32 v14, 16, v4
	v_and_b32_e32 v15, 0xffff0000, v4
	v_lshlrev_b32_e32 v4, 16, v5
	v_and_b32_e32 v5, 0xffff0000, v5
	v_pk_fma_f32 v[14:15], v[68:69], v[6:7], v[14:15] op_sel_hi:[1,0,1]
	v_pk_fma_f32 v[4:5], v[70:71], v[6:7], v[4:5] op_sel_hi:[1,0,1]
	s_waitcnt vmcnt(0)
	v_lshlrev_b32_e32 v20, 16, v2
	v_and_b32_e32 v21, 0xffff0000, v2
	v_lshlrev_b32_e32 v2, 16, v3
	v_and_b32_e32 v3, 0xffff0000, v3
	v_mul_f32_e32 v0, 0xbfb8aa3b, v20
	v_mul_f32_e32 v22, 0xbfb8aa3b, v21
	v_mul_f32_e32 v23, 0xbfb8aa3b, v2
	v_mul_f32_e32 v24, 0xbfb8aa3b, v3
	v_exp_f32_e32 v0, v0
	v_exp_f32_e32 v22, v22
	v_exp_f32_e32 v23, v23
	v_exp_f32_e32 v24, v24
	v_add_f32_e32 v0, 1.0, v0
	v_add_f32_e32 v25, 1.0, v22
	v_add_f32_e32 v27, 1.0, v23
	v_add_f32_e32 v28, 1.0, v24
	v_rcp_f32_e32 v22, v0
	v_rcp_f32_e32 v23, v25
	v_rcp_f32_e32 v24, v27
	v_rcp_f32_e32 v25, v28
	v_add_u32_e32 v0, v9, v26
	v_mul_f32_e32 v20, v22, v20
	v_mul_f32_e32 v21, v23, v21
	v_add_u32_e32 v28, 0x48, v8
	v_mul_f32_e32 v2, v24, v2
	v_mul_f32_e32 v3, v25, v3
	v_mul_f32_e32 v14, v14, v20
	v_mul_f32_e32 v15, v15, v21
	v_mul_f32_e32 v2, v4, v2
	v_mul_f32_e32 v3, v5, v3
	v_cvt_pk_bf16_f32 v4, v14, v15
	v_cvt_pk_bf16_f32 v5, v2, v3
	global_store_dwordx2 v[16:17], v[4:5], off
	global_load_dwordx2 v[2:3], v[18:19], off
	v_add_u32_e32 v24, 56, v8
	v_lshl_add_u64 v[14:15], v[0:1], 1, s[28:29]
	v_add_u32_e32 v0, v7, v24
	v_lshl_add_u64 v[16:17], v[0:1], 1, s[30:31]
	s_waitcnt lgkmcnt(0)
	v_lshlrev_b32_e32 v4, 16, v10
	v_and_b32_e32 v5, 0xffff0000, v10
	v_lshlrev_b32_e32 v10, 16, v11
	v_and_b32_e32 v11, 0xffff0000, v11
	v_pk_fma_f32 v[4:5], v[72:73], v[6:7], v[4:5] op_sel_hi:[1,0,1]
	v_pk_fma_f32 v[10:11], v[74:75], v[6:7], v[10:11] op_sel_hi:[1,0,1]
	s_waitcnt vmcnt(0)
	v_lshlrev_b32_e32 v18, 16, v2
	v_and_b32_e32 v19, 0xffff0000, v2
	v_lshlrev_b32_e32 v2, 16, v3
	v_and_b32_e32 v3, 0xffff0000, v3
	v_mul_f32_e32 v0, 0xbfb8aa3b, v18
	v_mul_f32_e32 v20, 0xbfb8aa3b, v19
	v_mul_f32_e32 v21, 0xbfb8aa3b, v2
	v_mul_f32_e32 v22, 0xbfb8aa3b, v3
	v_exp_f32_e32 v0, v0
	v_exp_f32_e32 v20, v20
	v_exp_f32_e32 v21, v21
	v_exp_f32_e32 v22, v22
	v_add_f32_e32 v0, 1.0, v0
	v_add_f32_e32 v23, 1.0, v20
	v_add_f32_e32 v25, 1.0, v21
	v_add_f32_e32 v26, 1.0, v22
	v_rcp_f32_e32 v20, v0
	v_rcp_f32_e32 v21, v23
	v_rcp_f32_e32 v22, v25
	v_rcp_f32_e32 v23, v26
	v_add_u32_e32 v0, v9, v24
	v_mul_f32_e32 v18, v20, v18
	v_mul_f32_e32 v19, v21, v19
	v_mul_f32_e32 v2, v22, v2
	v_mul_f32_e32 v3, v23, v3
	v_mul_f32_e32 v4, v4, v18
	v_mul_f32_e32 v5, v5, v19
	v_mul_f32_e32 v2, v10, v2
	v_mul_f32_e32 v3, v11, v3
	v_cvt_pk_bf16_f32 v4, v4, v5
	v_cvt_pk_bf16_f32 v5, v2, v3
	global_store_dwordx2 v[14:15], v[4:5], off
	global_load_dwordx2 v[2:3], v[16:17], off
	v_add_u32_e32 v22, 64, v8
	v_lshlrev_b32_e32 v4, 16, v12
	v_and_b32_e32 v5, 0xffff0000, v12
	v_lshlrev_b32_e32 v10, 16, v13
	v_and_b32_e32 v11, 0xffff0000, v13
	v_lshl_add_u64 v[12:13], v[0:1], 1, s[28:29]
	v_add_u32_e32 v0, v7, v22
	v_lshl_add_u64 v[14:15], v[0:1], 1, s[30:31]
	v_pk_fma_f32 v[4:5], v[76:77], v[6:7], v[4:5] op_sel_hi:[1,0,1]
	v_pk_fma_f32 v[10:11], v[78:79], v[6:7], v[10:11] op_sel_hi:[1,0,1]
	s_waitcnt vmcnt(0)
; DI unsigned pk2(float lo, float hi) { f32x2 v = {lo, hi}; bf16x2_t b = __builtin_convertvector(v, bf16x2_t); return __builtin_bit_cast(unsigned, b); }
; DI float lo16(unsigned u) { return __uint_as_float(u << 16); }
; DI float hi16(unsigned u) { return __uint_as_float(u & 0xffff0000u); }
; DI float siluf_(float x) { return x * __builtin_amdgcn_rcpf(1.f + __expf(-x)); }
; DI int opaque_i(int v) { asm volatile("" : "+v"(v)); return v; }
; DI void nsa_block_item(const Params& P, unsigned char* smem_g, int b, int g, int tb, int tid_in) {
;     ...
;     {
;         const int lane2 = opaque_i(lane); const int hh = lane2 >> 5, head = g * 8 + (lane2 & 7); const unsigned tok = (unsigned)(b * TT + t0 + ((lane2 & 31) >> 3));
;         const unsigned poff = tok * (unsigned)LDP, ooff = tok * 4096u + 2048u + (unsigned)head * 128u;
;         const float inv = st.l > 0.f ? g1 / st.l : 0.f;
; #pragma unroll
;         for (int dt = 0; dt < 4; ++dt)
; #pragma unroll
;             for (int ig = 0; ig < 4; ++ig) { const int d0 = 32 * dt + 8 * ig + 4 * hh;
;                 const u32x2 zz = *(const u32x2*)(P_proj + (poff + C_ZNSA + head * 128 + d0)); const u32x2 pv = totw[(dt * 4 + ig) * 64 + lane];
;                 const float o0 = st.acc[dt][4 * ig + 0] * inv + lo16(pv.x), o1 = st.acc[dt][4 * ig + 1] * inv + hi16(pv.x), o2 = st.acc[dt][4 * ig + 2] * inv + lo16(pv.y), o3 = st.acc[dt][4 * ig + 3] * inv + hi16(pv.y);
;                 u32x2 w; w.x = pk2(o0 * siluf_(lo16(zz.x)), o1 * siluf_(hi16(zz.x))); w.y = pk2(o2 * siluf_(lo16(zz.y)), o3 * siluf_(hi16(zz.y)));
;                 *(u32x2*)(P_onsa + (ooff + d0)) = w; }
	v_lshlrev_b32_e32 v16, 16, v2
	v_and_b32_e32 v17, 0xffff0000, v2
	v_lshlrev_b32_e32 v2, 16, v3
	v_and_b32_e32 v3, 0xffff0000, v3
	v_mul_f32_e32 v0, 0xbfb8aa3b, v16
	v_mul_f32_e32 v18, 0xbfb8aa3b, v17
	v_mul_f32_e32 v19, 0xbfb8aa3b, v2
	v_mul_f32_e32 v20, 0xbfb8aa3b, v3
	v_exp_f32_e32 v0, v0
	v_exp_f32_e32 v18, v18
	v_exp_f32_e32 v19, v19
	v_exp_f32_e32 v20, v20
	v_add_f32_e32 v0, 1.0, v0
	v_add_f32_e32 v21, 1.0, v18
	v_add_f32_e32 v23, 1.0, v19
	v_add_f32_e32 v24, 1.0, v20
	v_rcp_f32_e32 v18, v0
	v_rcp_f32_e32 v19, v21
	v_rcp_f32_e32 v20, v23
	v_rcp_f32_e32 v21, v24
	v_add_u32_e32 v0, v9, v22
	v_mul_f32_e32 v16, v18, v16
	v_mul_f32_e32 v17, v19, v17
	v_lshl_add_u64 v[18:19], v[0:1], 1, s[28:29]
	v_mul_f32_e32 v2, v20, v2
	v_mul_f32_e32 v3, v21, v3
	v_mul_f32_e32 v4, v4, v16
	v_mul_f32_e32 v5, v5, v17
	v_mul_f32_e32 v2, v10, v2
	v_mul_f32_e32 v3, v11, v3
	v_cvt_pk_bf16_f32 v4, v4, v5
	v_cvt_pk_bf16_f32 v5, v2, v3
	global_store_dwordx2 v[12:13], v[4:5], off
	global_load_dwordx2 v[14:15], v[14:15], off
	v_add_u32_e32 v0, v7, v28
	v_lshl_add_u64 v[20:21], v[0:1], 1, s[30:31]
	ds_read2st64_b64 v[2:5], v157 offset0:8 offset1:9
	ds_read2st64_b64 v[10:13], v157 offset0:10 offset1:11
	s_waitcnt lgkmcnt(1)
	v_lshlrev_b32_e32 v16, 16, v2
	v_and_b32_e32 v17, 0xffff0000, v2
	v_lshlrev_b32_e32 v2, 16, v3
	v_and_b32_e32 v3, 0xffff0000, v3
	v_pk_fma_f32 v[16:17], v[48:49], v[6:7], v[16:17] op_sel_hi:[1,0,1]
	v_pk_fma_f32 v[2:3], v[50:51], v[6:7], v[2:3] op_sel_hi:[1,0,1]
	s_waitcnt vmcnt(0)
	v_lshlrev_b32_e32 v22, 16, v14
	v_and_b32_e32 v23, 0xffff0000, v14
	v_lshlrev_b32_e32 v14, 16, v15
	v_and_b32_e32 v15, 0xffff0000, v15
	v_mul_f32_e32 v0, 0xbfb8aa3b, v22
	v_mul_f32_e32 v24, 0xbfb8aa3b, v23
	v_mul_f32_e32 v25, 0xbfb8aa3b, v14
	v_mul_f32_e32 v26, 0xbfb8aa3b, v15
	v_exp_f32_e32 v0, v0
	v_exp_f32_e32 v24, v24
	v_exp_f32_e32 v25, v25
	v_exp_f32_e32 v26, v26
	v_add_f32_e32 v0, 1.0, v0
	v_add_f32_e32 v27, 1.0, v24
	v_add_f32_e32 v29, 1.0, v25
	v_add_f32_e32 v30, 1.0, v26
	v_rcp_f32_e32 v24, v0
	v_rcp_f32_e32 v25, v27
	v_rcp_f32_e32 v26, v29
	v_rcp_f32_e32 v27, v30
	v_add_u32_e32 v0, v9, v28
	v_mul_f32_e32 v22, v24, v22
	v_mul_f32_e32 v23, v25, v23
	v_add_u32_e32 v28, 0x68, v8
	v_mul_f32_e32 v14, v26, v14
	v_mul_f32_e32 v15, v27, v15
	v_mul_f32_e32 v16, v16, v22
	v_mul_f32_e32 v17, v17, v23
	v_mul_f32_e32 v2, v2, v14
	v_mul_f32_e32 v3, v3, v15
	v_cvt_pk_bf16_f32 v14, v16, v17
	v_cvt_pk_bf16_f32 v15, v2, v3
	global_store_dwordx2 v[18:19], v[14:15], off
	global_load_dwordx2 v[2:3], v[20:21], off
	v_lshl_add_u64 v[16:17], v[0:1], 1, s[28:29]
	v_lshlrev_b32_e32 v14, 16, v4
	v_and_b32_e32 v15, 0xffff0000, v4
	v_lshlrev_b32_e32 v4, 16, v5
	v_and_b32_e32 v5, 0xffff0000, v5
	v_pk_fma_f32 v[14:15], v[52:53], v[6:7], v[14:15] op_sel_hi:[1,0,1]
	v_pk_fma_f32 v[4:5], v[54:55], v[6:7], v[4:5] op_sel_hi:[1,0,1]
	v_add_u32_e32 v26, 0x50, v8
	s_waitcnt vmcnt(0)
	v_lshlrev_b32_e32 v18, 16, v2
	v_and_b32_e32 v19, 0xffff0000, v2
	v_lshlrev_b32_e32 v2, 16, v3
	v_and_b32_e32 v3, 0xffff0000, v3
	v_mul_f32_e32 v0, 0xbfb8aa3b, v18
	v_mul_f32_e32 v20, 0xbfb8aa3b, v19
	v_mul_f32_e32 v21, 0xbfb8aa3b, v2
	v_mul_f32_e32 v22, 0xbfb8aa3b, v3
	v_exp_f32_e32 v0, v0
	v_exp_f32_e32 v20, v20
	v_exp_f32_e32 v21, v21
	v_exp_f32_e32 v22, v22
	v_add_f32_e32 v0, 1.0, v0
	v_add_f32_e32 v23, 1.0, v20
	v_add_f32_e32 v24, 1.0, v21
	v_add_f32_e32 v25, 1.0, v22
	v_rcp_f32_e32 v20, v0
	v_rcp_f32_e32 v21, v23
	v_rcp_f32_e32 v22, v24
	v_rcp_f32_e32 v23, v25
	v_add_u32_e32 v0, v7, v26
	v_mul_f32_e32 v18, v20, v18
	v_mul_f32_e32 v19, v21, v19
	v_lshl_add_u64 v[24:25], v[0:1], 1, s[30:31]
	v_mul_f32_e32 v2, v22, v2
	v_mul_f32_e32 v3, v23, v3
	v_mul_f32_e32 v14, v14, v18
	v_mul_f32_e32 v15, v15, v19
	v_mul_f32_e32 v2, v4, v2
	v_mul_f32_e32 v3, v5, v3
	v_cvt_pk_bf16_f32 v4, v14, v15
	v_cvt_pk_bf16_f32 v5, v2, v3
	global_store_dwordx2 v[16:17], v[4:5], off
	global_load_dwordx2 v[2:3], v[24:25], off
	v_add_u32_e32 v0, v9, v26
	v_lshl_add_u64 v[14:15], v[0:1], 1, s[28:29]
	s_waitcnt lgkmcnt(0)
	v_lshlrev_b32_e32 v4, 16, v10
	v_and_b32_e32 v5, 0xffff0000, v10
	v_lshlrev_b32_e32 v10, 16, v11
	v_and_b32_e32 v11, 0xffff0000, v11
	v_pk_fma_f32 v[4:5], v[56:57], v[6:7], v[4:5] op_sel_hi:[1,0,1]
	v_pk_fma_f32 v[10:11], v[58:59], v[6:7], v[10:11] op_sel_hi:[1,0,1]
	v_add_u32_e32 v24, 0x58, v8
	s_waitcnt vmcnt(0)
	v_lshlrev_b32_e32 v16, 16, v2
	v_and_b32_e32 v17, 0xffff0000, v2
	v_lshlrev_b32_e32 v2, 16, v3
	v_and_b32_e32 v3, 0xffff0000, v3
	v_mul_f32_e32 v0, 0xbfb8aa3b, v16
	v_mul_f32_e32 v18, 0xbfb8aa3b, v17
	v_mul_f32_e32 v19, 0xbfb8aa3b, v2
	v_mul_f32_e32 v20, 0xbfb8aa3b, v3
	v_exp_f32_e32 v0, v0
	v_exp_f32_e32 v18, v18
	v_exp_f32_e32 v19, v19
	v_exp_f32_e32 v20, v20
	v_add_f32_e32 v0, 1.0, v0
	v_add_f32_e32 v21, 1.0, v18
	v_add_f32_e32 v22, 1.0, v19
	v_add_f32_e32 v23, 1.0, v20
	v_rcp_f32_e32 v18, v0
	v_rcp_f32_e32 v19, v21
	v_rcp_f32_e32 v20, v22
	v_rcp_f32_e32 v21, v23
	v_add_u32_e32 v0, v7, v24
	v_mul_f32_e32 v16, v18, v16
	v_mul_f32_e32 v17, v19, v17
	v_lshl_add_u64 v[22:23], v[0:1], 1, s[30:31]
	v_mul_f32_e32 v2, v20, v2
	v_mul_f32_e32 v3, v21, v3
	v_mul_f32_e32 v4, v4, v16
	v_mul_f32_e32 v5, v5, v17
	v_mul_f32_e32 v2, v10, v2
	v_mul_f32_e32 v3, v11, v3
	v_cvt_pk_bf16_f32 v4, v4, v5
	v_cvt_pk_bf16_f32 v5, v2, v3
	global_store_dwordx2 v[14:15], v[4:5], off
	global_load_dwordx2 v[2:3], v[22:23], off
	v_add_u32_e32 v0, v9, v24
	v_lshlrev_b32_e32 v4, 16, v12
	v_and_b32_e32 v5, 0xffff0000, v12
	v_lshlrev_b32_e32 v10, 16, v13
	v_and_b32_e32 v11, 0xffff0000, v13
	v_lshl_add_u64 v[12:13], v[0:1], 1, s[28:29]
	v_pk_fma_f32 v[4:5], v[60:61], v[6:7], v[4:5] op_sel_hi:[1,0,1]
	v_pk_fma_f32 v[10:11], v[62:63], v[6:7], v[10:11] op_sel_hi:[1,0,1]
	v_add_u32_e32 v22, 0x60, v8
	s_waitcnt vmcnt(0)
; DI unsigned pk2(float lo, float hi) { f32x2 v = {lo, hi}; bf16x2_t b = __builtin_convertvector(v, bf16x2_t); return __builtin_bit_cast(unsigned, b); }
; DI float lo16(unsigned u) { return __uint_as_float(u << 16); }
; DI float hi16(unsigned u) { return __uint_as_float(u & 0xffff0000u); }
; DI float siluf_(float x) { return x * __builtin_amdgcn_rcpf(1.f + __expf(-x)); }
; DI int opaque_i(int v) { asm volatile("" : "+v"(v)); return v; }
; DI void nsa_block_item(const Params& P, unsigned char* smem_g, int b, int g, int tb, int tid_in) {
;     ...
;     {
;         const int lane2 = opaque_i(lane); const int hh = lane2 >> 5, head = g * 8 + (lane2 & 7); const unsigned tok = (unsigned)(b * TT + t0 + ((lane2 & 31) >> 3));
;         const unsigned poff = tok * (unsigned)LDP, ooff = tok * 4096u + 2048u + (unsigned)head * 128u;
;         const float inv = st.l > 0.f ? g1 / st.l : 0.f;
; #pragma unroll
;         for (int dt = 0; dt < 4; ++dt)
; #pragma unroll
;             for (int ig = 0; ig < 4; ++ig) { const int d0 = 32 * dt + 8 * ig + 4 * hh;
;                 const u32x2 zz = *(const u32x2*)(P_proj + (poff + C_ZNSA + head * 128 + d0)); const u32x2 pv = totw[(dt * 4 + ig) * 64 + lane];
;                 const float o0 = st.acc[dt][4 * ig + 0] * inv + lo16(pv.x), o1 = st.acc[dt][4 * ig + 1] * inv + hi16(pv.x), o2 = st.acc[dt][4 * ig + 2] * inv + lo16(pv.y), o3 = st.acc[dt][4 * ig + 3] * inv + hi16(pv.y);
;                 u32x2 w; w.x = pk2(o0 * siluf_(lo16(zz.x)), o1 * siluf_(hi16(zz.x))); w.y = pk2(o2 * siluf_(lo16(zz.y)), o3 * siluf_(hi16(zz.y)));
;                 *(u32x2*)(P_onsa + (ooff + d0)) = w; }
	v_lshlrev_b32_e32 v14, 16, v2
	v_and_b32_e32 v15, 0xffff0000, v2
	v_lshlrev_b32_e32 v2, 16, v3
	v_and_b32_e32 v3, 0xffff0000, v3
	v_mul_f32_e32 v0, 0xbfb8aa3b, v14
	v_mul_f32_e32 v16, 0xbfb8aa3b, v15
	v_mul_f32_e32 v17, 0xbfb8aa3b, v2
	v_mul_f32_e32 v18, 0xbfb8aa3b, v3
	v_exp_f32_e32 v0, v0
	v_exp_f32_e32 v16, v16
	v_exp_f32_e32 v17, v17
	v_exp_f32_e32 v18, v18
	v_add_f32_e32 v0, 1.0, v0
	v_add_f32_e32 v19, 1.0, v16
	v_add_f32_e32 v20, 1.0, v17
	v_add_f32_e32 v21, 1.0, v18
	v_rcp_f32_e32 v16, v0
	v_rcp_f32_e32 v17, v19
	v_rcp_f32_e32 v18, v20
	v_rcp_f32_e32 v19, v21
	v_add_u32_e32 v0, v7, v22
	v_mul_f32_e32 v14, v16, v14
	v_mul_f32_e32 v15, v17, v15
	v_lshl_add_u64 v[20:21], v[0:1], 1, s[30:31]
	v_mul_f32_e32 v2, v18, v2
	v_mul_f32_e32 v3, v19, v3
	v_mul_f32_e32 v4, v4, v14
	v_mul_f32_e32 v5, v5, v15
	v_mul_f32_e32 v2, v10, v2
	v_mul_f32_e32 v3, v11, v3
	v_cvt_pk_bf16_f32 v4, v4, v5
	v_cvt_pk_bf16_f32 v5, v2, v3
	global_store_dwordx2 v[12:13], v[4:5], off
	global_load_dwordx2 v[14:15], v[20:21], off
	v_add_u32_e32 v0, v9, v22
	v_lshl_add_u64 v[18:19], v[0:1], 1, s[28:29]
	ds_read2st64_b64 v[2:5], v157 offset0:12 offset1:13
	ds_read2st64_b64 v[10:13], v157 offset0:14 offset1:15
	s_waitcnt lgkmcnt(1)
	v_lshlrev_b32_e32 v16, 16, v2
	v_and_b32_e32 v17, 0xffff0000, v2
	v_lshlrev_b32_e32 v2, 16, v3
	v_and_b32_e32 v3, 0xffff0000, v3
	v_pk_fma_f32 v[16:17], v[32:33], v[6:7], v[16:17] op_sel_hi:[1,0,1]
	v_pk_fma_f32 v[2:3], v[34:35], v[6:7], v[2:3] op_sel_hi:[1,0,1]
	s_waitcnt vmcnt(0)
	v_lshlrev_b32_e32 v20, 16, v14
	v_and_b32_e32 v21, 0xffff0000, v14
	v_lshlrev_b32_e32 v14, 16, v15
	v_and_b32_e32 v15, 0xffff0000, v15
	v_mul_f32_e32 v0, 0xbfb8aa3b, v20
	v_mul_f32_e32 v22, 0xbfb8aa3b, v21
	v_mul_f32_e32 v23, 0xbfb8aa3b, v14
	v_mul_f32_e32 v24, 0xbfb8aa3b, v15
	v_exp_f32_e32 v0, v0
	v_exp_f32_e32 v22, v22
	v_exp_f32_e32 v23, v23
	v_exp_f32_e32 v24, v24
	v_add_f32_e32 v0, 1.0, v0
	v_add_f32_e32 v25, 1.0, v22
	v_add_f32_e32 v26, 1.0, v23
	v_add_f32_e32 v27, 1.0, v24
	v_rcp_f32_e32 v22, v0
	v_rcp_f32_e32 v23, v25
	v_rcp_f32_e32 v24, v26
	v_rcp_f32_e32 v25, v27
	v_add_u32_e32 v0, v7, v28
	v_mul_f32_e32 v20, v22, v20
	v_mul_f32_e32 v21, v23, v21
	v_lshl_add_u64 v[26:27], v[0:1], 1, s[30:31]
	v_mul_f32_e32 v14, v24, v14
	v_mul_f32_e32 v15, v25, v15
	v_mul_f32_e32 v16, v16, v20
	v_mul_f32_e32 v17, v17, v21
	v_mul_f32_e32 v2, v2, v14
	v_mul_f32_e32 v3, v3, v15
	v_cvt_pk_bf16_f32 v14, v16, v17
	v_cvt_pk_bf16_f32 v15, v2, v3
	global_store_dwordx2 v[18:19], v[14:15], off
	global_load_dwordx2 v[2:3], v[26:27], off
	v_add_u32_e32 v0, v9, v28
	v_lshl_add_u64 v[16:17], v[0:1], 1, s[28:29]
	v_lshlrev_b32_e32 v14, 16, v4
	v_and_b32_e32 v15, 0xffff0000, v4
	v_lshlrev_b32_e32 v4, 16, v5
	v_and_b32_e32 v5, 0xffff0000, v5
	v_pk_fma_f32 v[14:15], v[36:37], v[6:7], v[14:15] op_sel_hi:[1,0,1]
	v_pk_fma_f32 v[4:5], v[38:39], v[6:7], v[4:5] op_sel_hi:[1,0,1]
	v_add_u32_e32 v26, 0x70, v8
	v_add_u32_e32 v8, 0x78, v8
	s_waitcnt vmcnt(0)
	v_lshlrev_b32_e32 v18, 16, v2
	v_and_b32_e32 v19, 0xffff0000, v2
	v_lshlrev_b32_e32 v2, 16, v3
	v_and_b32_e32 v3, 0xffff0000, v3
	v_mul_f32_e32 v0, 0xbfb8aa3b, v18
	v_mul_f32_e32 v20, 0xbfb8aa3b, v19
	v_mul_f32_e32 v21, 0xbfb8aa3b, v2
	v_mul_f32_e32 v22, 0xbfb8aa3b, v3
	v_exp_f32_e32 v0, v0
	v_exp_f32_e32 v20, v20
	v_exp_f32_e32 v21, v21
	v_exp_f32_e32 v22, v22
	v_add_f32_e32 v0, 1.0, v0
	v_add_f32_e32 v23, 1.0, v20
	v_add_f32_e32 v24, 1.0, v21
	v_add_f32_e32 v25, 1.0, v22
	v_rcp_f32_e32 v20, v0
	v_rcp_f32_e32 v21, v23
	v_rcp_f32_e32 v22, v24
	v_rcp_f32_e32 v23, v25
	v_add_u32_e32 v0, v7, v26
	v_mul_f32_e32 v18, v20, v18
	v_mul_f32_e32 v19, v21, v19
	v_lshl_add_u64 v[24:25], v[0:1], 1, s[30:31]
	v_mul_f32_e32 v2, v22, v2
	v_mul_f32_e32 v3, v23, v3
	v_mul_f32_e32 v14, v14, v18
	v_mul_f32_e32 v15, v15, v19
	v_mul_f32_e32 v2, v4, v2
	v_mul_f32_e32 v3, v5, v3
	v_cvt_pk_bf16_f32 v4, v14, v15
	v_cvt_pk_bf16_f32 v5, v2, v3
	global_store_dwordx2 v[16:17], v[4:5], off
	global_load_dwordx2 v[2:3], v[24:25], off
	v_add_u32_e32 v0, v9, v26
	v_lshl_add_u64 v[14:15], v[0:1], 1, s[28:29]
	s_waitcnt lgkmcnt(0)
	v_lshlrev_b32_e32 v4, 16, v10
	v_and_b32_e32 v5, 0xffff0000, v10
	v_lshlrev_b32_e32 v10, 16, v11
	v_and_b32_e32 v11, 0xffff0000, v11
	v_pk_fma_f32 v[4:5], v[40:41], v[6:7], v[4:5] op_sel_hi:[1,0,1]
	v_pk_fma_f32 v[10:11], v[42:43], v[6:7], v[10:11] op_sel_hi:[1,0,1]
	s_waitcnt vmcnt(0)
	v_lshlrev_b32_e32 v16, 16, v2
	v_and_b32_e32 v17, 0xffff0000, v2
	v_lshlrev_b32_e32 v2, 16, v3
	v_and_b32_e32 v3, 0xffff0000, v3
	v_mul_f32_e32 v0, 0xbfb8aa3b, v16
	v_mul_f32_e32 v18, 0xbfb8aa3b, v17
	v_mul_f32_e32 v19, 0xbfb8aa3b, v2
	v_mul_f32_e32 v20, 0xbfb8aa3b, v3
	v_exp_f32_e32 v0, v0
	v_exp_f32_e32 v18, v18
	v_exp_f32_e32 v19, v19
	v_exp_f32_e32 v20, v20
	v_add_f32_e32 v0, 1.0, v0
	v_add_f32_e32 v21, 1.0, v18
	v_add_f32_e32 v22, 1.0, v19
	v_add_f32_e32 v23, 1.0, v20
	v_rcp_f32_e32 v18, v0
	v_rcp_f32_e32 v19, v21
	v_rcp_f32_e32 v20, v22
	v_rcp_f32_e32 v21, v23
	v_add_u32_e32 v0, v7, v8
	v_mul_f32_e32 v16, v18, v16
	v_mul_f32_e32 v17, v19, v17
	v_lshl_add_u64 v[22:23], v[0:1], 1, s[30:31]
	v_mul_f32_e32 v2, v20, v2
	v_mul_f32_e32 v3, v21, v3
	v_mul_f32_e32 v4, v4, v16
	v_mul_f32_e32 v5, v5, v17
	v_mul_f32_e32 v2, v10, v2
	v_mul_f32_e32 v3, v11, v3
	v_cvt_pk_bf16_f32 v4, v4, v5
	v_cvt_pk_bf16_f32 v5, v2, v3
	global_store_dwordx2 v[14:15], v[4:5], off
	global_load_dwordx2 v[2:3], v[22:23], off
	v_lshlrev_b32_e32 v4, 16, v12
	v_and_b32_e32 v5, 0xffff0000, v12
	v_lshlrev_b32_e32 v10, 16, v13
	v_and_b32_e32 v11, 0xffff0000, v13
	v_pk_fma_f32 v[4:5], v[44:45], v[6:7], v[4:5] op_sel_hi:[1,0,1]
	v_pk_fma_f32 v[6:7], v[46:47], v[6:7], v[10:11] op_sel_hi:[1,0,1]
	s_waitcnt vmcnt(0)
	v_lshlrev_b32_e32 v10, 16, v2
	v_and_b32_e32 v11, 0xffff0000, v2
	v_lshlrev_b32_e32 v2, 16, v3
	v_and_b32_e32 v3, 0xffff0000, v3
	v_mul_f32_e32 v0, 0xbfb8aa3b, v10
	v_mul_f32_e32 v12, 0xbfb8aa3b, v11
	v_mul_f32_e32 v13, 0xbfb8aa3b, v2
	v_mul_f32_e32 v14, 0xbfb8aa3b, v3
	v_exp_f32_e32 v0, v0
	v_exp_f32_e32 v12, v12
	v_exp_f32_e32 v13, v13
	v_exp_f32_e32 v14, v14
	v_add_f32_e32 v0, 1.0, v0
	v_add_f32_e32 v15, 1.0, v12
	v_add_f32_e32 v16, 1.0, v13
	v_add_f32_e32 v17, 1.0, v14
	v_rcp_f32_e32 v12, v0
	v_rcp_f32_e32 v13, v15
	v_rcp_f32_e32 v14, v16
	v_rcp_f32_e32 v15, v17
	v_add_u32_e32 v0, v9, v8
	v_mul_f32_e32 v10, v12, v10
	v_mul_f32_e32 v11, v13, v11
	v_lshl_add_u64 v[8:9], v[0:1], 1, s[28:29]
	v_mul_f32_e32 v2, v14, v2
	v_mul_f32_e32 v3, v15, v3
	v_mul_f32_e32 v4, v4, v10
	v_mul_f32_e32 v5, v5, v11
	v_mul_f32_e32 v2, v6, v2
	v_mul_f32_e32 v3, v7, v3
	v_cvt_pk_bf16_f32 v4, v4, v5
	v_cvt_pk_bf16_f32 v5, v2, v3
	global_store_dwordx2 v[8:9], v[4:5], off
	s_cbranch_scc0 .LBB0_562
; DI void nsa_block_item(const Params& P, unsigned char* smem_g, int b, int g, int tb, int tid_in) {
;     ...
;     const int tid = opaque_i(tid_in), lane = tid & 63, wave = __builtin_amdgcn_readfirstlane(tid >> 6);
;     const int l32 = lane & 31, hh = lane >> 5; const int tki = l32 >> 3, head = g * 8 + (l32 & 7);
;     const int t0b = tb * 32, t0 = t0b + 4 * wave, tq = t0 + tki;
;     const unsigned tok = (unsigned)(b * TT + tq); const unsigned poff = tok * (unsigned)LDP; const unsigned ooff = tok * 4096u + 2048u + (unsigned)head * 128u;
;     const int ka = l32 * 256 + 16 * (hh ^ (l32 & 15)), vb = 8192 + l32 * 64 + 8 * hh + 16 * ((l32 >> 2) & 3);
;     LAS unsigned char* ring = sm + CO_RING; LAS u32x2* totw = (LAS u32x2*)(sm + CO_TOT + wave * 8192);
;     LAS float* psum = (LAS float*)(sm + CO_SCR + wave * 2560); LAS unsigned* vals = (LAS unsigned*)(sm + CO_SCR + wave * 2560 + 2048);
;     LAS unsigned* list1 = (LAS unsigned*)(sm + CO_LIST); LAS unsigned* list2 = list1 + 32; LAS unsigned* uw = (LAS unsigned*)(sm + CO_UW);
;     bf16x8 qf[8];
;     {
;         float qv[64]; float s = 0.f;
; #pragma unroll
;         for (int ks = 0; ks < 8; ++ks) { const u32x4 a = *(const u32x4*)(P_proj + (poff + C_Q + head * 128 + 16 * ks + 8 * hh)); const unsigned uw4[4] = {a.x, a.y, a.z, a.w};
; #pragma unroll
;             for (int j = 0; j < 4; ++j) { const float v0 = lo16(uw4[j]), v1 = hi16(uw4[j]); qv[8 * ks + 2 * j] = v0; qv[8 * ks + 2 * j + 1] = v1; s += v0 * v0 + v1 * v1; } }
;         s += __shfl_xor(s, 32);
;         const float rstd = 1.f / sqrtf(s * (1.f / 128.f) + EPSF);
; #pragma unroll
;         for (int ks = 0; ks < 8; ++ks) { const f32x4 w0 = *(const f32x4*)(P.q_norm_w + 16 * ks + 8 * hh), w1 = *(const f32x4*)(P.q_norm_w + 16 * ks + 8 * hh + 4);
;             u32x4 o; o.x = pk2(qv[8 * ks + 0] * rstd * w0[0], qv[8 * ks + 1] * rstd * w0[1]); o.y = pk2(qv[8 * ks + 2] * rstd * w0[2], qv[8 * ks + 3] * rstd * w0[3]);
;             o.z = pk2(qv[8 * ks + 4] * rstd * w1[0], qv[8 * ks + 5] * rstd * w1[1]); o.w = pk2(qv[8 * ks + 6] * rstd * w1[2], qv[8 * ks + 7] * rstd * w1[3]);
;             qf[ks] = __builtin_bit_cast(bf16x8, o); }
;     }
;     const float g0 = sigmoidf_(bf2f(P_proj[poff + C_GATE + head * 3 + 0])), g1 = sigmoidf_(bf2f(P_proj[poff + C_GATE + head * 3 + 1])), g2 = sigmoidf_(bf2f(P_proj[poff + C_GATE + head * 3 + 2]));
.LBB0_380:
	s_ashr_i32 s0, s57, 5
	s_and_b32 s1, s57, 0x100
	s_xor_b32 s2, s0, 7
	s_cmp_eq_u32 s1, 0
	s_waitcnt vmcnt(3)
	v_mov_b32_e32 v163, v146
	s_cselect_b32 s63, s0, s2
	s_lshl_b32 s2, s63, 5
	v_readfirstlane_b32 s0, v163
	s_ashr_i32 s71, s0, 6
	s_lshl_b32 s61, s71, 2
	s_bfe_u32 s16, s57, 0x40001
	s_and_b32 s22, s57, 1
	v_bfe_u32 v176, v163, 3, 2
	s_add_i32 s59, s61, s2
	v_bfe_u32 v144, v163, 5, 1
	s_lshl_b32 s58, s22, 3
	v_and_b32_e32 v178, 7, v163
	v_or_b32_e32 v175, s59, v176
	s_lshl_b32 s60, s16, 11
	v_or_b32_e32 v139, s58, v178
	v_add_u32_e32 v0, s60, v175
	v_lshlrev_b32_e32 v138, 3, v144
	v_mul_lo_u32 v145, v0, s44
	v_lshl_or_b32 v0, v139, 7, v138
	v_add3_u32 v0, v0, v145, s45
	v_lshl_add_u64 v[2:3], v[0:1], 1, s[30:31]
	global_load_dwordx4 v[78:81], v[2:3], off offset:224
	global_load_dwordx4 v[86:89], v[2:3], off offset:192
	global_load_dwordx4 v[94:97], v[2:3], off offset:160
	global_load_dwordx4 v[102:105], v[2:3], off offset:128
	global_load_dwordx4 v[114:117], v[2:3], off offset:96
	global_load_dwordx4 v[118:121], v[2:3], off offset:64
	v_cmp_lt_i32_e32 vcc, v148, v149
	s_lshl_b32 s0, s63, 1
	s_add_i32 s0, s0, 32
	v_cndmask_b32_e32 v0, v147, v148, vcc
	v_lshlrev_b32_e32 v155, 2, v0
	v_and_b32_e32 v0, 32, v163
	global_load_dwordx4 v[58:61], v0, s[38:39] offset:16
	global_load_dwordx4 v[62:65], v0, s[38:39]
	global_load_dwordx4 v[50:53], v0, s[38:39] offset:80
	global_load_dwordx4 v[54:57], v0, s[38:39] offset:64
	global_load_dwordx4 v[42:45], v0, s[38:39] offset:144
	global_load_dwordx4 v[46:49], v0, s[38:39] offset:128
	global_load_dwordx4 v[34:37], v0, s[38:39] offset:208
	global_load_dwordx4 v[38:41], v0, s[38:39] offset:192
	global_load_dwordx4 v[26:29], v0, s[38:39] offset:272
	global_load_dwordx4 v[30:33], v0, s[38:39] offset:256
	global_load_dwordx4 v[18:21], v0, s[38:39] offset:336
	global_load_dwordx4 v[22:25], v0, s[38:39] offset:320
	global_load_dwordx4 v[10:13], v0, s[38:39] offset:400
	global_load_dwordx4 v[14:17], v0, s[38:39] offset:384
	global_load_dwordx4 v[66:69], v[2:3], off
	global_load_dwordx4 v[134:137], v[2:3], off offset:32
	s_nop 0
	global_load_dwordx4 v[2:5], v0, s[38:39] offset:464
	global_load_dwordx4 v[6:9], v0, s[38:39] offset:448
	v_mul_u32_u24_e32 v0, 3, v139
	v_or_b32_e32 v0, v0, v145
	v_add_u32_e32 v0, 0x3a20, v0
	s_ashr_i32 s68, s0, 5
	s_max_i32 s0, s2, 0x1ff
	s_add_i32 s69, s0, 0xfffffe01
	s_andn2_b32 s69, s69, 31
	s_sub_i32 s0, s2, s69
	s_ashr_i32 s33, s0, 5
	s_lshl_b32 s70, s68, 1
	s_add_i32 s33, s33, s70
	v_cmp_ge_i32_e32 vcc, s33, v163
	s_waitcnt vmcnt(23)
	v_lshlrev_b32_e32 v70, 16, v81
	v_and_b32_e32 v73, 0xffff0000, v81
	v_and_b32_e32 v77, 0xffff0000, v79
	s_waitcnt vmcnt(22)
	v_and_b32_e32 v81, 0xffff0000, v89
	v_lshlrev_b32_e32 v72, 16, v80
	s_waitcnt vmcnt(18)
	v_lshlrev_b32_e32 v126, 16, v121
	v_and_b32_e32 v127, 0xffff0000, v121
	v_lshlrev_b32_e32 v122, 16, v120
	v_and_b32_e32 v123, 0xffff0000, v120
	v_lshlrev_b32_e32 v128, 16, v119
	v_and_b32_e32 v129, 0xffff0000, v119
	v_lshlrev_b32_e32 v120, 16, v118
	v_and_b32_e32 v121, 0xffff0000, v118
	s_waitcnt vmcnt(2)
; DI float bf2f(bf16_t u) { return __uint_as_float(((unsigned)u) << 16); }
; DI unsigned pk2(float lo, float hi) { f32x2 v = {lo, hi}; bf16x2_t b = __builtin_convertvector(v, bf16x2_t); return __builtin_bit_cast(unsigned, b); }
; DI float lo16(unsigned u) { return __uint_as_float(u << 16); }
; DI float hi16(unsigned u) { return __uint_as_float(u & 0xffff0000u); }
; DI float sigmoidf_(float x) { return __builtin_amdgcn_rcpf(1.f + __expf(-x)); }
; DI void nsa_block_item(const Params& P, unsigned char* smem_g, int b, int g, int tb, int tid_in) {
;     ...
;         float qv[64]; float s = 0.f;
; #pragma unroll
;         for (int ks = 0; ks < 8; ++ks) { const u32x4 a = *(const u32x4*)(P_proj + (poff + C_Q + head * 128 + 16 * ks + 8 * hh)); const unsigned uw4[4] = {a.x, a.y, a.z, a.w};
; #pragma unroll
;             for (int j = 0; j < 4; ++j) { const float v0 = lo16(uw4[j]), v1 = hi16(uw4[j]); qv[8 * ks + 2 * j] = v0; qv[8 * ks + 2 * j + 1] = v1; s += v0 * v0 + v1 * v1; } }
;         s += __shfl_xor(s, 32);
;         const float rstd = 1.f / sqrtf(s * (1.f / 128.f) + EPSF);
; #pragma unroll
;         for (int ks = 0; ks < 8; ++ks) { const f32x4 w0 = *(const f32x4*)(P.q_norm_w + 16 * ks + 8 * hh), w1 = *(const f32x4*)(P.q_norm_w + 16 * ks + 8 * hh + 4);
;             u32x4 o; o.x = pk2(qv[8 * ks + 0] * rstd * w0[0], qv[8 * ks + 1] * rstd * w0[1]); o.y = pk2(qv[8 * ks + 2] * rstd * w0[2], qv[8 * ks + 3] * rstd * w0[3]);
;             o.z = pk2(qv[8 * ks + 4] * rstd * w1[0], qv[8 * ks + 5] * rstd * w1[1]); o.w = pk2(qv[8 * ks + 6] * rstd * w1[2], qv[8 * ks + 7] * rstd * w1[3]);
;             qf[ks] = __builtin_bit_cast(bf16x8, o); }
;     }
;     const float g0 = sigmoidf_(bf2f(P_proj[poff + C_GATE + head * 3 + 0])), g1 = sigmoidf_(bf2f(P_proj[poff + C_GATE + head * 3 + 1])), g2 = sigmoidf_(bf2f(P_proj[poff + C_GATE + head * 3 + 2]));
;     const int nA = (((t0b >> 4) + 1) + 31) >> 5;
;     int lo = t0b - 511; if (lo < 0) lo = 0; lo &= ~31;
;     const int nD = ((t0b - lo) >> 5) + 1, n1 = 2 * nA + nD;
;     asm volatile("s_waitcnt vmcnt(0)" ::: "memory");
;     CO_BAR();
;     if (tid < n1) { const unsigned d = tid < nA ? (unsigned)(tid * 32) : (tid < 2 * nA ? ((1u << 16) | (unsigned)((tid - nA) * 32)) : ((2u << 16) | (unsigned)(lo + (tid - 2 * nA) * 32))); list1[tid] = d; }
;     CO_BAR();
	v_lshlrev_b32_e32 v130, 16, v137
	v_and_b32_e32 v131, 0xffff0000, v137
	v_lshlrev_b32_e32 v118, 16, v136
	v_and_b32_e32 v119, 0xffff0000, v136
	v_lshl_add_u64 v[136:137], v[0:1], 1, s[30:31]
	global_load_dword v154, v[136:137], off
	global_load_ushort v174, v[136:137], off offset:4
	v_and_b32_e32 v107, 0xffff0000, v80
	v_lshlrev_b32_e32 v76, 16, v78
	v_and_b32_e32 v113, 0xffff0000, v78
	v_lshlrev_b32_e32 v80, 16, v88
	v_and_b32_e32 v109, 0xffff0000, v88
	v_mov_b32_e32 v106, v73
	v_mov_b32_e32 v112, v77
	v_mov_b32_e32 v108, v81
	v_lshlrev_b32_e32 v74, 16, v79
	v_lshlrev_b32_e32 v78, 16, v89
	v_lshlrev_b32_e32 v82, 16, v87
	v_and_b32_e32 v83, 0xffff0000, v87
	v_lshlrev_b32_e32 v84, 16, v86
	v_and_b32_e32 v85, 0xffff0000, v86
	v_lshlrev_b32_e32 v86, 16, v97
	v_and_b32_e32 v87, 0xffff0000, v97
	v_lshlrev_b32_e32 v88, 16, v96
	v_and_b32_e32 v89, 0xffff0000, v96
	v_mov_b32_e32 v71, v72
	v_mov_b32_e32 v75, v76
	v_mov_b32_e32 v79, v80
	v_mul_f32_e32 v96, v106, v106
	v_mul_f32_e32 v97, v107, v107
	v_mul_f32_e32 v98, v112, v112
	v_mul_f32_e32 v99, v113, v113
	v_mul_f32_e32 v100, v108, v108
	v_mul_f32_e32 v101, v109, v109
	v_lshlrev_b32_e32 v90, 16, v95
	v_and_b32_e32 v91, 0xffff0000, v95
	v_lshlrev_b32_e32 v92, 16, v94
	v_pk_fma_f32 v[164:165], v[70:71], v[70:71], v[96:97]
	v_pk_fma_f32 v[166:167], v[74:75], v[74:75], v[98:99]
	v_pk_fma_f32 v[168:169], v[78:79], v[78:79], v[100:101]
	v_and_b32_e32 v93, 0xffff0000, v94
	v_lshlrev_b32_e32 v94, 16, v105
	v_and_b32_e32 v95, 0xffff0000, v105
	v_lshlrev_b32_e32 v96, 16, v104
	v_and_b32_e32 v97, 0xffff0000, v104
	v_lshlrev_b32_e32 v98, 16, v103
	v_and_b32_e32 v99, 0xffff0000, v103
	v_lshlrev_b32_e32 v100, 16, v102
	v_and_b32_e32 v101, 0xffff0000, v102
	v_lshlrev_b32_e32 v102, 16, v117
	v_and_b32_e32 v103, 0xffff0000, v117
	v_lshlrev_b32_e32 v104, 16, v116
	v_and_b32_e32 v105, 0xffff0000, v116
	v_lshlrev_b32_e32 v110, 16, v115
	v_and_b32_e32 v111, 0xffff0000, v115
	v_lshlrev_b32_e32 v124, 16, v114
	v_and_b32_e32 v125, 0xffff0000, v114
	v_lshlrev_b32_e32 v132, 16, v135
	v_and_b32_e32 v133, 0xffff0000, v135
	v_lshlrev_b32_e32 v116, 16, v134
	v_and_b32_e32 v117, 0xffff0000, v134
	v_lshlrev_b32_e32 v134, 16, v69
	v_and_b32_e32 v135, 0xffff0000, v69
	v_lshlrev_b32_e32 v114, 16, v68
	v_and_b32_e32 v115, 0xffff0000, v68
	v_lshlrev_b32_e32 v68, 16, v67
	v_and_b32_e32 v69, 0xffff0000, v67
	v_lshlrev_b32_e32 v136, 16, v66
	v_and_b32_e32 v137, 0xffff0000, v66
	v_mul_f32_e32 v216, v68, v68
	v_mul_f32_e32 v217, v69, v69
	v_mul_f32_e32 v66, v136, v136
	v_mul_f32_e32 v67, v137, v137
	v_mul_f32_e32 v212, v114, v114
	v_mul_f32_e32 v213, v115, v115
	v_add_f32_e32 v71, v216, v217
	v_add_f32_e32 v66, v66, v67
	v_mul_f32_e32 v210, v134, v134
	v_mul_f32_e32 v211, v135, v135
	v_add_f32_e32 v66, v66, v71
	v_add_f32_e32 v67, v212, v213
	v_mul_f32_e32 v208, v116, v116
	v_mul_f32_e32 v209, v117, v117
	v_add_f32_e32 v0, v210, v211
	v_add_f32_e32 v66, v67, v66
	v_mul_f32_e32 v206, v132, v132
	v_mul_f32_e32 v207, v133, v133
	v_add_f32_e32 v0, v0, v66
	v_add_f32_e32 v66, v208, v209
	v_mul_f32_e32 v204, v118, v118
	v_mul_f32_e32 v205, v119, v119
	v_add_f32_e32 v0, v66, v0
	v_add_f32_e32 v66, v206, v207
	v_mul_f32_e32 v202, v130, v130
	v_mul_f32_e32 v203, v131, v131
	v_add_f32_e32 v0, v66, v0
	v_add_f32_e32 v66, v204, v205
	v_mul_f32_e32 v200, v120, v120
	v_mul_f32_e32 v201, v121, v121
	v_add_f32_e32 v0, v66, v0
	v_add_f32_e32 v66, v202, v203
	v_mul_f32_e32 v198, v128, v128
	v_mul_f32_e32 v199, v129, v129
	v_add_f32_e32 v0, v66, v0
	v_add_f32_e32 v66, v200, v201
	v_mul_f32_e32 v196, v122, v122
	v_mul_f32_e32 v197, v123, v123
	v_add_f32_e32 v0, v66, v0
	v_add_f32_e32 v66, v198, v199
	v_mul_f32_e32 v194, v126, v126
	v_mul_f32_e32 v195, v127, v127
	v_add_f32_e32 v0, v66, v0
	v_add_f32_e32 v66, v196, v197
	v_mul_f32_e32 v192, v124, v124
	v_mul_f32_e32 v193, v125, v125
	v_add_f32_e32 v0, v66, v0
	v_add_f32_e32 v66, v194, v195
	v_mul_f32_e32 v190, v110, v110
	v_mul_f32_e32 v191, v111, v111
	v_add_f32_e32 v0, v66, v0
	v_add_f32_e32 v66, v192, v193
	v_mul_f32_e32 v188, v104, v104
	v_mul_f32_e32 v189, v105, v105
	v_add_f32_e32 v0, v66, v0
	v_add_f32_e32 v66, v190, v191
	v_mul_f32_e32 v186, v102, v102
	v_mul_f32_e32 v187, v103, v103
	v_add_f32_e32 v0, v66, v0
	v_add_f32_e32 v66, v188, v189
	v_mul_f32_e32 v184, v100, v100
	v_mul_f32_e32 v185, v101, v101
	v_add_f32_e32 v0, v66, v0
	v_add_f32_e32 v66, v186, v187
	v_mul_f32_e32 v182, v98, v98
	v_mul_f32_e32 v183, v99, v99
	v_add_f32_e32 v0, v66, v0
	v_add_f32_e32 v66, v184, v185
	v_mul_f32_e32 v180, v96, v96
	v_mul_f32_e32 v181, v97, v97
	v_add_f32_e32 v0, v66, v0
	v_add_f32_e32 v66, v182, v183
	v_mul_f32_e32 v172, v94, v94
	v_mul_f32_e32 v173, v95, v95
	v_add_f32_e32 v0, v66, v0
	v_add_f32_e32 v66, v180, v181
	v_mul_f32_e32 v170, v92, v92
	v_mul_f32_e32 v171, v93, v93
	v_add_f32_e32 v0, v66, v0
	v_add_f32_e32 v66, v172, v173
	v_mul_f32_e32 v160, v90, v90
	v_mul_f32_e32 v161, v91, v91
	v_add_f32_e32 v0, v66, v0
	v_add_f32_e32 v66, v170, v171
	v_mul_f32_e32 v158, v88, v88
	v_mul_f32_e32 v159, v89, v89
	v_add_f32_e32 v0, v66, v0
	v_add_f32_e32 v66, v160, v161
	v_mul_f32_e32 v156, v86, v86
	v_mul_f32_e32 v157, v87, v87
	v_add_f32_e32 v0, v66, v0
	v_add_f32_e32 v66, v158, v159
	v_mul_f32_e32 v142, v84, v84
	v_mul_f32_e32 v143, v85, v85
	v_add_f32_e32 v0, v66, v0
	v_add_f32_e32 v66, v156, v157
	v_mul_f32_e32 v140, v82, v82
	v_mul_f32_e32 v141, v83, v83
	v_add_f32_e32 v0, v66, v0
	v_add_f32_e32 v66, v142, v143
	v_add_f32_e32 v0, v66, v0
	v_add_f32_e32 v66, v140, v141
	v_add_f32_e32 v0, v66, v0
	v_add_f32_e32 v0, v169, v0
	v_add_f32_e32 v0, v168, v0
	v_add_f32_e32 v0, v167, v0
	v_add_f32_e32 v0, v166, v0
	v_add_f32_e32 v0, v165, v0
	v_add_f32_e32 v0, v164, v0
	ds_bpermute_b32 v66, v155, v0
	s_waitcnt vmcnt(0)
	s_waitcnt lgkmcnt(0)
	s_barrier
	s_and_saveexec_b64 s[2:3], vcc
	s_cbranch_execz .LBB0_390
	v_cmp_le_i32_e32 vcc, s68, v163
	s_and_saveexec_b64 s[0:1], vcc
	s_xor_b64 s[4:5], exec, s[0:1]
	s_cbranch_execz .LBB0_387
	v_cmp_le_i32_e32 vcc, s70, v163
	s_and_saveexec_b64 s[0:1], vcc
	s_xor_b64 s[8:9], exec, s[0:1]
	v_subrev_u32_e32 v67, s70, v163
	v_lshl_add_u32 v67, v67, 5, s69
	v_or_b32_e32 v67, 0x20000, v67
	s_andn2_saveexec_b64 s[8:9], s[8:9]
	v_subrev_u32_e32 v67, s68, v163
	v_lshl_or_b32 v67, v67, 5, v152
	s_or_b64 exec, exec, s[8:9]

; #define LAS __attribute__((address_space(3)))
; DI unsigned pk2(float lo, float hi) { f32x2 v = {lo, hi}; bf16x2_t b = __builtin_convertvector(v, bf16x2_t); return __builtin_bit_cast(unsigned, b); }
; DI float lo16(unsigned u) { return __uint_as_float(u << 16); }
; DI float hi16(unsigned u) { return __uint_as_float(u & 0xffff0000u); }
; DI void nsa_block_item(const Params& P, unsigned char* smem_g, int b, int g, int tb, int tid_in) {
;     ...
;     const int ka = l32 * 256 + 16 * (hh ^ (l32 & 15)), vb = 8192 + l32 * 64 + 8 * hh + 16 * ((l32 >> 2) & 3);
;     LAS unsigned char* ring = sm + CO_RING; LAS u32x2* totw = (LAS u32x2*)(sm + CO_TOT + wave * 8192);
;     LAS float* psum = (LAS float*)(sm + CO_SCR + wave * 2560); LAS unsigned* vals = (LAS unsigned*)(sm + CO_SCR + wave * 2560 + 2048);
;     LAS unsigned* list1 = (LAS unsigned*)(sm + CO_LIST); LAS unsigned* list2 = list1 + 32; LAS unsigned* uw = (LAS unsigned*)(sm + CO_UW);
;     bf16x8 qf[8];
;     {
;         float qv[64]; float s = 0.f;
; #pragma unroll
;         for (int ks = 0; ks < 8; ++ks) { const u32x4 a = *(const u32x4*)(P_proj + (poff + C_Q + head * 128 + 16 * ks + 8 * hh)); const unsigned uw4[4] = {a.x, a.y, a.z, a.w};
; #pragma unroll
;             for (int j = 0; j < 4; ++j) { const float v0 = lo16(uw4[j]), v1 = hi16(uw4[j]); qv[8 * ks + 2 * j] = v0; qv[8 * ks + 2 * j + 1] = v1; s += v0 * v0 + v1 * v1; } }
;         s += __shfl_xor(s, 32);
;         const float rstd = 1.f / sqrtf(s * (1.f / 128.f) + EPSF);
; #pragma unroll
;         for (int ks = 0; ks < 8; ++ks) { const f32x4 w0 = *(const f32x4*)(P.q_norm_w + 16 * ks + 8 * hh), w1 = *(const f32x4*)(P.q_norm_w + 16 * ks + 8 * hh + 4);
;             u32x4 o; o.x = pk2(qv[8 * ks + 0] * rstd * w0[0], qv[8 * ks + 1] * rstd * w0[1]); o.y = pk2(qv[8 * ks + 2] * rstd * w0[2], qv[8 * ks + 3] * rstd * w0[3]);
;             o.z = pk2(qv[8 * ks + 4] * rstd * w1[0], qv[8 * ks + 5] * rstd * w1[1]); o.w = pk2(qv[8 * ks + 6] * rstd * w1[2], qv[8 * ks + 7] * rstd * w1[3]);
;             qf[ks] = __builtin_bit_cast(bf16x8, o); }
.LBB0_412:
	s_waitcnt lgkmcnt(0)
	v_add_f32_e32 v0, v0, v66
	v_fmamk_f32 v0, v0, 0x3c000000, v150
	v_mul_f32_e32 v66, 0x4f800000, v0
	v_cmp_gt_f32_e32 vcc, s49, v0
	v_lshlrev_b32_e32 v75, 2, v163
	v_and_b32_e32 v67, 15, v163
	v_cndmask_b32_e32 v0, v0, v66, vcc
	v_sqrt_f32_e32 v66, v0
	v_lshlrev_b32_e32 v71, 6, v145
	v_and_b32_e32 v75, 48, v75
	v_xor_b32_e32 v67, v144, v67
	v_or3_b32 v156, v71, v75, v138
	v_lshlrev_b32_e32 v71, 8, v145
	v_lshl_or_b32 v162, v67, 4, v71
	v_add_u32_e32 v67, -1, v66
	v_fma_f32 v79, -v67, v66, v0
	v_cmp_ge_f32_e64 s[2:3], 0, v79
	v_add_u32_e32 v79, 1, v66
	v_mov_b32_e32 v71, v73
	v_cndmask_b32_e64 v67, v66, v67, s[2:3]
	v_fma_f32 v66, -v79, v66, v0
	v_cmp_lt_f32_e64 s[2:3], 0, v66
	v_mov_b32_e32 v73, v107
	v_mov_b32_e32 v75, v77
	v_cndmask_b32_e64 v66, v67, v79, s[2:3]
	v_mul_f32_e32 v67, 0x37800000, v66
	v_cndmask_b32_e32 v66, v66, v67, vcc
	v_cmp_class_f32_e32 vcc, v0, v151
	v_mov_b32_e32 v77, v113
	v_mov_b32_e32 v79, v81
	v_cndmask_b32_e32 v0, v66, v0, vcc
	v_div_scale_f32 v66, s[0:1], v0, v0, 1.0
	v_rcp_f32_e32 v67, v66
	v_mov_b32_e32 v81, v109
	s_mov_b32 s80, 0
	s_cmp_gt_i32 s68, 0
	v_fma_f32 v106, -v66, v67, 1.0
	v_fmac_f32_e32 v67, v106, v67
	v_div_scale_f32 v106, vcc, 1.0, v0, 1.0
	v_mul_f32_e32 v107, v106, v67
	v_fma_f32 v108, -v66, v107, v106
	v_fmac_f32_e32 v107, v108, v67
	v_fma_f32 v66, -v66, v107, v106
	v_div_fmas_f32 v66, v66, v67, v107
	v_div_fixup_f32 v0, v66, v0, 1.0
	v_mul_f32_e32 v66, v0, v136
	v_mul_f32_e32 v67, v0, v137
	v_mul_f32_e32 v62, v62, v66
	v_mul_f32_e32 v63, v63, v67
	v_xor_b32_e32 v164, 32, v162
	v_cvt_pk_bf16_f32 v112, v62, v63
	v_mul_f32_e32 v62, v0, v68
	v_mul_f32_e32 v63, v0, v69
	v_mul_f32_e32 v62, v64, v62
	v_mul_f32_e32 v63, v65, v63
	v_xor_b32_e32 v165, 64, v162
	v_cvt_pk_bf16_f32 v113, v62, v63
	v_mul_f32_e32 v62, v0, v114
	v_mul_f32_e32 v63, v0, v115
	v_mul_f32_e32 v58, v58, v62
	v_mul_f32_e32 v59, v59, v63
	v_xor_b32_e32 v166, 0x60, v162
	v_cvt_pk_bf16_f32 v114, v58, v59
	v_mul_f32_e32 v58, v0, v134
	v_mul_f32_e32 v59, v0, v135
	v_mul_f32_e32 v58, v60, v58
	v_mul_f32_e32 v59, v61, v59
	v_xor_b32_e32 v167, 0x80, v162
	v_cvt_pk_bf16_f32 v115, v58, v59
	v_mul_f32_e32 v58, v0, v116
	v_mul_f32_e32 v59, v0, v117
	v_mul_f32_e32 v54, v54, v58
	v_mul_f32_e32 v55, v55, v59
	v_xor_b32_e32 v168, 0xa0, v162
	v_cvt_pk_bf16_f32 v116, v54, v55
	v_mul_f32_e32 v54, v0, v132
	v_mul_f32_e32 v55, v0, v133
	v_mul_f32_e32 v54, v56, v54
	v_mul_f32_e32 v55, v57, v55
	v_xor_b32_e32 v169, 0xc0, v162
	v_cvt_pk_bf16_f32 v117, v54, v55
	v_mul_f32_e32 v54, v0, v118
	v_mul_f32_e32 v55, v0, v119
	v_mul_f32_e32 v50, v50, v54
	v_mul_f32_e32 v51, v51, v55
	v_xor_b32_e32 v170, 0xe0, v162
	v_cvt_pk_bf16_f32 v118, v50, v51
	v_mul_f32_e32 v50, v0, v130
	v_mul_f32_e32 v51, v0, v131
	v_mul_f32_e32 v50, v52, v50
	v_mul_f32_e32 v51, v53, v51
	v_lshlrev_b32_e32 v177, 2, v144
	v_cvt_pk_bf16_f32 v119, v50, v51
	v_mul_f32_e32 v50, v0, v120
	v_mul_f32_e32 v51, v0, v121
	v_mul_f32_e32 v46, v46, v50
	v_mul_f32_e32 v47, v47, v51
	v_xor_b32_e32 v171, 16, v156
	v_cvt_pk_bf16_f32 v120, v46, v47
	v_mul_f32_e32 v46, v0, v128
	v_mul_f32_e32 v47, v0, v129
	v_mul_f32_e32 v46, v48, v46
	v_mul_f32_e32 v47, v49, v47
	v_xor_b32_e32 v172, 32, v156
	v_cvt_pk_bf16_f32 v121, v46, v47
	v_mul_f32_e32 v46, v0, v122
	v_mul_f32_e32 v47, v0, v123
	v_mul_f32_e32 v42, v42, v46
	v_mul_f32_e32 v43, v43, v47
	v_xor_b32_e32 v173, 48, v156
	v_cvt_pk_bf16_f32 v122, v42, v43
	v_mul_f32_e32 v42, v0, v126
	v_mul_f32_e32 v43, v0, v127
	v_mul_f32_e32 v42, v44, v42
	v_mul_f32_e32 v43, v45, v43
	s_nop 0
	v_cvt_pk_bf16_f32 v123, v42, v43
	v_mul_f32_e32 v42, v0, v124
	v_mul_f32_e32 v43, v0, v125
	v_mul_f32_e32 v38, v38, v42
	v_mul_f32_e32 v39, v39, v43
	s_nop 0
	v_cvt_pk_bf16_f32 v124, v38, v39
	v_mul_f32_e32 v38, v0, v110
	v_mul_f32_e32 v39, v0, v111
	v_mul_f32_e32 v38, v40, v38
	v_mul_f32_e32 v39, v41, v39
	s_nop 0
	v_cvt_pk_bf16_f32 v125, v38, v39
	v_mul_f32_e32 v38, v0, v104
	v_mul_f32_e32 v39, v0, v105
	v_mul_f32_e32 v34, v34, v38
	v_mul_f32_e32 v35, v35, v39
	s_nop 0
	v_cvt_pk_bf16_f32 v126, v34, v35
	v_mul_f32_e32 v34, v0, v102
	v_mul_f32_e32 v35, v0, v103
	v_mul_f32_e32 v34, v36, v34
	v_mul_f32_e32 v35, v37, v35
	s_nop 0
	v_cvt_pk_bf16_f32 v127, v34, v35
	v_mul_f32_e32 v34, v0, v100
	v_mul_f32_e32 v35, v0, v101
	v_mul_f32_e32 v30, v30, v34
	v_mul_f32_e32 v31, v31, v35
	s_nop 0
	v_cvt_pk_bf16_f32 v128, v30, v31
	v_mul_f32_e32 v30, v0, v98
	v_mul_f32_e32 v31, v0, v99
	v_mul_f32_e32 v30, v32, v30
	v_mul_f32_e32 v31, v33, v31
	s_nop 0
	v_cvt_pk_bf16_f32 v129, v30, v31
	v_mul_f32_e32 v30, v0, v96
	v_mul_f32_e32 v31, v0, v97
	v_mul_f32_e32 v26, v26, v30
	v_mul_f32_e32 v27, v27, v31
	s_nop 0
	v_cvt_pk_bf16_f32 v130, v26, v27
	v_mul_f32_e32 v26, v0, v94
	v_mul_f32_e32 v27, v0, v95
	v_mul_f32_e32 v26, v28, v26
	v_mul_f32_e32 v27, v29, v27
	s_nop 0
	v_cvt_pk_bf16_f32 v131, v26, v27
	v_mul_f32_e32 v26, v0, v92
	v_mul_f32_e32 v27, v0, v93
	v_mul_f32_e32 v22, v22, v26
	v_mul_f32_e32 v23, v23, v27
	s_nop 0
	v_cvt_pk_bf16_f32 v132, v22, v23
	v_mul_f32_e32 v22, v0, v90
	v_mul_f32_e32 v23, v0, v91
	v_mul_f32_e32 v22, v24, v22
	v_mul_f32_e32 v23, v25, v23
	s_nop 0
	v_cvt_pk_bf16_f32 v133, v22, v23
	v_mul_f32_e32 v22, v0, v88
	v_mul_f32_e32 v23, v0, v89
	v_mul_f32_e32 v18, v18, v22
	v_mul_f32_e32 v19, v19, v23
	s_nop 0
	v_cvt_pk_bf16_f32 v134, v18, v19
	v_mul_f32_e32 v18, v0, v86
	v_mul_f32_e32 v19, v0, v87
	v_mul_f32_e32 v18, v20, v18
	v_mul_f32_e32 v19, v21, v19
	s_nop 0
	v_cvt_pk_bf16_f32 v135, v18, v19
	v_mul_f32_e32 v18, v0, v84
	v_mul_f32_e32 v19, v0, v85
	v_mul_f32_e32 v14, v14, v18
	v_mul_f32_e32 v15, v15, v19
	s_nop 0
	v_cvt_pk_bf16_f32 v136, v14, v15
	v_mul_f32_e32 v14, v0, v82
	v_mul_f32_e32 v15, v0, v83
	v_mul_f32_e32 v14, v16, v14
	v_mul_f32_e32 v15, v17, v15
	s_nop 0
	v_cvt_pk_bf16_f32 v137, v14, v15
	v_mul_f32_e32 v14, v0, v80
	v_mul_f32_e32 v15, v0, v81
	v_mul_f32_e32 v10, v10, v14
	v_mul_f32_e32 v11, v11, v15
	s_nop 0
	v_cvt_pk_bf16_f32 v138, v10, v11
	v_mul_f32_e32 v10, v0, v78
	v_mul_f32_e32 v11, v0, v79
	v_mul_f32_e32 v10, v12, v10
	v_mul_f32_e32 v11, v13, v11
	s_nop 0
	v_cvt_pk_bf16_f32 v139, v10, v11
	v_mul_f32_e32 v10, v0, v76
	v_mul_f32_e32 v11, v0, v77
	s_waitcnt vmcnt(0)
	v_mul_f32_e32 v6, v6, v10
	v_mul_f32_e32 v7, v7, v11
	s_nop 0
	v_cvt_pk_bf16_f32 v140, v6, v7
	v_mul_f32_e32 v6, v0, v74
	v_mul_f32_e32 v7, v0, v75
	v_mul_f32_e32 v6, v8, v6
	v_mul_f32_e32 v7, v9, v7
	s_nop 0
	v_cvt_pk_bf16_f32 v141, v6, v7
	v_mul_f32_e32 v6, v0, v72
	v_mul_f32_e32 v7, v0, v73
	v_mul_f32_e32 v2, v2, v6
	v_mul_f32_e32 v3, v3, v7
	s_nop 0
	v_cvt_pk_bf16_f32 v142, v2, v3
	v_mul_f32_e32 v2, v0, v70
	v_mul_f32_e32 v3, v0, v71
	v_mul_f32_e32 v2, v4, v2
	v_mul_f32_e32 v3, v5, v3
	v_subrev_u32_e32 v0, 31, v175
	v_cvt_pk_bf16_f32 v143, v2, v3
	v_ashrrev_i32_e32 v157, 4, v0
	s_cbranch_scc0 .LBB0_436
; #define LAS __attribute__((address_space(3)))
; #define CO_STEP2(list, n, i) do { \
;     if ((n) - 1 - (i) >= 1) asm volatile("s_waitcnt vmcnt(2)" ::: "memory"); else asm volatile("s_waitcnt vmcnt(0)" ::: "memory"); \
;     asm volatile("s_waitcnt lgkmcnt(0)" ::: "memory"); __builtin_amdgcn_s_barrier(); asm volatile("" ::: "memory"); \
;     if ((i) + 2 < (n)) co_issue(P, ring, ((i) + 2) & 3, (list)[(i) + 2], b, g, wave, lane); } while (0)
; #define CO_PIPE(MODE, REL, KB, RS) do { const bool rel_ = (REL); LAS unsigned char* sp_ = ring + (i & 3) * 16384; f32x16 Sn_; \
;     if (rel_) Sn_ = co_qk1(sp_, qf, ka); \
;     if (pend) co_finish<MODE>(Sp, pst, pkb, st, tq, prs, vb, hh); \
;     pend = rel_; if (rel_) { Sp = Sn_; pst = sp_; pkb = (KB); prs = (RS); } } while (0)
; DI void nsa_block_item(const Params& P, unsigned char* smem_g, int b, int g, int tb, int tid_in) {
;     ...
;     AttnState st;
;     bool pend = false, prs = false; f32x16 Sp; int pkb = 0; LAS unsigned char* pst = ring;
; #pragma unroll
;     for (int i2 = 0; i2 < 16; ++i2) Sp[i2] = 0.f;
; #pragma unroll
;     for (int s = 0; s < 2; ++s) if (s < n1) co_issue(P, ring, s, list1[s], b, g, wave, lane);
;     int i = 0;
;     attn_reset(st);
;     for (; i < nA; ++i) { CO_STEP2(list1, n1, i); const int kb_ = 32 * i; CO_PIPE(0, 16 * kb_ + 31 <= t0 + 3, kb_, true); }
	s_lshl_b32 s0, s67, 1
	s_add_u32 s0, s30, s0
	s_addc_u32 s1, s31, 0
	s_lshl_b32 s2, s22, 1
	s_add_u32 s2, s21, s2
	s_addc_u32 s3, s23, 0
	s_lshl_b32 s4, s66, 1
	v_mov_b32_e32 v14, v1
	v_mov_b32_e32 v15, v1
	s_add_u32 s72, s0, s4
	v_mov_b32_e32 v0, v1
	v_mov_b32_e32 v2, v1
	v_mov_b32_e32 v3, v1
	v_mov_b32_e32 v4, v1
	v_mov_b32_e32 v5, v1
	v_mov_b32_e32 v6, v1
	v_mov_b32_e32 v7, v1
	v_mov_b32_e32 v8, v1
	v_mov_b32_e32 v9, v1
	v_mov_b32_e32 v10, v1
	v_mov_b32_e32 v11, v1
	v_mov_b32_e32 v12, v1
	v_mov_b32_e32 v13, v1
	v_mov_b64_e32 v[30:31], v[14:15]
	v_mov_b64_e32 v[94:95], v[14:15]
	v_mov_b64_e32 v[78:79], v[14:15]
	v_mov_b64_e32 v[62:63], v[14:15]
	v_mov_b64_e32 v[46:47], v[14:15]
	v_sub_u32_e32 v180, v157, v177
	s_addc_u32 s73, s1, 0
	s_mov_b32 s62, 0
	s_add_i32 s74, s65, 0
	s_add_i32 s75, 0, 0x25008
	s_mov_b32 s76, 0
	v_mov_b32_e32 v179, 0
	v_mov_b32_e32 v181, 0xf149f2ca
	s_mov_b64 s[8:9], 0
	s_mov_b32 s77, 28
	s_mov_b32 s78, 0
	s_mov_b64 s[26:27], 0
	v_mov_b64_e32 v[28:29], v[12:13]
	v_mov_b64_e32 v[26:27], v[10:11]
	v_mov_b64_e32 v[24:25], v[8:9]
	v_mov_b64_e32 v[22:23], v[6:7]
	v_mov_b64_e32 v[20:21], v[4:5]
	v_mov_b64_e32 v[18:19], v[2:3]
	v_mov_b64_e32 v[16:17], v[0:1]
	s_mov_b32 s64, 0
	s_mov_b32 s16, 0
	v_mov_b64_e32 v[92:93], v[12:13]
	v_mov_b64_e32 v[90:91], v[10:11]
	v_mov_b64_e32 v[88:89], v[8:9]
	v_mov_b64_e32 v[86:87], v[6:7]
	v_mov_b64_e32 v[84:85], v[4:5]
	v_mov_b64_e32 v[82:83], v[2:3]
	v_mov_b64_e32 v[80:81], v[0:1]
	v_mov_b64_e32 v[76:77], v[12:13]
	v_mov_b64_e32 v[74:75], v[10:11]
	v_mov_b64_e32 v[72:73], v[8:9]
	v_mov_b64_e32 v[70:71], v[6:7]
	v_mov_b64_e32 v[68:69], v[4:5]
	v_mov_b64_e32 v[66:67], v[2:3]
	v_mov_b64_e32 v[64:65], v[0:1]
	v_mov_b64_e32 v[60:61], v[12:13]
	v_mov_b64_e32 v[58:59], v[10:11]
	v_mov_b64_e32 v[56:57], v[8:9]
	v_mov_b64_e32 v[54:55], v[6:7]
	v_mov_b64_e32 v[52:53], v[4:5]
	v_mov_b64_e32 v[50:51], v[2:3]
	v_mov_b64_e32 v[48:49], v[0:1]
	v_mov_b64_e32 v[44:45], v[12:13]
	v_mov_b64_e32 v[42:43], v[10:11]
	v_mov_b64_e32 v[40:41], v[8:9]
	v_mov_b64_e32 v[38:39], v[6:7]
	v_mov_b64_e32 v[36:37], v[4:5]
	v_mov_b64_e32 v[34:35], v[2:3]
	v_mov_b64_e32 v[32:33], v[0:1]
	s_cmp_le_i32 s33, s16
	s_mov_b64 s[4:5], -1
	s_cbranch_scc0 .LBB0_415

; #define LAS __attribute__((address_space(3)))
; DI float xh_max(float x) { const unsigned u = __float_as_uint(x); const auto r = __builtin_amdgcn_permlane32_swap(u, u, false, false); return fmaxf(__uint_as_float(r[0]), __uint_as_float(r[1])); }
; DI float xh_sum(float x) { const unsigned u = __float_as_uint(x); const auto r = __builtin_amdgcn_permlane32_swap(u, u, false, false); return __uint_as_float(r[0]) + __uint_as_float(r[1]); }
; template <int MODE>
; DI void co_finish(f32x16 S, LAS unsigned char* st, int key_base, AttnState& as, int tq, bool rowsel, int vb_in, int hh) {
;     const int vb = vb_in;
;     {
;         const int base = key_base + 4 * hh;
;         const int hi = (MODE == 0) ? (((tq - 31) >> 4) - base) : (tq - base);
;         const int lo = hi - 512;
; #pragma unroll
;         for (int i = 0; i < 16; ++i) { const int c = (i & 3) + 8 * (i >> 2); bool ok = (c <= hi); if (MODE == 2) ok = ok && (c > lo); if (MODE == 1) ok = ok && rowsel; S[i] = ok ? S[i] : -1e30f; }
;     }
;     float mx = S[0];
; #pragma unroll
;     for (int i = 1; i < 16; ++i) mx = fmaxf(mx, S[i]);
;     mx = xh_max(mx);
;     const float mxs = mx * SM_SCALE; const bool need = mxs > as.m + 8.f;
;     const float mnew = need ? mxs : as.m, muse = -fmaxf(mnew, -1e20f); float ps = 0.f;
; #pragma unroll
;     for (int i = 0; i < 16; ++i) { const float p = __builtin_amdgcn_exp2f(__builtin_fmaf(S[i], SM_SCALE, muse)); S[i] = p; ps += p; }
;     ps = xh_sum(ps);
;     if (__builtin_amdgcn_ballot_w64(need) != 0ull) {
;         const float alpha = __builtin_amdgcn_exp2f(as.m - mnew);
;         as.l *= alpha;
; #pragma unroll
;         for (int dt = 0; dt < 4; ++dt)
; #pragma unroll
;             for (int i = 0; i < 16; ++i) as.acc[dt][i] *= alpha;
;     }
.LBB0_424:
	s_andn2_b64 vcc, exec, s[8:9]
	s_cbranch_vccnz .LBB0_428
	v_add_u32_e32 v0, s80, v180
	v_cmp_lt_i32_e32 vcc, -1, v0
	s_nop 1
	v_cndmask_b32_e32 v3, v153, v16, vcc
	v_cmp_lt_i32_e32 vcc, 0, v0
	v_max_f32_e32 v2, v3, v3
	s_nop 0
	v_cndmask_b32_e32 v4, v153, v17, vcc
	v_cmp_lt_i32_e32 vcc, 1, v0
	s_nop 1
	v_cndmask_b32_e32 v5, v153, v18, vcc
	v_cmp_lt_i32_e32 vcc, 2, v0
	s_nop 1
	v_cndmask_b32_e32 v6, v153, v19, vcc
	v_cmp_lt_i32_e32 vcc, 7, v0
	s_nop 1
	v_cndmask_b32_e32 v7, v153, v20, vcc
	v_cmp_lt_i32_e32 vcc, 8, v0
	s_nop 1
	v_cndmask_b32_e32 v8, v153, v21, vcc
	v_cmp_lt_i32_e32 vcc, 9, v0
	s_nop 1
	v_cndmask_b32_e32 v9, v153, v22, vcc
	v_cmp_lt_i32_e32 vcc, 10, v0
	s_nop 1
	v_cndmask_b32_e32 v10, v153, v23, vcc
	v_cmp_lt_i32_e32 vcc, 15, v0
	s_nop 1
	v_cndmask_b32_e32 v11, v153, v24, vcc
	v_cmp_lt_i32_e32 vcc, 16, v0
	s_nop 1
	v_cndmask_b32_e32 v12, v153, v25, vcc
	v_cmp_lt_i32_e32 vcc, 17, v0
	s_nop 1
	v_cndmask_b32_e32 v13, v153, v26, vcc
	v_cmp_lt_i32_e32 vcc, 18, v0
	s_nop 1
	v_cndmask_b32_e32 v14, v153, v27, vcc
	v_cmp_lt_i32_e32 vcc, 23, v0
	s_nop 1
	v_cndmask_b32_e32 v15, v153, v28, vcc
	v_cmp_lt_i32_e32 vcc, 24, v0
	s_nop 1
	v_cndmask_b32_e32 v182, v153, v29, vcc
	v_cmp_lt_i32_e32 vcc, 25, v0
	s_nop 1
	v_cndmask_b32_e32 v183, v153, v30, vcc
	v_cmp_lt_i32_e32 vcc, 26, v0
	v_max_f32_e32 v0, v4, v4
	v_max_f32_e32 v0, v2, v0
	v_max3_f32 v0, v0, v5, v6
	v_max3_f32 v0, v0, v7, v8
	v_max3_f32 v0, v0, v9, v10
	v_max3_f32 v0, v0, v11, v12
	v_max3_f32 v0, v0, v13, v14
	v_cndmask_b32_e32 v184, v153, v31, vcc
	v_max3_f32 v0, v0, v15, v182
	v_max3_f32 v0, v0, v183, v184
	v_mov_b32_e32 v2, v0
	s_nop 1
	v_permlane32_swap_b32_e32 v0, v2
	v_max_f32_e32 v2, v2, v2
	v_max_f32_e32 v0, v0, v0
	v_max_f32_e32 v0, v0, v2
	v_mul_f32_e32 v0, 0x3e0293ee, v0
	v_add_f32_e32 v2, 0x41000000, v181
	v_cmp_gt_f32_e32 vcc, v0, v2
	s_nop 1
	v_cndmask_b32_e32 v2, v181, v0, vcc
	v_max_f32_e32 v0, v2, v2
	v_max_f32_e32 v185, 0xe0ad78ec, v0
	v_fma_f32 v0, v3, s52, -v185
	v_exp_f32_e32 v0, v0
	v_fma_f32 v3, v4, s52, -v185
	v_exp_f32_e32 v3, v3
	v_fma_f32 v4, v5, s52, -v185
	v_exp_f32_e32 v4, v4
	v_fma_f32 v5, v6, s52, -v185
	v_exp_f32_e32 v5, v5
	v_add_f32_e32 v6, 0, v0
	v_add_f32_e32 v6, v3, v6
	v_add_f32_e32 v6, v4, v6
	v_add_f32_e32 v186, v5, v6
	v_fma_f32 v6, v7, s52, -v185
	v_exp_f32_e32 v6, v6
	v_fma_f32 v7, v8, s52, -v185
	v_exp_f32_e32 v7, v7
	v_fma_f32 v8, v9, s52, -v185
	v_exp_f32_e32 v8, v8
	v_fma_f32 v9, v10, s52, -v185
	v_exp_f32_e32 v9, v9
	v_add_f32_e32 v10, v6, v186
	v_add_f32_e32 v10, v7, v10
	v_add_f32_e32 v10, v8, v10
	v_add_f32_e32 v186, v9, v10
	v_fma_f32 v10, v11, s52, -v185
	v_exp_f32_e32 v10, v10
	v_fma_f32 v11, v12, s52, -v185
	v_exp_f32_e32 v11, v11
	v_fma_f32 v12, v13, s52, -v185
	v_exp_f32_e32 v12, v12
	v_fma_f32 v13, v14, s52, -v185
	v_exp_f32_e32 v13, v13
	v_add_f32_e32 v14, v10, v186
	v_add_f32_e32 v14, v11, v14
	v_add_f32_e32 v14, v12, v14
	v_add_f32_e32 v186, v13, v14
	v_fma_f32 v14, v15, s52, -v185
	v_exp_f32_e32 v14, v14
	v_fma_f32 v15, v182, s52, -v185
	v_exp_f32_e32 v15, v15
	v_fma_f32 v182, v183, s52, -v185
	v_exp_f32_e32 v182, v182
	v_fma_f32 v183, v184, s52, -v185
	v_exp_f32_e32 v183, v183
	v_add_f32_e32 v184, v14, v186
	v_add_f32_e32 v184, v15, v184
	v_add_f32_e32 v184, v182, v184
	v_add_f32_e32 v184, v183, v184
	v_mov_b32_e32 v185, v184
	s_nop 1
	v_permlane32_swap_b32_e32 v184, v185
	s_cbranch_vccz .LBB0_427
	v_sub_f32_e32 v181, v181, v2
	v_exp_f32_e32 v186, v181
	s_nop 0
	v_mul_f32_e32 v179, v179, v186
	v_mul_f32_e32 v94, v94, v186
	v_mul_f32_e32 v95, v95, v186
	v_mul_f32_e32 v92, v92, v186
	v_mul_f32_e32 v93, v93, v186
	v_mul_f32_e32 v90, v90, v186
	v_mul_f32_e32 v91, v91, v186
	v_mul_f32_e32 v88, v88, v186
	v_mul_f32_e32 v89, v89, v186
	v_mul_f32_e32 v86, v86, v186
	v_mul_f32_e32 v87, v87, v186
	v_mul_f32_e32 v84, v84, v186
	v_mul_f32_e32 v85, v85, v186
	v_mul_f32_e32 v82, v82, v186
	v_mul_f32_e32 v83, v83, v186
	v_mul_f32_e32 v80, v80, v186
	v_mul_f32_e32 v81, v81, v186
	v_mul_f32_e32 v78, v78, v186
	v_mul_f32_e32 v79, v79, v186
	v_mul_f32_e32 v76, v76, v186
	v_mul_f32_e32 v77, v77, v186
	v_mul_f32_e32 v74, v74, v186
	v_mul_f32_e32 v75, v75, v186
	v_mul_f32_e32 v72, v72, v186
	v_mul_f32_e32 v73, v73, v186
	v_mul_f32_e32 v70, v70, v186
	v_mul_f32_e32 v71, v71, v186
	v_mul_f32_e32 v68, v68, v186
	v_mul_f32_e32 v69, v69, v186
	v_mul_f32_e32 v66, v66, v186
	v_mul_f32_e32 v67, v67, v186
	v_mul_f32_e32 v64, v64, v186
	v_mul_f32_e32 v65, v65, v186
	v_mul_f32_e32 v62, v62, v186
	v_mul_f32_e32 v63, v63, v186
	v_mul_f32_e32 v60, v60, v186
	v_mul_f32_e32 v61, v61, v186
	v_mul_f32_e32 v58, v58, v186
	v_mul_f32_e32 v59, v59, v186
	v_mul_f32_e32 v56, v56, v186
	v_mul_f32_e32 v57, v57, v186
	v_mul_f32_e32 v54, v54, v186
	v_mul_f32_e32 v55, v55, v186
	v_mul_f32_e32 v52, v52, v186
	v_mul_f32_e32 v53, v53, v186
	v_mul_f32_e32 v50, v50, v186
	v_mul_f32_e32 v51, v51, v186
	v_mul_f32_e32 v48, v48, v186
	v_mul_f32_e32 v49, v49, v186
	v_mul_f32_e32 v46, v46, v186
	v_mul_f32_e32 v47, v47, v186
	v_mul_f32_e32 v44, v44, v186
	v_mul_f32_e32 v45, v45, v186
	v_mul_f32_e32 v42, v42, v186
	v_mul_f32_e32 v43, v43, v186
	v_mul_f32_e32 v40, v40, v186
	v_mul_f32_e32 v41, v41, v186
	v_mul_f32_e32 v38, v38, v186
	v_mul_f32_e32 v39, v39, v186
	v_mul_f32_e32 v36, v36, v186
	v_mul_f32_e32 v37, v37, v186
	v_mul_f32_e32 v34, v34, v186
	v_mul_f32_e32 v35, v35, v186
	v_mul_f32_e32 v32, v32, v186
	v_mul_f32_e32 v33, v33, v186

; #define LAS __attribute__((address_space(3)))
; DI float xh_max(float x) { const unsigned u = __float_as_uint(x); const auto r = __builtin_amdgcn_permlane32_swap(u, u, false, false); return fmaxf(__uint_as_float(r[0]), __uint_as_float(r[1])); }
; DI float xh_sum(float x) { const unsigned u = __float_as_uint(x); const auto r = __builtin_amdgcn_permlane32_swap(u, u, false, false); return __uint_as_float(r[0]) + __uint_as_float(r[1]); }
; template <int MODE>
; DI void co_finish(f32x16 S, LAS unsigned char* st, int key_base, AttnState& as, int tq, bool rowsel, int vb_in, int hh) {
;     const int vb = vb_in;
;     {
;         const int base = key_base + 4 * hh;
;         const int hi = (MODE == 0) ? (((tq - 31) >> 4) - base) : (tq - base);
;         const int lo = hi - 512;
; #pragma unroll
;         for (int i = 0; i < 16; ++i) { const int c = (i & 3) + 8 * (i >> 2); bool ok = (c <= hi); if (MODE == 2) ok = ok && (c > lo); if (MODE == 1) ok = ok && rowsel; S[i] = ok ? S[i] : -1e30f; }
;     }
;     float mx = S[0];
; #pragma unroll
;     for (int i = 1; i < 16; ++i) mx = fmaxf(mx, S[i]);
;     mx = xh_max(mx);
;     const float mxs = mx * SM_SCALE; const bool need = mxs > as.m + 8.f;
;     const float mnew = need ? mxs : as.m, muse = -fmaxf(mnew, -1e20f); float ps = 0.f;
; #pragma unroll
;     for (int i = 0; i < 16; ++i) { const float p = __builtin_amdgcn_exp2f(__builtin_fmaf(S[i], SM_SCALE, muse)); S[i] = p; ps += p; }
;     ps = xh_sum(ps);
;     if (__builtin_amdgcn_ballot_w64(need) != 0ull) {
;         const float alpha = __builtin_amdgcn_exp2f(as.m - mnew);
;         as.l *= alpha;
; #pragma unroll
;         for (int dt = 0; dt < 4; ++dt)
; #pragma unroll
;             for (int i = 0; i < 16; ++i) as.acc[dt][i] *= alpha;
;     }
.LBB0_433:
	v_sub_u32_e32 v0, v157, v177
	v_add_u32_e32 v0, s80, v0
	v_cmp_lt_i32_e32 vcc, -1, v0
	s_nop 1
	v_cndmask_b32_e32 v3, v153, v16, vcc
	v_cmp_lt_i32_e32 vcc, 0, v0
	v_max_f32_e32 v99, v3, v3
	s_nop 0
	v_cndmask_b32_e32 v4, v153, v17, vcc
	v_cmp_lt_i32_e32 vcc, 1, v0
	s_nop 1
	v_cndmask_b32_e32 v5, v153, v18, vcc
	v_cmp_lt_i32_e32 vcc, 2, v0
	s_nop 1
	v_cndmask_b32_e32 v6, v153, v19, vcc
	v_cmp_lt_i32_e32 vcc, 7, v0
	s_nop 1
	v_cndmask_b32_e32 v7, v153, v20, vcc
	v_cmp_lt_i32_e32 vcc, 8, v0
	s_nop 1
	v_cndmask_b32_e32 v8, v153, v21, vcc
	v_cmp_lt_i32_e32 vcc, 9, v0
	s_nop 1
	v_cndmask_b32_e32 v9, v153, v22, vcc
	v_cmp_lt_i32_e32 vcc, 10, v0
	s_nop 1
	v_cndmask_b32_e32 v10, v153, v23, vcc
	v_cmp_lt_i32_e32 vcc, 15, v0
	s_nop 1
	v_cndmask_b32_e32 v11, v153, v24, vcc
	v_cmp_lt_i32_e32 vcc, 16, v0
	s_nop 1
	v_cndmask_b32_e32 v12, v153, v25, vcc
	v_cmp_lt_i32_e32 vcc, 17, v0
	s_nop 1
	v_cndmask_b32_e32 v13, v153, v26, vcc
	v_cmp_lt_i32_e32 vcc, 18, v0
	s_nop 1
	v_cndmask_b32_e32 v14, v153, v27, vcc
	v_cmp_lt_i32_e32 vcc, 23, v0
	s_nop 1
	v_cndmask_b32_e32 v15, v153, v28, vcc
	v_cmp_lt_i32_e32 vcc, 24, v0
	s_nop 1
	v_cndmask_b32_e32 v96, v153, v29, vcc
	v_cmp_lt_i32_e32 vcc, 25, v0
	s_nop 1
	v_cndmask_b32_e32 v97, v153, v30, vcc
	v_cmp_lt_i32_e32 vcc, 26, v0
	v_max_f32_e32 v0, v4, v4
	v_max_f32_e32 v0, v99, v0
	v_max3_f32 v0, v0, v5, v6
	v_max3_f32 v0, v0, v7, v8
	v_max3_f32 v0, v0, v9, v10
	v_max3_f32 v0, v0, v11, v12
	v_max3_f32 v0, v0, v13, v14
	v_cndmask_b32_e32 v98, v153, v31, vcc
	v_max3_f32 v0, v0, v15, v96
	v_max3_f32 v0, v0, v97, v98
	v_mov_b32_e32 v99, v0
	s_nop 1
	v_permlane32_swap_b32_e32 v0, v99
	v_max_f32_e32 v99, v99, v99
	v_max_f32_e32 v0, v0, v0
	v_max_f32_e32 v0, v0, v99
	v_mul_f32_e32 v0, 0x3e0293ee, v0
	v_add_f32_e32 v99, 0x41000000, v2
	v_cmp_gt_f32_e32 vcc, v0, v99
	s_nop 1
	v_cndmask_b32_e32 v0, v2, v0, vcc
	v_max_f32_e32 v99, v0, v0
	v_max_f32_e32 v99, 0xe0ad78ec, v99
	v_fma_f32 v3, v3, s52, -v99
	v_exp_f32_e32 v3, v3
	v_fma_f32 v4, v4, s52, -v99
	v_exp_f32_e32 v4, v4
	v_fma_f32 v5, v5, s52, -v99
	v_exp_f32_e32 v5, v5
	v_fma_f32 v6, v6, s52, -v99
	v_exp_f32_e32 v6, v6
	v_fma_f32 v7, v7, s52, -v99
	v_add_f32_e32 v100, 0, v3
	v_exp_f32_e32 v7, v7
	v_fma_f32 v8, v8, s52, -v99
	v_add_f32_e32 v100, v4, v100
	v_exp_f32_e32 v8, v8
	v_fma_f32 v9, v9, s52, -v99
	v_add_f32_e32 v100, v5, v100
	v_exp_f32_e32 v9, v9
	v_fma_f32 v10, v10, s52, -v99
	v_add_f32_e32 v100, v6, v100
	v_exp_f32_e32 v10, v10
	v_fma_f32 v11, v11, s52, -v99
	v_add_f32_e32 v100, v7, v100
	v_exp_f32_e32 v11, v11
	v_fma_f32 v12, v12, s52, -v99
	v_add_f32_e32 v100, v8, v100
	v_exp_f32_e32 v12, v12
	v_fma_f32 v13, v13, s52, -v99
	v_add_f32_e32 v100, v9, v100
	v_exp_f32_e32 v13, v13
	v_fma_f32 v14, v14, s52, -v99
	v_add_f32_e32 v100, v10, v100
	v_exp_f32_e32 v14, v14
	v_fma_f32 v15, v15, s52, -v99
	v_add_f32_e32 v100, v11, v100
	v_exp_f32_e32 v15, v15
	v_fma_f32 v96, v96, s52, -v99
	v_add_f32_e32 v100, v12, v100
	v_exp_f32_e32 v96, v96
	v_fma_f32 v97, v97, s52, -v99
	v_add_f32_e32 v100, v13, v100
	v_exp_f32_e32 v97, v97
	v_fma_f32 v98, v98, s52, -v99
	v_add_f32_e32 v100, v14, v100
	v_exp_f32_e32 v98, v98
	v_add_f32_e32 v99, v15, v100
	v_add_f32_e32 v99, v96, v99
	v_add_f32_e32 v99, v97, v99
	v_add_f32_e32 v99, v98, v99
	v_mov_b32_e32 v100, v99
	s_nop 1
	v_permlane32_swap_b32_e32 v99, v100
	s_cbranch_vccz .LBB0_435
	v_sub_f32_e32 v2, v2, v0
	v_exp_f32_e32 v2, v2
	s_nop 0
	v_mul_f32_e32 v179, v179, v2
	v_mul_f32_e32 v94, v94, v2
	v_mul_f32_e32 v95, v95, v2
	v_mul_f32_e32 v92, v92, v2
	v_mul_f32_e32 v93, v93, v2
	v_mul_f32_e32 v90, v90, v2
	v_mul_f32_e32 v91, v91, v2
	v_mul_f32_e32 v88, v88, v2
	v_mul_f32_e32 v89, v89, v2
	v_mul_f32_e32 v86, v86, v2
	v_mul_f32_e32 v87, v87, v2
	v_mul_f32_e32 v84, v84, v2
	v_mul_f32_e32 v85, v85, v2
	v_mul_f32_e32 v82, v82, v2
	v_mul_f32_e32 v83, v83, v2
	v_mul_f32_e32 v80, v80, v2
	v_mul_f32_e32 v81, v81, v2
	v_mul_f32_e32 v78, v78, v2
	v_mul_f32_e32 v79, v79, v2
	v_mul_f32_e32 v76, v76, v2
	v_mul_f32_e32 v77, v77, v2
	v_mul_f32_e32 v74, v74, v2
	v_mul_f32_e32 v75, v75, v2
	v_mul_f32_e32 v72, v72, v2
	v_mul_f32_e32 v73, v73, v2
	v_mul_f32_e32 v70, v70, v2
	v_mul_f32_e32 v71, v71, v2
	v_mul_f32_e32 v68, v68, v2
	v_mul_f32_e32 v69, v69, v2
	v_mul_f32_e32 v66, v66, v2
	v_mul_f32_e32 v67, v67, v2
	v_mul_f32_e32 v64, v64, v2
	v_mul_f32_e32 v65, v65, v2
	v_mul_f32_e32 v62, v62, v2
	v_mul_f32_e32 v63, v63, v2
	v_mul_f32_e32 v60, v60, v2
	v_mul_f32_e32 v61, v61, v2
	v_mul_f32_e32 v58, v58, v2
	v_mul_f32_e32 v59, v59, v2
	v_mul_f32_e32 v56, v56, v2
	v_mul_f32_e32 v57, v57, v2
	v_mul_f32_e32 v54, v54, v2
	v_mul_f32_e32 v55, v55, v2
	v_mul_f32_e32 v52, v52, v2
	v_mul_f32_e32 v53, v53, v2
	v_mul_f32_e32 v50, v50, v2
	v_mul_f32_e32 v51, v51, v2
	v_mul_f32_e32 v48, v48, v2
	v_mul_f32_e32 v49, v49, v2
	v_mul_f32_e32 v46, v46, v2
	v_mul_f32_e32 v47, v47, v2
	v_mul_f32_e32 v44, v44, v2
	v_mul_f32_e32 v45, v45, v2
	v_mul_f32_e32 v42, v42, v2
	v_mul_f32_e32 v43, v43, v2
	v_mul_f32_e32 v40, v40, v2
	v_mul_f32_e32 v41, v41, v2
	v_mul_f32_e32 v38, v38, v2
	v_mul_f32_e32 v39, v39, v2
	v_mul_f32_e32 v36, v36, v2
	v_mul_f32_e32 v37, v37, v2
	v_mul_f32_e32 v34, v34, v2
	v_mul_f32_e32 v35, v35, v2
	v_mul_f32_e32 v32, v32, v2
	v_mul_f32_e32 v33, v33, v2

; #define LAS __attribute__((address_space(3)))
; DI float bf2f(bf16_t u) { return __uint_as_float(((unsigned)u) << 16); }
; DI unsigned pk2(float lo, float hi) { f32x2 v = {lo, hi}; bf16x2_t b = __builtin_convertvector(v, bf16x2_t); return __builtin_bit_cast(unsigned, b); }
; DI float sigmoidf_(float x) { return __builtin_amdgcn_rcpf(1.f + __expf(-x)); }
; #define CO_DRAIN(MODE) do { if (pend) { co_finish<MODE>(Sp, pst, pkb, st, tq, prs, vb, hh); pend = false; } } while (0)
; DI void nsa_block_item(const Params& P, unsigned char* smem_g, int b, int g, int tb, int tid_in) {
;     ...
;     const float g0 = sigmoidf_(bf2f(P_proj[poff + C_GATE + head * 3 + 0])), g1 = sigmoidf_(bf2f(P_proj[poff + C_GATE + head * 3 + 1])), g2 = sigmoidf_(bf2f(P_proj[poff + C_GATE + head * 3 + 2]));
;     const int nA = (((t0b >> 4) + 1) + 31) >> 5;
;     int lo = t0b - 511; if (lo < 0) lo = 0; lo &= ~31;
;     const int nD = ((t0b - lo) >> 5) + 1, n1 = 2 * nA + nD;
;     asm volatile("s_waitcnt vmcnt(0)" ::: "memory");
;     CO_BAR();
;     if (tid < n1) { const unsigned d = tid < nA ? (unsigned)(tid * 32) : (tid < 2 * nA ? ((1u << 16) | (unsigned)((tid - nA) * 32)) : ((2u << 16) | (unsigned)(lo + (tid - 2 * nA) * 32))); list1[tid] = d; }
;     CO_BAR();
;     AttnState st;
;     bool pend = false, prs = false; f32x16 Sp; int pkb = 0; LAS unsigned char* pst = ring;
; #pragma unroll
;     for (int i2 = 0; i2 < 16; ++i2) Sp[i2] = 0.f;
; #pragma unroll
;     for (int s = 0; s < 2; ++s) if (s < n1) co_issue(P, ring, s, list1[s], b, g, wave, lane);
;     int i = 0;
;     attn_reset(st);
;     for (; i < nA; ++i) { CO_STEP2(list1, n1, i); const int kb_ = 32 * i; CO_PIPE(0, 16 * kb_ + 31 <= t0 + 3, kb_, true); }
;     CO_DRAIN(0);
;     {
;         const float inv = st.l > 0.f ? g0 / st.l : 0.f;
; #pragma unroll
;         for (int dt = 0; dt < 4; ++dt)
; #pragma unroll
;             for (int ig = 0; ig < 4; ++ig) { u32x2 w; w.x = pk2(st.acc[dt][4 * ig] * inv, st.acc[dt][4 * ig + 1] * inv); w.y = pk2(st.acc[dt][4 * ig + 2] * inv, st.acc[dt][4 * ig + 3] * inv); totw[(dt * 4 + ig) * 64 + lane] = w; }
;     }
;     {
;         const float invl = st.l > 0.f ? 1.f / st.l : 0.f; const float mfin = st.m;
;         for (int k = lane; k < 512; k += 64) psum[k] = 0.f;
.LBB0_438:
	v_lshlrev_b32_e32 v2, 16, v154
	v_mul_f32_e32 v2, 0xbfb8aa3b, v2
	v_exp_f32_e32 v2, v2
	s_lshl_b32 s0, s71, 13
	s_add_i32 s2, s0, 0
	v_lshl_add_u32 v5, v155, 3, s2
	v_add_f32_e32 v2, 1.0, v2
	v_rcp_f32_e32 v2, v2
	v_cmp_lt_f32_e64 s[2:3], 0, v179
	v_add_u32_e32 v157, 0x10000, v5
	s_mul_i32 s8, s71, 0xa00
	v_div_scale_f32 v3, s[0:1], v179, v179, v2
	v_rcp_f32_e32 v4, v3
	v_div_scale_f32 v6, vcc, v2, v179, v2
	s_add_i32 s72, s8, 0
	v_fma_f32 v7, -v3, v4, 1.0
	v_fmac_f32_e32 v4, v7, v4
	v_mul_f32_e32 v7, v6, v4
	v_fma_f32 v8, -v3, v7, v6
	v_fmac_f32_e32 v7, v8, v4
	v_fma_f32 v3, -v3, v7, v6
	v_div_fmas_f32 v3, v3, v4, v7
	v_div_fixup_f32 v2, v3, v179, v2
	v_cndmask_b32_e64 v2, 0, v2, s[2:3]
	v_mul_f32_e32 v4, v80, v2
	v_mul_f32_e32 v5, v81, v2
	v_mul_f32_e32 v6, v82, v2
	v_mul_f32_e32 v7, v83, v2
	v_cvt_pk_bf16_f32 v4, v4, v5
	v_cvt_pk_bf16_f32 v5, v6, v7
	v_mul_f32_e32 v6, v84, v2
	v_mul_f32_e32 v7, v85, v2
	v_mul_f32_e32 v8, v86, v2
	v_mul_f32_e32 v9, v87, v2
	v_cvt_pk_bf16_f32 v6, v6, v7
	v_cvt_pk_bf16_f32 v7, v8, v9
	ds_write2st64_b64 v157, v[4:5], v[6:7] offset1:1
	v_mul_f32_e32 v4, v88, v2
	v_mul_f32_e32 v5, v89, v2
	v_mul_f32_e32 v6, v90, v2
	v_mul_f32_e32 v7, v91, v2
	v_cvt_pk_bf16_f32 v4, v4, v5
	v_cvt_pk_bf16_f32 v5, v6, v7
	v_mul_f32_e32 v6, v92, v2
	v_mul_f32_e32 v7, v93, v2
	v_mul_f32_e32 v8, v94, v2
	v_mul_f32_e32 v9, v95, v2
	v_cvt_pk_bf16_f32 v6, v6, v7
	v_cvt_pk_bf16_f32 v7, v8, v9
	ds_write2st64_b64 v157, v[4:5], v[6:7] offset0:2 offset1:3
	v_mul_f32_e32 v4, v64, v2
	v_mul_f32_e32 v5, v65, v2
	v_mul_f32_e32 v6, v66, v2
	v_mul_f32_e32 v7, v67, v2
	v_cvt_pk_bf16_f32 v4, v4, v5
	v_cvt_pk_bf16_f32 v5, v6, v7
	v_mul_f32_e32 v6, v68, v2
	v_mul_f32_e32 v7, v69, v2
	v_mul_f32_e32 v8, v70, v2
	v_mul_f32_e32 v9, v71, v2
	v_cvt_pk_bf16_f32 v6, v6, v7
	v_cvt_pk_bf16_f32 v7, v8, v9
	ds_write2st64_b64 v157, v[4:5], v[6:7] offset0:4 offset1:5
	v_mul_f32_e32 v4, v72, v2
	v_mul_f32_e32 v5, v73, v2
	v_mul_f32_e32 v6, v74, v2
	v_mul_f32_e32 v7, v75, v2
	v_cvt_pk_bf16_f32 v4, v4, v5
	v_cvt_pk_bf16_f32 v5, v6, v7
	v_mul_f32_e32 v6, v76, v2
	v_mul_f32_e32 v7, v77, v2
	v_mul_f32_e32 v8, v78, v2
	v_mul_f32_e32 v9, v79, v2
	v_cvt_pk_bf16_f32 v6, v6, v7
	v_cvt_pk_bf16_f32 v7, v8, v9
	ds_write2st64_b64 v157, v[4:5], v[6:7] offset0:6 offset1:7
	v_mul_f32_e32 v4, v48, v2
	v_mul_f32_e32 v5, v49, v2
	v_mul_f32_e32 v6, v50, v2
	v_mul_f32_e32 v7, v51, v2
	v_cvt_pk_bf16_f32 v4, v4, v5
	v_cvt_pk_bf16_f32 v5, v6, v7
	v_mul_f32_e32 v6, v52, v2
	v_mul_f32_e32 v7, v53, v2
	v_mul_f32_e32 v8, v54, v2
	v_mul_f32_e32 v9, v55, v2
	v_cvt_pk_bf16_f32 v6, v6, v7
	v_cvt_pk_bf16_f32 v7, v8, v9
	ds_write2st64_b64 v157, v[4:5], v[6:7] offset0:8 offset1:9
	v_mul_f32_e32 v4, v56, v2
	v_mul_f32_e32 v5, v57, v2
	v_mul_f32_e32 v6, v58, v2
	v_mul_f32_e32 v7, v59, v2
	v_cvt_pk_bf16_f32 v4, v4, v5
	v_cvt_pk_bf16_f32 v5, v6, v7
	v_mul_f32_e32 v6, v60, v2
	v_mul_f32_e32 v7, v61, v2
	v_mul_f32_e32 v8, v62, v2
	v_mul_f32_e32 v9, v63, v2
	v_cvt_pk_bf16_f32 v6, v6, v7
	v_cvt_pk_bf16_f32 v7, v8, v9
	ds_write2st64_b64 v157, v[4:5], v[6:7] offset0:10 offset1:11
	v_mul_f32_e32 v4, v32, v2
	v_mul_f32_e32 v5, v33, v2
	v_mul_f32_e32 v6, v34, v2
	v_mul_f32_e32 v7, v35, v2
	v_cvt_pk_bf16_f32 v4, v4, v5
	v_cvt_pk_bf16_f32 v5, v6, v7
	v_mul_f32_e32 v6, v36, v2
	v_mul_f32_e32 v7, v37, v2
	v_mul_f32_e32 v8, v38, v2
	v_mul_f32_e32 v9, v39, v2
	v_cvt_pk_bf16_f32 v6, v6, v7
	v_cvt_pk_bf16_f32 v7, v8, v9
	ds_write2st64_b64 v157, v[4:5], v[6:7] offset0:12 offset1:13
	v_mul_f32_e32 v4, v40, v2
	v_mul_f32_e32 v5, v41, v2
	v_mul_f32_e32 v6, v42, v2
	v_mul_f32_e32 v7, v43, v2
	s_add_i32 s71, s72, 0x20000
	v_cvt_pk_bf16_f32 v4, v4, v5
	v_cvt_pk_bf16_f32 v5, v6, v7
	v_mul_f32_e32 v6, v44, v2
	v_mul_f32_e32 v7, v45, v2
	v_mul_f32_e32 v3, v47, v2
	v_mul_f32_e32 v2, v46, v2
	v_cvt_pk_bf16_f32 v6, v6, v7
	v_cvt_pk_bf16_f32 v7, v2, v3
	v_lshl_add_u32 v2, v155, 2, s71
	s_cmp_ge_i32 s40, s70
	ds_write2st64_b64 v157, v[4:5], v[6:7] offset0:14 offset1:15
	ds_write2st64_b32 v2, v1, v1 offset1:1
	ds_write2st64_b32 v2, v1, v1 offset0:2 offset1:3
	ds_write2st64_b32 v2, v1, v1 offset0:4 offset1:5
	ds_write2st64_b32 v2, v1, v1 offset0:6 offset1:7
	s_cbranch_scc1 .LBB0_485
	v_div_scale_f32 v2, s[0:1], v179, v179, 1.0
	v_rcp_f32_e32 v3, v2
	s_lshl_b32 s0, s67, 1
	s_add_u32 s0, s30, s0
	s_addc_u32 s1, s31, 0
	v_fma_f32 v5, -v2, v3, 1.0
	s_lshl_b32 s4, s22, 1
	v_div_scale_f32 v4, vcc, 1.0, v179, 1.0
	v_fmac_f32_e32 v3, v5, v3
	s_add_u32 s4, s21, s4
	v_mul_f32_e32 v5, v4, v3
	s_addc_u32 s5, s23, 0
	s_lshl_b32 s9, s66, 1
	v_fma_f32 v6, -v2, v5, v4
	s_add_u32 s73, s0, s9
	v_fmac_f32_e32 v5, v6, v3
	s_addc_u32 s74, s1, 0
	s_lshl_b32 s0, s40, 2
	v_fma_f32 v2, -v2, v5, v4
	s_add_i32 s77, s0, 0x25008
	s_lshl_b32 s0, s40, 9
	s_lshl_b32 s1, s68, 9
	v_div_fmas_f32 v2, v2, v3, v5
	s_sub_i32 s78, s0, s1
	v_lshl_or_b32 v5, s40, 5, v177
	s_lshl_b32 s0, s68, 5
	v_subrev_u32_e32 v5, s0, v5
	v_div_fixup_f32 v2, v2, v179, 1.0
	v_lshlrev_b32_e32 v4, 9, v176
	v_lshlrev_b32_e32 v5, 2, v5
	v_cndmask_b32_e64 v2, 0, v2, s[2:3]
	v_cmp_eq_u32_e64 s[2:3], 0, v178
	s_add_i32 s75, s65, 0
	s_lshl_b32 s76, s40, 14
	v_lshlrev_b32_e32 v3, 6, v144
	v_add3_u32 v4, s8, v4, v5
	s_branch .LBB0_442

; #define LAS __attribute__((address_space(3)))
; DI float xh_max(float x) { const unsigned u = __float_as_uint(x); const auto r = __builtin_amdgcn_permlane32_swap(u, u, false, false); return fmaxf(__uint_as_float(r[0]), __uint_as_float(r[1])); }
; DI float xh_sum(float x) { const unsigned u = __float_as_uint(x); const auto r = __builtin_amdgcn_permlane32_swap(u, u, false, false); return __uint_as_float(r[0]) + __uint_as_float(r[1]); }
; #define CO_PIPE(MODE, REL, KB, RS) do { const bool rel_ = (REL); LAS unsigned char* sp_ = ring + (i & 3) * 16384; f32x16 Sn_; \
;     if (rel_) Sn_ = co_qk1(sp_, qf, ka); \
;     if (pend) co_finish<MODE>(Sp, pst, pkb, st, tq, prs, vb, hh); \
;     pend = rel_; if (rel_) { Sp = Sn_; pst = sp_; pkb = (KB); prs = (RS); } } while (0)
; template <int MODE>
; DI void co_finish(f32x16 S, LAS unsigned char* st, int key_base, AttnState& as, int tq, bool rowsel, int vb_in, int hh) {
;     const int vb = vb_in;
;     {
;         const int base = key_base + 4 * hh;
;         const int hi = (MODE == 0) ? (((tq - 31) >> 4) - base) : (tq - base);
;         const int lo = hi - 512;
; #pragma unroll
;         for (int i = 0; i < 16; ++i) { const int c = (i & 3) + 8 * (i >> 2); bool ok = (c <= hi); if (MODE == 2) ok = ok && (c > lo); if (MODE == 1) ok = ok && rowsel; S[i] = ok ? S[i] : -1e30f; }
;     }
;     float mx = S[0];
; #pragma unroll
;     for (int i = 1; i < 16; ++i) mx = fmaxf(mx, S[i]);
;     mx = xh_max(mx);
;     const float mxs = mx * SM_SCALE; const bool need = mxs > as.m + 8.f;
;     const float mnew = need ? mxs : as.m, muse = -fmaxf(mnew, -1e20f); float ps = 0.f;
; #pragma unroll
;     for (int i = 0; i < 16; ++i) { const float p = __builtin_amdgcn_exp2f(__builtin_fmaf(S[i], SM_SCALE, muse)); S[i] = p; ps += p; }
;     ps = xh_sum(ps);
;     if (__builtin_amdgcn_ballot_w64(need) != 0ull) {
;         const float alpha = __builtin_amdgcn_exp2f(as.m - mnew);
;         as.l *= alpha;
; #pragma unroll
;         for (int dt = 0; dt < 4; ++dt)
; #pragma unroll
;             for (int i = 0; i < 16; ++i) as.acc[dt][i] *= alpha;
;     }
; DI void nsa_block_item(const Params& P, unsigned char* smem_g, int b, int g, int tb, int tid_in) {
;     ...
;     for (; i < n1; ++i) { CO_STEP2(list1, n1, i); const int kb_ = lo + 32 * (i - 2 * nA); CO_PIPE(2, kb_ + 31 >= t0 - 511 && kb_ <= t0 + 3, kb_, true); }
.LBB0_517:
	s_andn2_b64 vcc, exec, s[36:37]
	s_cbranch_vccnz .LBB0_521
	s_add_i32 s88, s72, s79
	s_sub_i32 s88, s88, 34
	s_cmp_lt_u32 s88, 0x1de
	s_cbranch_scc1 .Lfastf_win
	v_add_u32_e32 v0, s79, v145
	v_cmp_gt_u32_e32 vcc, s53, v0
	v_add_u32_e32 v3, -1, v0
	v_add_u32_e32 v4, -2, v0
	v_cndmask_b32_e32 v2, v153, v16, vcc
	v_cmp_gt_u32_e32 vcc, s53, v3
	v_add_u32_e32 v5, -3, v0
	v_add_u32_e32 v6, -8, v0
	v_cndmask_b32_e32 v3, v153, v17, vcc
	v_cmp_gt_u32_e32 vcc, s53, v4
	v_add_u32_e32 v7, -9, v0
	v_add_u32_e32 v8, -10, v0
	v_cndmask_b32_e32 v4, v153, v18, vcc
	v_cmp_gt_u32_e32 vcc, s53, v5
	v_add_u32_e32 v9, -11, v0
	v_add_u32_e32 v10, -16, v0
	v_cndmask_b32_e32 v5, v153, v19, vcc
	v_cmp_gt_u32_e32 vcc, s53, v6
	v_subrev_u32_e32 v11, 17, v0
	v_subrev_u32_e32 v12, 18, v0
	v_cndmask_b32_e32 v6, v153, v20, vcc
	v_cmp_gt_u32_e32 vcc, s53, v7
	v_subrev_u32_e32 v13, 19, v0
	v_subrev_u32_e32 v14, 24, v0
	v_cndmask_b32_e32 v7, v153, v21, vcc
	v_cmp_gt_u32_e32 vcc, s53, v8
	v_subrev_u32_e32 v15, 25, v0
	v_subrev_u32_e32 v176, 26, v0
	v_cndmask_b32_e32 v8, v153, v22, vcc
	v_cmp_gt_u32_e32 vcc, s53, v9
	v_subrev_u32_e32 v0, 27, v0
	s_nop 0
	v_cndmask_b32_e32 v9, v153, v23, vcc
	v_cmp_gt_u32_e32 vcc, s53, v10
	s_nop 1
	v_cndmask_b32_e32 v10, v153, v24, vcc
	v_cmp_gt_u32_e32 vcc, s53, v11
	s_nop 1
	v_cndmask_b32_e32 v11, v153, v25, vcc
	v_cmp_gt_u32_e32 vcc, s53, v12
	s_nop 1
	v_cndmask_b32_e32 v12, v153, v26, vcc
	v_cmp_gt_u32_e32 vcc, s53, v13
	s_nop 1
	v_cndmask_b32_e32 v13, v153, v27, vcc
	v_cmp_gt_u32_e32 vcc, s53, v14
	s_nop 1
	v_cndmask_b32_e32 v14, v153, v28, vcc
	v_cmp_gt_u32_e32 vcc, s53, v15
	s_nop 1
	v_cndmask_b32_e32 v15, v153, v29, vcc
	v_cmp_gt_u32_e32 vcc, s53, v176
	v_max_f32_e32 v176, v3, v3
	s_nop 0
	v_cndmask_b32_e32 v178, v153, v30, vcc
	v_cmp_gt_u32_e32 vcc, s53, v0
	v_max_f32_e32 v0, v2, v2
	v_max_f32_e32 v0, v0, v176
	v_max3_f32 v0, v0, v4, v5
	v_max3_f32 v0, v0, v6, v7
	v_max3_f32 v0, v0, v8, v9
	v_max3_f32 v0, v0, v10, v11
	v_max3_f32 v0, v0, v12, v13
	v_cndmask_b32_e32 v179, v153, v31, vcc
	v_max3_f32 v0, v0, v14, v15
	v_max3_f32 v0, v0, v178, v179
	v_mov_b32_e32 v176, v0
	s_nop 1
	v_permlane32_swap_b32_e32 v0, v176
	v_max_f32_e32 v176, v176, v176
	v_max_f32_e32 v0, v0, v0
	v_max_f32_e32 v0, v0, v176
	v_mul_f32_e32 v0, 0x3e0293ee, v0
	v_add_f32_e32 v176, 0x41000000, v177
	v_cmp_gt_f32_e32 vcc, v0, v176
	s_nop 1
	v_cndmask_b32_e32 v176, v177, v0, vcc
	v_max_f32_e32 v0, v176, v176
	v_max_f32_e32 v180, 0xe0ad78ec, v0
	v_fma_f32 v0, v2, s52, -v180
	v_exp_f32_e32 v0, v0
	v_fma_f32 v2, v3, s52, -v180
	v_exp_f32_e32 v2, v2
	v_fma_f32 v3, v4, s52, -v180
	v_exp_f32_e32 v3, v3
	v_fma_f32 v4, v5, s52, -v180
	v_exp_f32_e32 v4, v4
	v_add_f32_e32 v5, 0, v0
	v_add_f32_e32 v5, v2, v5
	v_add_f32_e32 v5, v3, v5
	v_add_f32_e32 v181, v4, v5
	v_fma_f32 v5, v6, s52, -v180
	v_exp_f32_e32 v5, v5
	v_fma_f32 v6, v7, s52, -v180
	v_exp_f32_e32 v6, v6
	v_fma_f32 v7, v8, s52, -v180
	v_exp_f32_e32 v7, v7
	v_fma_f32 v8, v9, s52, -v180
	v_exp_f32_e32 v8, v8
	v_add_f32_e32 v9, v5, v181
	v_add_f32_e32 v9, v6, v9
	v_add_f32_e32 v9, v7, v9
	v_add_f32_e32 v181, v8, v9
	v_fma_f32 v9, v10, s52, -v180
	v_exp_f32_e32 v9, v9
	v_fma_f32 v10, v11, s52, -v180
	v_exp_f32_e32 v10, v10
	v_fma_f32 v11, v12, s52, -v180
	v_exp_f32_e32 v11, v11
	v_fma_f32 v12, v13, s52, -v180
	v_exp_f32_e32 v12, v12
	v_add_f32_e32 v13, v9, v181
	v_add_f32_e32 v13, v10, v13
	v_add_f32_e32 v13, v11, v13
	v_add_f32_e32 v181, v12, v13
	v_fma_f32 v13, v14, s52, -v180
	v_exp_f32_e32 v13, v13
	v_fma_f32 v14, v15, s52, -v180
	v_exp_f32_e32 v14, v14
	v_fma_f32 v15, v178, s52, -v180
	v_exp_f32_e32 v15, v15
	v_fma_f32 v178, v179, s52, -v180
	v_exp_f32_e32 v178, v178
	v_add_f32_e32 v179, v13, v181
	v_add_f32_e32 v179, v14, v179
	v_add_f32_e32 v179, v15, v179
	v_add_f32_e32 v179, v178, v179
	v_mov_b32_e32 v180, v179
	s_nop 1
	v_permlane32_swap_b32_e32 v179, v180
	s_cbranch_vccz .LBB0_520
	v_sub_f32_e32 v177, v177, v176
	v_exp_f32_e32 v182, v177
	s_nop 0
	v_mul_f32_e32 v175, v175, v182
	v_mul_f32_e32 v94, v94, v182
	v_mul_f32_e32 v95, v95, v182
	v_mul_f32_e32 v92, v92, v182
	v_mul_f32_e32 v93, v93, v182
	v_mul_f32_e32 v90, v90, v182
	v_mul_f32_e32 v91, v91, v182
	v_mul_f32_e32 v88, v88, v182
	v_mul_f32_e32 v89, v89, v182
	v_mul_f32_e32 v86, v86, v182
	v_mul_f32_e32 v87, v87, v182
	v_mul_f32_e32 v84, v84, v182
	v_mul_f32_e32 v85, v85, v182
	v_mul_f32_e32 v82, v82, v182
	v_mul_f32_e32 v83, v83, v182
	v_mul_f32_e32 v80, v80, v182
	v_mul_f32_e32 v81, v81, v182
	v_mul_f32_e32 v78, v78, v182
	v_mul_f32_e32 v79, v79, v182
	v_mul_f32_e32 v76, v76, v182
	v_mul_f32_e32 v77, v77, v182
	v_mul_f32_e32 v74, v74, v182
	v_mul_f32_e32 v75, v75, v182
	v_mul_f32_e32 v72, v72, v182
	v_mul_f32_e32 v73, v73, v182
	v_mul_f32_e32 v70, v70, v182
	v_mul_f32_e32 v71, v71, v182
	v_mul_f32_e32 v68, v68, v182
	v_mul_f32_e32 v69, v69, v182
	v_mul_f32_e32 v66, v66, v182
	v_mul_f32_e32 v67, v67, v182
	v_mul_f32_e32 v64, v64, v182
	v_mul_f32_e32 v65, v65, v182
	v_mul_f32_e32 v62, v62, v182
	v_mul_f32_e32 v63, v63, v182
	v_mul_f32_e32 v60, v60, v182
	v_mul_f32_e32 v61, v61, v182
	v_mul_f32_e32 v58, v58, v182
	v_mul_f32_e32 v59, v59, v182
	v_mul_f32_e32 v56, v56, v182
	v_mul_f32_e32 v57, v57, v182
	v_mul_f32_e32 v54, v54, v182
	v_mul_f32_e32 v55, v55, v182
	v_mul_f32_e32 v52, v52, v182
	v_mul_f32_e32 v53, v53, v182
	v_mul_f32_e32 v50, v50, v182
	v_mul_f32_e32 v51, v51, v182
	v_mul_f32_e32 v48, v48, v182
	v_mul_f32_e32 v49, v49, v182
	v_mul_f32_e32 v46, v46, v182
	v_mul_f32_e32 v47, v47, v182
	v_mul_f32_e32 v44, v44, v182
	v_mul_f32_e32 v45, v45, v182
	v_mul_f32_e32 v42, v42, v182
	v_mul_f32_e32 v43, v43, v182
	v_mul_f32_e32 v40, v40, v182
	v_mul_f32_e32 v41, v41, v182
	v_mul_f32_e32 v38, v38, v182
	v_mul_f32_e32 v39, v39, v182
	v_mul_f32_e32 v36, v36, v182
	v_mul_f32_e32 v37, v37, v182
	v_mul_f32_e32 v34, v34, v182
	v_mul_f32_e32 v35, v35, v182
	v_mul_f32_e32 v32, v32, v182
	v_mul_f32_e32 v33, v33, v182

; #define LAS __attribute__((address_space(3)))
; DI float xh_max(float x) { const unsigned u = __float_as_uint(x); const auto r = __builtin_amdgcn_permlane32_swap(u, u, false, false); return fmaxf(__uint_as_float(r[0]), __uint_as_float(r[1])); }
; DI float xh_sum(float x) { const unsigned u = __float_as_uint(x); const auto r = __builtin_amdgcn_permlane32_swap(u, u, false, false); return __uint_as_float(r[0]) + __uint_as_float(r[1]); }
; template <int MODE>
; DI void co_finish(f32x16 S, LAS unsigned char* st, int key_base, AttnState& as, int tq, bool rowsel, int vb_in, int hh) {
;     const int vb = vb_in;
;     {
;         const int base = key_base + 4 * hh;
;         const int hi = (MODE == 0) ? (((tq - 31) >> 4) - base) : (tq - base);
;         const int lo = hi - 512;
; #pragma unroll
;         for (int i = 0; i < 16; ++i) { const int c = (i & 3) + 8 * (i >> 2); bool ok = (c <= hi); if (MODE == 2) ok = ok && (c > lo); if (MODE == 1) ok = ok && rowsel; S[i] = ok ? S[i] : -1e30f; }
;     }
;     float mx = S[0];
; #pragma unroll
;     for (int i = 1; i < 16; ++i) mx = fmaxf(mx, S[i]);
;     mx = xh_max(mx);
;     const float mxs = mx * SM_SCALE; const bool need = mxs > as.m + 8.f;
;     const float mnew = need ? mxs : as.m, muse = -fmaxf(mnew, -1e20f); float ps = 0.f;
; #pragma unroll
;     for (int i = 0; i < 16; ++i) { const float p = __builtin_amdgcn_exp2f(__builtin_fmaf(S[i], SM_SCALE, muse)); S[i] = p; ps += p; }
;     ps = xh_sum(ps);
;     if (__builtin_amdgcn_ballot_w64(need) != 0ull) {
;         const float alpha = __builtin_amdgcn_exp2f(as.m - mnew);
;         as.l *= alpha;
; #pragma unroll
;         for (int dt = 0; dt < 4; ++dt)
; #pragma unroll
;             for (int i = 0; i < 16; ++i) as.acc[dt][i] *= alpha;
;     }
.LBB0_526:
	s_andn2_b64 vcc, exec, s[8:9]
	s_cbranch_vccnz .LBB0_530
	v_add_u32_e32 v0, s79, v145
	v_cmp_gt_u32_e32 vcc, s53, v0
	v_add_u32_e32 v3, -1, v0
	v_add_u32_e32 v4, -2, v0
	v_cndmask_b32_e32 v2, v153, v16, vcc
	v_cmp_gt_u32_e32 vcc, s53, v3
	v_add_u32_e32 v5, -3, v0
	v_add_u32_e32 v6, -8, v0
	v_cndmask_b32_e32 v3, v153, v17, vcc
	v_cmp_gt_u32_e32 vcc, s53, v4
	v_add_u32_e32 v7, -9, v0
	v_add_u32_e32 v8, -10, v0
	v_cndmask_b32_e32 v4, v153, v18, vcc
	v_cmp_gt_u32_e32 vcc, s53, v5
	v_add_u32_e32 v9, -11, v0
	v_add_u32_e32 v10, -16, v0
	v_cndmask_b32_e32 v5, v153, v19, vcc
	v_cmp_gt_u32_e32 vcc, s53, v6
	v_subrev_u32_e32 v11, 17, v0
	v_subrev_u32_e32 v12, 18, v0
	v_cndmask_b32_e32 v6, v153, v20, vcc
	v_cmp_gt_u32_e32 vcc, s53, v7
	v_subrev_u32_e32 v13, 19, v0
	v_subrev_u32_e32 v14, 24, v0
	v_cndmask_b32_e32 v7, v153, v21, vcc
	v_cmp_gt_u32_e32 vcc, s53, v8
	v_subrev_u32_e32 v15, 25, v0
	v_subrev_u32_e32 v96, 26, v0
	v_cndmask_b32_e32 v8, v153, v22, vcc
	v_cmp_gt_u32_e32 vcc, s53, v9
	v_subrev_u32_e32 v0, 27, v0
	v_max_f32_e32 v98, v3, v3
	v_cndmask_b32_e32 v9, v153, v23, vcc
	v_cmp_gt_u32_e32 vcc, s53, v10
	s_nop 1
	v_cndmask_b32_e32 v10, v153, v24, vcc
	v_cmp_gt_u32_e32 vcc, s53, v11
	s_nop 1
	v_cndmask_b32_e32 v11, v153, v25, vcc
	v_cmp_gt_u32_e32 vcc, s53, v12
	s_nop 1
	v_cndmask_b32_e32 v12, v153, v26, vcc
	v_cmp_gt_u32_e32 vcc, s53, v13
	s_nop 1
	v_cndmask_b32_e32 v13, v153, v27, vcc
	v_cmp_gt_u32_e32 vcc, s53, v14
	s_nop 1
	v_cndmask_b32_e32 v14, v153, v28, vcc
	v_cmp_gt_u32_e32 vcc, s53, v15
	s_nop 1
	v_cndmask_b32_e32 v15, v153, v29, vcc
	v_cmp_gt_u32_e32 vcc, s53, v96
	s_nop 1
	v_cndmask_b32_e32 v96, v153, v30, vcc
	v_cmp_gt_u32_e32 vcc, s53, v0
	v_max_f32_e32 v0, v2, v2
	v_max_f32_e32 v0, v0, v98
	v_max3_f32 v0, v0, v4, v5
	v_max3_f32 v0, v0, v6, v7
	v_max3_f32 v0, v0, v8, v9
	v_max3_f32 v0, v0, v10, v11
	v_max3_f32 v0, v0, v12, v13
	v_cndmask_b32_e32 v97, v153, v31, vcc
	v_max3_f32 v0, v0, v14, v15
	v_max3_f32 v0, v0, v96, v97
	v_mov_b32_e32 v98, v0
	s_nop 1
	v_permlane32_swap_b32_e32 v0, v98
	v_max_f32_e32 v98, v98, v98
	v_max_f32_e32 v0, v0, v0
	v_max_f32_e32 v0, v0, v98
	v_mul_f32_e32 v0, 0x3e0293ee, v0
	v_add_f32_e32 v98, 0x41000000, v176
	v_cmp_gt_f32_e32 vcc, v0, v98
	s_nop 1
	v_cndmask_b32_e32 v99, v176, v0, vcc
	v_max_f32_e32 v0, v99, v99
	v_max_f32_e32 v98, 0xe0ad78ec, v0
	v_fma_f32 v0, v2, s52, -v98
	v_exp_f32_e32 v0, v0
	v_fma_f32 v2, v3, s52, -v98
	v_exp_f32_e32 v2, v2
	v_fma_f32 v3, v4, s52, -v98
	v_exp_f32_e32 v3, v3
	v_fma_f32 v4, v5, s52, -v98
	v_exp_f32_e32 v4, v4
	v_add_f32_e32 v5, 0, v0
	v_add_f32_e32 v5, v2, v5
	v_add_f32_e32 v5, v3, v5
	v_add_f32_e32 v100, v4, v5
	v_fma_f32 v5, v6, s52, -v98
	v_exp_f32_e32 v5, v5
	v_fma_f32 v6, v7, s52, -v98
	v_exp_f32_e32 v6, v6
	v_fma_f32 v7, v8, s52, -v98
	v_exp_f32_e32 v7, v7
	v_fma_f32 v8, v9, s52, -v98
	v_exp_f32_e32 v8, v8
	v_add_f32_e32 v9, v5, v100
	v_add_f32_e32 v9, v6, v9
	v_add_f32_e32 v9, v7, v9
	v_add_f32_e32 v100, v8, v9
	v_fma_f32 v9, v10, s52, -v98
	v_exp_f32_e32 v9, v9
	v_fma_f32 v10, v11, s52, -v98
	v_exp_f32_e32 v10, v10
	v_fma_f32 v11, v12, s52, -v98
	v_exp_f32_e32 v11, v11
	v_fma_f32 v12, v13, s52, -v98
	v_exp_f32_e32 v12, v12
	v_add_f32_e32 v13, v9, v100
	v_add_f32_e32 v13, v10, v13
	v_add_f32_e32 v13, v11, v13
	v_add_f32_e32 v100, v12, v13
	v_fma_f32 v13, v14, s52, -v98
	v_exp_f32_e32 v13, v13
	v_fma_f32 v14, v15, s52, -v98
	v_exp_f32_e32 v14, v14
	v_fma_f32 v15, v96, s52, -v98
	v_exp_f32_e32 v15, v15
	v_fma_f32 v96, v97, s52, -v98
	v_exp_f32_e32 v96, v96
	v_add_f32_e32 v97, v13, v100
	v_add_f32_e32 v97, v14, v97
	v_add_f32_e32 v97, v15, v97
	v_add_f32_e32 v97, v96, v97
	v_mov_b32_e32 v98, v97
	s_nop 1
	v_permlane32_swap_b32_e32 v97, v98
	s_cbranch_vccz .LBB0_529
	v_sub_f32_e32 v99, v176, v99
	v_exp_f32_e32 v100, v99
	s_nop 0
	v_mul_f32_e32 v175, v175, v100
	v_mul_f32_e32 v94, v94, v100
	v_mul_f32_e32 v95, v95, v100
	v_mul_f32_e32 v92, v92, v100
	v_mul_f32_e32 v93, v93, v100
	v_mul_f32_e32 v90, v90, v100
	v_mul_f32_e32 v91, v91, v100
	v_mul_f32_e32 v88, v88, v100
	v_mul_f32_e32 v89, v89, v100
	v_mul_f32_e32 v86, v86, v100
	v_mul_f32_e32 v87, v87, v100
	v_mul_f32_e32 v84, v84, v100
	v_mul_f32_e32 v85, v85, v100
	v_mul_f32_e32 v82, v82, v100
	v_mul_f32_e32 v83, v83, v100
	v_mul_f32_e32 v80, v80, v100
	v_mul_f32_e32 v81, v81, v100
	v_mul_f32_e32 v78, v78, v100
	v_mul_f32_e32 v79, v79, v100
	v_mul_f32_e32 v76, v76, v100
	v_mul_f32_e32 v77, v77, v100
	v_mul_f32_e32 v74, v74, v100
	v_mul_f32_e32 v75, v75, v100
	v_mul_f32_e32 v72, v72, v100
	v_mul_f32_e32 v73, v73, v100
	v_mul_f32_e32 v70, v70, v100
	v_mul_f32_e32 v71, v71, v100
	v_mul_f32_e32 v68, v68, v100
	v_mul_f32_e32 v69, v69, v100
	v_mul_f32_e32 v66, v66, v100
	v_mul_f32_e32 v67, v67, v100
	v_mul_f32_e32 v64, v64, v100
	v_mul_f32_e32 v65, v65, v100
	v_mul_f32_e32 v62, v62, v100
	v_mul_f32_e32 v63, v63, v100
	v_mul_f32_e32 v60, v60, v100
	v_mul_f32_e32 v61, v61, v100
	v_mul_f32_e32 v58, v58, v100
	v_mul_f32_e32 v59, v59, v100
	v_mul_f32_e32 v56, v56, v100
	v_mul_f32_e32 v57, v57, v100
	v_mul_f32_e32 v54, v54, v100
	v_mul_f32_e32 v55, v55, v100
	v_mul_f32_e32 v52, v52, v100
	v_mul_f32_e32 v53, v53, v100
	v_mul_f32_e32 v50, v50, v100
	v_mul_f32_e32 v51, v51, v100
	v_mul_f32_e32 v48, v48, v100
	v_mul_f32_e32 v49, v49, v100
	v_mul_f32_e32 v46, v46, v100
	v_mul_f32_e32 v47, v47, v100
	v_mul_f32_e32 v44, v44, v100
	v_mul_f32_e32 v45, v45, v100
	v_mul_f32_e32 v42, v42, v100
	v_mul_f32_e32 v43, v43, v100
	v_mul_f32_e32 v40, v40, v100
	v_mul_f32_e32 v41, v41, v100
	v_mul_f32_e32 v38, v38, v100
	v_mul_f32_e32 v39, v39, v100
	v_mul_f32_e32 v36, v36, v100
	v_mul_f32_e32 v37, v37, v100
	v_mul_f32_e32 v34, v34, v100
	v_mul_f32_e32 v35, v35, v100
	v_mul_f32_e32 v32, v32, v100
	v_mul_f32_e32 v33, v33, v100

; #define LAS __attribute__((address_space(3)))
; DI float xh_max(float x) { const unsigned u = __float_as_uint(x); const auto r = __builtin_amdgcn_permlane32_swap(u, u, false, false); return fmaxf(__uint_as_float(r[0]), __uint_as_float(r[1])); }
; DI float xh_sum(float x) { const unsigned u = __float_as_uint(x); const auto r = __builtin_amdgcn_permlane32_swap(u, u, false, false); return __uint_as_float(r[0]) + __uint_as_float(r[1]); }
; template <int MODE>
; DI void co_finish(f32x16 S, LAS unsigned char* st, int key_base, AttnState& as, int tq, bool rowsel, int vb_in, int hh) {
;     const int vb = vb_in;
;     {
;         const int base = key_base + 4 * hh;
;         const int hi = (MODE == 0) ? (((tq - 31) >> 4) - base) : (tq - base);
;         const int lo = hi - 512;
; #pragma unroll
;         for (int i = 0; i < 16; ++i) { const int c = (i & 3) + 8 * (i >> 2); bool ok = (c <= hi); if (MODE == 2) ok = ok && (c > lo); if (MODE == 1) ok = ok && rowsel; S[i] = ok ? S[i] : -1e30f; }
;     }
;     float mx = S[0];
; #pragma unroll
;     for (int i = 1; i < 16; ++i) mx = fmaxf(mx, S[i]);
;     mx = xh_max(mx);
;     const float mxs = mx * SM_SCALE; const bool need = mxs > as.m + 8.f;
;     const float mnew = need ? mxs : as.m, muse = -fmaxf(mnew, -1e20f); float ps = 0.f;
; #pragma unroll
;     for (int i = 0; i < 16; ++i) { const float p = __builtin_amdgcn_exp2f(__builtin_fmaf(S[i], SM_SCALE, muse)); S[i] = p; ps += p; }
;     ps = xh_sum(ps);
;     if (__builtin_amdgcn_ballot_w64(need) != 0ull) {
;         const float alpha = __builtin_amdgcn_exp2f(as.m - mnew);
;         as.l *= alpha;
; #pragma unroll
;         for (int dt = 0; dt < 4; ++dt)
; #pragma unroll
;             for (int i = 0; i < 16; ++i) as.acc[dt][i] *= alpha;
;     }
.LBB0_548:
	s_andn2_b64 vcc, exec, s[36:37]
	s_cbranch_vccnz .LBB0_552
	s_add_i32 s88, s59, s74
	s_cmp_ge_i32 s88, 31
	s_cbranch_scc1 .Lfastf_sel
	v_add_u32_e32 v0, s74, v145
	v_cmp_lt_i32_e32 vcc, -1, v0
	s_and_b64 vcc, s[26:27], vcc
	s_nop 0
	v_cndmask_b32_e32 v2, v153, v16, vcc
	v_cmp_lt_i32_e32 vcc, 0, v0
	s_and_b64 vcc, s[26:27], vcc
	v_max_f32_e32 v174, v2, v2
	v_cndmask_b32_e32 v3, v153, v17, vcc
	v_cmp_lt_i32_e32 vcc, 1, v0
	s_and_b64 vcc, s[26:27], vcc
	s_nop 0
	v_cndmask_b32_e32 v4, v153, v18, vcc
	v_cmp_lt_i32_e32 vcc, 2, v0
	s_and_b64 vcc, s[26:27], vcc
	s_nop 0
	v_cndmask_b32_e32 v5, v153, v19, vcc
	v_cmp_lt_i32_e32 vcc, 7, v0
	s_and_b64 vcc, s[26:27], vcc
	s_nop 0
	v_cndmask_b32_e32 v6, v153, v20, vcc
	v_cmp_lt_i32_e32 vcc, 8, v0
	s_and_b64 vcc, s[26:27], vcc
	s_nop 0
	v_cndmask_b32_e32 v7, v153, v21, vcc
	v_cmp_lt_i32_e32 vcc, 9, v0
	s_and_b64 vcc, s[26:27], vcc
	s_nop 0
	v_cndmask_b32_e32 v8, v153, v22, vcc
	v_cmp_lt_i32_e32 vcc, 10, v0
	s_and_b64 vcc, s[26:27], vcc
	s_nop 0
	v_cndmask_b32_e32 v9, v153, v23, vcc
	v_cmp_lt_i32_e32 vcc, 15, v0
	s_and_b64 vcc, s[26:27], vcc
	s_nop 0
	v_cndmask_b32_e32 v10, v153, v24, vcc
	v_cmp_lt_i32_e32 vcc, 16, v0
	s_and_b64 vcc, s[26:27], vcc
	s_nop 0
	v_cndmask_b32_e32 v11, v153, v25, vcc
	v_cmp_lt_i32_e32 vcc, 17, v0
	s_and_b64 vcc, s[26:27], vcc
	s_nop 0
	v_cndmask_b32_e32 v12, v153, v26, vcc
	v_cmp_lt_i32_e32 vcc, 18, v0
	s_and_b64 vcc, s[26:27], vcc
	s_nop 0
	v_cndmask_b32_e32 v13, v153, v27, vcc
	v_cmp_lt_i32_e32 vcc, 23, v0
	s_and_b64 vcc, s[26:27], vcc
	s_nop 0
	v_cndmask_b32_e32 v14, v153, v28, vcc
	v_cmp_lt_i32_e32 vcc, 24, v0
	s_and_b64 vcc, s[26:27], vcc
	s_nop 0
	v_cndmask_b32_e32 v15, v153, v29, vcc
	v_cmp_lt_i32_e32 vcc, 25, v0
	s_and_b64 vcc, s[26:27], vcc
	s_nop 0
	v_cndmask_b32_e32 v176, v153, v30, vcc
	v_cmp_lt_i32_e32 vcc, 26, v0
	v_max_f32_e32 v0, v3, v3
	v_max_f32_e32 v0, v174, v0
	v_max3_f32 v0, v0, v4, v5
	v_max3_f32 v0, v0, v6, v7
	v_max3_f32 v0, v0, v8, v9
	v_max3_f32 v0, v0, v10, v11
	s_and_b64 vcc, s[26:27], vcc
	v_max3_f32 v0, v0, v12, v13
	v_cndmask_b32_e32 v177, v153, v31, vcc
	v_max3_f32 v0, v0, v14, v15
	v_max3_f32 v0, v0, v176, v177
	v_mov_b32_e32 v174, v0
	s_nop 1
	v_permlane32_swap_b32_e32 v0, v174
	v_max_f32_e32 v174, v174, v174
	v_max_f32_e32 v0, v0, v0
	v_max_f32_e32 v0, v0, v174
	v_mul_f32_e32 v0, 0x3e0293ee, v0
	v_add_f32_e32 v174, 0x41000000, v175
	v_cmp_gt_f32_e32 vcc, v0, v174
	s_nop 1
	v_cndmask_b32_e32 v174, v175, v0, vcc
	v_max_f32_e32 v0, v174, v174
	v_max_f32_e32 v178, 0xe0ad78ec, v0
	v_fma_f32 v0, v2, s52, -v178
	v_exp_f32_e32 v0, v0
	v_fma_f32 v2, v3, s52, -v178
	v_exp_f32_e32 v2, v2
	v_fma_f32 v3, v4, s52, -v178
	v_exp_f32_e32 v3, v3
	v_fma_f32 v4, v5, s52, -v178
	v_exp_f32_e32 v4, v4
	v_add_f32_e32 v5, 0, v0
	v_add_f32_e32 v5, v2, v5
	v_add_f32_e32 v5, v3, v5
	v_add_f32_e32 v179, v4, v5
	v_fma_f32 v5, v6, s52, -v178
	v_exp_f32_e32 v5, v5
	v_fma_f32 v6, v7, s52, -v178
	v_exp_f32_e32 v6, v6
	v_fma_f32 v7, v8, s52, -v178
	v_exp_f32_e32 v7, v7
	v_fma_f32 v8, v9, s52, -v178
	v_exp_f32_e32 v8, v8
	v_add_f32_e32 v9, v5, v179
	v_add_f32_e32 v9, v6, v9
	v_add_f32_e32 v9, v7, v9
	v_add_f32_e32 v179, v8, v9
	v_fma_f32 v9, v10, s52, -v178
	v_exp_f32_e32 v9, v9
	v_fma_f32 v10, v11, s52, -v178
	v_exp_f32_e32 v10, v10
	v_fma_f32 v11, v12, s52, -v178
	v_exp_f32_e32 v11, v11
	v_fma_f32 v12, v13, s52, -v178
	v_exp_f32_e32 v12, v12
	v_add_f32_e32 v13, v9, v179
	v_add_f32_e32 v13, v10, v13
	v_add_f32_e32 v13, v11, v13
	v_add_f32_e32 v179, v12, v13
	v_fma_f32 v13, v14, s52, -v178
	v_exp_f32_e32 v13, v13
	v_fma_f32 v14, v15, s52, -v178
	v_exp_f32_e32 v14, v14
	v_fma_f32 v15, v176, s52, -v178
	v_exp_f32_e32 v15, v15
	v_fma_f32 v176, v177, s52, -v178
	v_exp_f32_e32 v176, v176
	v_add_f32_e32 v177, v13, v179
	v_add_f32_e32 v177, v14, v177
	v_add_f32_e32 v177, v15, v177
	v_add_f32_e32 v177, v176, v177
	v_mov_b32_e32 v178, v177
	s_nop 1
	v_permlane32_swap_b32_e32 v177, v178
	s_cbranch_vccz .LBB0_551
	v_sub_f32_e32 v175, v175, v174
	v_exp_f32_e32 v180, v175
	s_nop 0
	v_mul_f32_e32 v163, v163, v180
	v_mul_f32_e32 v94, v94, v180
	v_mul_f32_e32 v95, v95, v180
	v_mul_f32_e32 v92, v92, v180
	v_mul_f32_e32 v93, v93, v180
	v_mul_f32_e32 v90, v90, v180
	v_mul_f32_e32 v91, v91, v180
	v_mul_f32_e32 v88, v88, v180
	v_mul_f32_e32 v89, v89, v180
	v_mul_f32_e32 v86, v86, v180
	v_mul_f32_e32 v87, v87, v180
	v_mul_f32_e32 v84, v84, v180
	v_mul_f32_e32 v85, v85, v180
	v_mul_f32_e32 v82, v82, v180
	v_mul_f32_e32 v83, v83, v180
	v_mul_f32_e32 v80, v80, v180
	v_mul_f32_e32 v81, v81, v180
	v_mul_f32_e32 v78, v78, v180
	v_mul_f32_e32 v79, v79, v180
	v_mul_f32_e32 v76, v76, v180
	v_mul_f32_e32 v77, v77, v180
	v_mul_f32_e32 v74, v74, v180
	v_mul_f32_e32 v75, v75, v180
	v_mul_f32_e32 v72, v72, v180
	v_mul_f32_e32 v73, v73, v180
	v_mul_f32_e32 v70, v70, v180
	v_mul_f32_e32 v71, v71, v180
	v_mul_f32_e32 v68, v68, v180
	v_mul_f32_e32 v69, v69, v180
	v_mul_f32_e32 v66, v66, v180
	v_mul_f32_e32 v67, v67, v180
	v_mul_f32_e32 v64, v64, v180
	v_mul_f32_e32 v65, v65, v180
	v_mul_f32_e32 v62, v62, v180
	v_mul_f32_e32 v63, v63, v180
	v_mul_f32_e32 v60, v60, v180
	v_mul_f32_e32 v61, v61, v180
	v_mul_f32_e32 v58, v58, v180
	v_mul_f32_e32 v59, v59, v180
	v_mul_f32_e32 v56, v56, v180
	v_mul_f32_e32 v57, v57, v180
	v_mul_f32_e32 v54, v54, v180
	v_mul_f32_e32 v55, v55, v180
	v_mul_f32_e32 v52, v52, v180
	v_mul_f32_e32 v53, v53, v180
	v_mul_f32_e32 v50, v50, v180
	v_mul_f32_e32 v51, v51, v180
	v_mul_f32_e32 v48, v48, v180
	v_mul_f32_e32 v49, v49, v180
	v_mul_f32_e32 v46, v46, v180
	v_mul_f32_e32 v47, v47, v180
	v_mul_f32_e32 v44, v44, v180
	v_mul_f32_e32 v45, v45, v180
	v_mul_f32_e32 v42, v42, v180
	v_mul_f32_e32 v43, v43, v180
	v_mul_f32_e32 v40, v40, v180
	v_mul_f32_e32 v41, v41, v180
	v_mul_f32_e32 v38, v38, v180
	v_mul_f32_e32 v39, v39, v180
	v_mul_f32_e32 v36, v36, v180
	v_mul_f32_e32 v37, v37, v180
	v_mul_f32_e32 v34, v34, v180
	v_mul_f32_e32 v35, v35, v180
	v_mul_f32_e32 v32, v32, v180
	v_mul_f32_e32 v33, v33, v180

; #define LAS __attribute__((address_space(3)))
; DI float xh_max(float x) { const unsigned u = __float_as_uint(x); const auto r = __builtin_amdgcn_permlane32_swap(u, u, false, false); return fmaxf(__uint_as_float(r[0]), __uint_as_float(r[1])); }
; DI float xh_sum(float x) { const unsigned u = __float_as_uint(x); const auto r = __builtin_amdgcn_permlane32_swap(u, u, false, false); return __uint_as_float(r[0]) + __uint_as_float(r[1]); }
; template <int MODE>
; DI void co_finish(f32x16 S, LAS unsigned char* st, int key_base, AttnState& as, int tq, bool rowsel, int vb_in, int hh) {
;     const int vb = vb_in;
;     {
;         const int base = key_base + 4 * hh;
;         const int hi = (MODE == 0) ? (((tq - 31) >> 4) - base) : (tq - base);
;         const int lo = hi - 512;
; #pragma unroll
;         for (int i = 0; i < 16; ++i) { const int c = (i & 3) + 8 * (i >> 2); bool ok = (c <= hi); if (MODE == 2) ok = ok && (c > lo); if (MODE == 1) ok = ok && rowsel; S[i] = ok ? S[i] : -1e30f; }
;     }
;     float mx = S[0];
; #pragma unroll
;     for (int i = 1; i < 16; ++i) mx = fmaxf(mx, S[i]);
;     mx = xh_max(mx);
;     const float mxs = mx * SM_SCALE; const bool need = mxs > as.m + 8.f;
;     const float mnew = need ? mxs : as.m, muse = -fmaxf(mnew, -1e20f); float ps = 0.f;
; #pragma unroll
;     for (int i = 0; i < 16; ++i) { const float p = __builtin_amdgcn_exp2f(__builtin_fmaf(S[i], SM_SCALE, muse)); S[i] = p; ps += p; }
;     ps = xh_sum(ps);
;     if (__builtin_amdgcn_ballot_w64(need) != 0ull) {
;         const float alpha = __builtin_amdgcn_exp2f(as.m - mnew);
;         as.l *= alpha;
; #pragma unroll
;         for (int dt = 0; dt < 4; ++dt)
; #pragma unroll
;             for (int i = 0; i < 16; ++i) as.acc[dt][i] *= alpha;
;     }
.LBB0_560:
	v_add_u32_e32 v0, s74, v145
	v_cmp_lt_i32_e32 vcc, -1, v0
	s_and_b64 vcc, s[26:27], vcc
	s_nop 0
	v_cndmask_b32_e32 v2, v153, v16, vcc
	v_cmp_lt_i32_e32 vcc, 0, v0
	s_and_b64 vcc, s[26:27], vcc
	s_nop 0
	v_cndmask_b32_e32 v3, v153, v17, vcc
	v_cmp_lt_i32_e32 vcc, 1, v0
	s_and_b64 vcc, s[26:27], vcc
	s_nop 0
	v_cndmask_b32_e32 v4, v153, v18, vcc
	v_cmp_lt_i32_e32 vcc, 2, v0
	s_and_b64 vcc, s[26:27], vcc
	v_max_f32_e32 v18, v2, v2
	v_cndmask_b32_e32 v5, v153, v19, vcc
	v_cmp_lt_i32_e32 vcc, 7, v0
	s_and_b64 vcc, s[26:27], vcc
	s_nop 0
	v_cndmask_b32_e32 v6, v153, v20, vcc
	v_cmp_lt_i32_e32 vcc, 8, v0
	s_and_b64 vcc, s[26:27], vcc
	s_nop 0
	v_cndmask_b32_e32 v7, v153, v21, vcc
	v_cmp_lt_i32_e32 vcc, 9, v0
	s_and_b64 vcc, s[26:27], vcc
	s_nop 0
	v_cndmask_b32_e32 v8, v153, v22, vcc
	v_cmp_lt_i32_e32 vcc, 10, v0
	s_and_b64 vcc, s[26:27], vcc
	s_nop 0
	v_cndmask_b32_e32 v9, v153, v23, vcc
	v_cmp_lt_i32_e32 vcc, 15, v0
	s_and_b64 vcc, s[26:27], vcc
	s_nop 0
	v_cndmask_b32_e32 v10, v153, v24, vcc
	v_cmp_lt_i32_e32 vcc, 16, v0
	s_and_b64 vcc, s[26:27], vcc
	s_nop 0
	v_cndmask_b32_e32 v11, v153, v25, vcc
	v_cmp_lt_i32_e32 vcc, 17, v0
	s_and_b64 vcc, s[26:27], vcc
	s_nop 0
	v_cndmask_b32_e32 v12, v153, v26, vcc
	v_cmp_lt_i32_e32 vcc, 18, v0
	s_and_b64 vcc, s[26:27], vcc
	s_nop 0
	v_cndmask_b32_e32 v13, v153, v27, vcc
	v_cmp_lt_i32_e32 vcc, 23, v0
	s_and_b64 vcc, s[26:27], vcc
	s_nop 0
	v_cndmask_b32_e32 v14, v153, v28, vcc
	v_cmp_lt_i32_e32 vcc, 24, v0
	s_and_b64 vcc, s[26:27], vcc
	s_nop 0
	v_cndmask_b32_e32 v15, v153, v29, vcc
	v_cmp_lt_i32_e32 vcc, 25, v0
	s_and_b64 vcc, s[26:27], vcc
	s_nop 0
	v_cndmask_b32_e32 v16, v153, v30, vcc
	v_cmp_lt_i32_e32 vcc, 26, v0
	v_max_f32_e32 v0, v3, v3
	v_max_f32_e32 v0, v18, v0
	v_max3_f32 v0, v0, v4, v5
	v_max3_f32 v0, v0, v6, v7
	v_max3_f32 v0, v0, v8, v9
	v_max3_f32 v0, v0, v10, v11
	s_and_b64 vcc, s[26:27], vcc
	v_max3_f32 v0, v0, v12, v13
	v_cndmask_b32_e32 v17, v153, v31, vcc
	v_max3_f32 v0, v0, v14, v15
	v_max3_f32 v0, v0, v16, v17
	v_mov_b32_e32 v18, v0
	s_nop 1
	v_permlane32_swap_b32_e32 v0, v18
	v_max_f32_e32 v18, v18, v18
	v_max_f32_e32 v0, v0, v0
	v_max_f32_e32 v0, v0, v18
	v_mul_f32_e32 v0, 0x3e0293ee, v0
	v_add_f32_e32 v18, 0x41000000, v174
	v_cmp_gt_f32_e32 vcc, v0, v18
	s_nop 1
	v_cndmask_b32_e32 v19, v174, v0, vcc
	v_max_f32_e32 v0, v19, v19
	v_max_f32_e32 v18, 0xe0ad78ec, v0
	v_fma_f32 v0, v2, s52, -v18
	v_exp_f32_e32 v0, v0
	v_fma_f32 v2, v3, s52, -v18
	v_exp_f32_e32 v2, v2
	v_fma_f32 v3, v4, s52, -v18
	v_exp_f32_e32 v3, v3
	v_fma_f32 v4, v5, s52, -v18
	v_exp_f32_e32 v4, v4
	v_add_f32_e32 v5, 0, v0
	v_add_f32_e32 v5, v2, v5
	v_add_f32_e32 v5, v3, v5
	v_add_f32_e32 v20, v4, v5
	v_fma_f32 v5, v6, s52, -v18
	v_exp_f32_e32 v5, v5
	v_fma_f32 v6, v7, s52, -v18
	v_exp_f32_e32 v6, v6
	v_fma_f32 v7, v8, s52, -v18
	v_exp_f32_e32 v7, v7
	v_fma_f32 v8, v9, s52, -v18
	v_exp_f32_e32 v8, v8
	v_add_f32_e32 v9, v5, v20
	v_add_f32_e32 v9, v6, v9
	v_add_f32_e32 v9, v7, v9
	v_add_f32_e32 v20, v8, v9
	v_fma_f32 v9, v10, s52, -v18
	v_exp_f32_e32 v9, v9
	v_fma_f32 v10, v11, s52, -v18
	v_exp_f32_e32 v10, v10
	v_fma_f32 v11, v12, s52, -v18
	v_exp_f32_e32 v11, v11
	v_fma_f32 v12, v13, s52, -v18
	v_exp_f32_e32 v12, v12
	v_add_f32_e32 v13, v9, v20
	v_add_f32_e32 v13, v10, v13
	v_add_f32_e32 v13, v11, v13
	v_add_f32_e32 v20, v12, v13
	v_fma_f32 v13, v14, s52, -v18
	v_exp_f32_e32 v13, v13
	v_fma_f32 v14, v15, s52, -v18
	v_exp_f32_e32 v14, v14
	v_fma_f32 v15, v16, s52, -v18
	v_exp_f32_e32 v15, v15
	v_fma_f32 v16, v17, s52, -v18
	v_exp_f32_e32 v16, v16
	v_add_f32_e32 v17, v13, v20
	v_add_f32_e32 v17, v14, v17
	v_add_f32_e32 v17, v15, v17
	v_add_f32_e32 v17, v16, v17
	v_mov_b32_e32 v18, v17
	s_nop 1
	v_permlane32_swap_b32_e32 v17, v18
	s_cbranch_vccz .LBB0_378
	v_sub_f32_e32 v19, v174, v19
	v_exp_f32_e32 v20, v19
	s_nop 0
	v_mul_f32_e32 v163, v163, v20
	v_mul_f32_e32 v94, v94, v20
	v_mul_f32_e32 v95, v95, v20
	v_mul_f32_e32 v92, v92, v20
	v_mul_f32_e32 v93, v93, v20
	v_mul_f32_e32 v90, v90, v20
	v_mul_f32_e32 v91, v91, v20
	v_mul_f32_e32 v88, v88, v20
	v_mul_f32_e32 v89, v89, v20
	v_mul_f32_e32 v86, v86, v20
	v_mul_f32_e32 v87, v87, v20
	v_mul_f32_e32 v84, v84, v20
	v_mul_f32_e32 v85, v85, v20
	v_mul_f32_e32 v82, v82, v20
	v_mul_f32_e32 v83, v83, v20
	v_mul_f32_e32 v80, v80, v20
	v_mul_f32_e32 v81, v81, v20
	v_mul_f32_e32 v78, v78, v20
	v_mul_f32_e32 v79, v79, v20
	v_mul_f32_e32 v76, v76, v20
	v_mul_f32_e32 v77, v77, v20
	v_mul_f32_e32 v74, v74, v20
	v_mul_f32_e32 v75, v75, v20
	v_mul_f32_e32 v72, v72, v20
	v_mul_f32_e32 v73, v73, v20
	v_mul_f32_e32 v70, v70, v20
	v_mul_f32_e32 v71, v71, v20
	v_mul_f32_e32 v68, v68, v20
	v_mul_f32_e32 v69, v69, v20
	v_mul_f32_e32 v66, v66, v20
	v_mul_f32_e32 v67, v67, v20
	v_mul_f32_e32 v64, v64, v20
	v_mul_f32_e32 v65, v65, v20
	v_mul_f32_e32 v62, v62, v20
	v_mul_f32_e32 v63, v63, v20
	v_mul_f32_e32 v60, v60, v20
	v_mul_f32_e32 v61, v61, v20
	v_mul_f32_e32 v58, v58, v20
	v_mul_f32_e32 v59, v59, v20
	v_mul_f32_e32 v56, v56, v20
	v_mul_f32_e32 v57, v57, v20
	v_mul_f32_e32 v54, v54, v20
	v_mul_f32_e32 v55, v55, v20
	v_mul_f32_e32 v52, v52, v20
	v_mul_f32_e32 v53, v53, v20
	v_mul_f32_e32 v50, v50, v20
	v_mul_f32_e32 v51, v51, v20
	v_mul_f32_e32 v48, v48, v20
	v_mul_f32_e32 v49, v49, v20
	v_mul_f32_e32 v46, v46, v20
	v_mul_f32_e32 v47, v47, v20
	v_mul_f32_e32 v44, v44, v20
	v_mul_f32_e32 v45, v45, v20
	v_mul_f32_e32 v42, v42, v20
	v_mul_f32_e32 v43, v43, v20
	v_mul_f32_e32 v40, v40, v20
	v_mul_f32_e32 v41, v41, v20
	v_mul_f32_e32 v38, v38, v20
	v_mul_f32_e32 v39, v39, v20
	v_mul_f32_e32 v36, v36, v20
	v_mul_f32_e32 v37, v37, v20
	v_mul_f32_e32 v34, v34, v20
	v_mul_f32_e32 v35, v35, v20
	v_mul_f32_e32 v32, v32, v20
	v_mul_f32_e32 v33, v33, v20
	s_branch .LBB0_378
; #define LAS __attribute__((address_space(3)))
; DI float xh_max(float x) { const unsigned u = __float_as_uint(x); const auto r = __builtin_amdgcn_permlane32_swap(u, u, false, false); return fmaxf(__uint_as_float(r[0]), __uint_as_float(r[1])); }
; DI float xh_sum(float x) { const unsigned u = __float_as_uint(x); const auto r = __builtin_amdgcn_permlane32_swap(u, u, false, false); return __uint_as_float(r[0]) + __uint_as_float(r[1]); }
; #define MFMA32(a, b, c) __builtin_amdgcn_mfma_f32_32x32x16_bf16((a), (b), (c), 0, 0, 0)
; DI f32x16 co_qk1(LAS unsigned char* st, const bf16x8 (&qf)[8], int ka_in) {
;     const int ka = ka_in;
;     f32x16 S;
; #pragma unroll
;     for (int i = 0; i < 16; ++i) S[i] = 0.f;
;     __builtin_amdgcn_s_setprio(1);
; #pragma unroll
;     for (int ks = 0; ks < 8; ++ks) { const bf16x8 a = *(const LAS bf16x8*)(st + (ka ^ (32 * ks))); S = MFMA32(a, qf[ks], S); }
;     __builtin_amdgcn_s_setprio(0);
;     return S;
; }
; template <int MODE>
; DI void co_finish(f32x16 S, LAS unsigned char* st, int key_base, AttnState& as, int tq, bool rowsel, int vb_in, int hh) {
;     const int vb = vb_in;
;     {
;         const int base = key_base + 4 * hh;
;         const int hi = (MODE == 0) ? (((tq - 31) >> 4) - base) : (tq - base);
;         const int lo = hi - 512;
; #pragma unroll
;         for (int i = 0; i < 16; ++i) { const int c = (i & 3) + 8 * (i >> 2); bool ok = (c <= hi); if (MODE == 2) ok = ok && (c > lo); if (MODE == 1) ok = ok && rowsel; S[i] = ok ? S[i] : -1e30f; }
;     }
;     float mx = S[0];
; #pragma unroll
;     for (int i = 1; i < 16; ++i) mx = fmaxf(mx, S[i]);
;     mx = xh_max(mx);
;     const float mxs = mx * SM_SCALE; const bool need = mxs > as.m + 8.f;
;     const float mnew = need ? mxs : as.m, muse = -fmaxf(mnew, -1e20f); float ps = 0.f;
; #pragma unroll
;     for (int i = 0; i < 16; ++i) { const float p = __builtin_amdgcn_exp2f(__builtin_fmaf(S[i], SM_SCALE, muse)); S[i] = p; ps += p; }
;     ps = xh_sum(ps);
.Lfs_sel:
	v_add_u32_e32 v246, s40, v162
	ds_read_b128 v[238:241], v246
	v_add_u32_e32 v246, s40, v164
	ds_read_b128 v[242:245], v246
	v_add_u32_e32 v0, s74, v145
	v_cmp_lt_i32_e32 vcc, -1, v0
	s_and_b64 vcc, s[26:27], vcc
	s_nop 0
	v_cndmask_b32_e32 v2, v153, v16, vcc
	v_cmp_lt_i32_e32 vcc, 0, v0
	s_and_b64 vcc, s[26:27], vcc
	v_max_f32_e32 v174, v2, v2
	v_cndmask_b32_e32 v3, v153, v17, vcc
	v_cmp_lt_i32_e32 vcc, 1, v0
	s_and_b64 vcc, s[26:27], vcc
	s_nop 0
	v_cndmask_b32_e32 v4, v153, v18, vcc
	s_waitcnt lgkmcnt(1)
	v_mfma_f32_32x32x16_bf16 v[96:111], v[238:241], v[112:115], 0
	v_add_u32_e32 v246, s40, v165
	ds_read_b128 v[238:241], v246
	v_cmp_lt_i32_e32 vcc, 2, v0
	s_and_b64 vcc, s[26:27], vcc
	s_nop 0
	v_cndmask_b32_e32 v5, v153, v19, vcc
	v_cmp_lt_i32_e32 vcc, 7, v0
	s_and_b64 vcc, s[26:27], vcc
	s_nop 0
	v_cndmask_b32_e32 v6, v153, v20, vcc
	v_cmp_lt_i32_e32 vcc, 8, v0
	s_and_b64 vcc, s[26:27], vcc
	s_nop 0
	v_cndmask_b32_e32 v7, v153, v21, vcc
	v_cmp_lt_i32_e32 vcc, 9, v0
	s_and_b64 vcc, s[26:27], vcc
	s_waitcnt lgkmcnt(1)
	v_mfma_f32_32x32x16_bf16 v[96:111], v[242:245], v[116:119], v[96:111]
	v_add_u32_e32 v246, s40, v166
	ds_read_b128 v[242:245], v246
	s_nop 0
	v_cndmask_b32_e32 v8, v153, v22, vcc
	v_cmp_lt_i32_e32 vcc, 10, v0
	s_and_b64 vcc, s[26:27], vcc
	s_nop 0
	v_cndmask_b32_e32 v9, v153, v23, vcc
	v_cmp_lt_i32_e32 vcc, 15, v0
	s_and_b64 vcc, s[26:27], vcc
	s_nop 0
	v_cndmask_b32_e32 v10, v153, v24, vcc
	v_cmp_lt_i32_e32 vcc, 16, v0
	s_and_b64 vcc, s[26:27], vcc
	s_nop 0
	v_cndmask_b32_e32 v11, v153, v25, vcc
	s_waitcnt lgkmcnt(1)
	v_mfma_f32_32x32x16_bf16 v[96:111], v[238:241], v[120:123], v[96:111]
	v_add_u32_e32 v246, s40, v167
	ds_read_b128 v[238:241], v246
	v_cmp_lt_i32_e32 vcc, 17, v0
	s_and_b64 vcc, s[26:27], vcc
	s_nop 0
	v_cndmask_b32_e32 v12, v153, v26, vcc
	v_cmp_lt_i32_e32 vcc, 18, v0
	s_and_b64 vcc, s[26:27], vcc
	s_nop 0
	v_cndmask_b32_e32 v13, v153, v27, vcc
	v_cmp_lt_i32_e32 vcc, 23, v0
	s_and_b64 vcc, s[26:27], vcc
	s_nop 0
	v_cndmask_b32_e32 v14, v153, v28, vcc
	v_cmp_lt_i32_e32 vcc, 24, v0
	s_waitcnt lgkmcnt(1)
	v_mfma_f32_32x32x16_bf16 v[96:111], v[242:245], v[124:127], v[96:111]
	v_add_u32_e32 v246, s40, v168
	ds_read_b128 v[242:245], v246
	s_and_b64 vcc, s[26:27], vcc
	s_nop 0
	v_cndmask_b32_e32 v15, v153, v29, vcc
	v_cmp_lt_i32_e32 vcc, 25, v0
	s_and_b64 vcc, s[26:27], vcc
	s_nop 0
	v_cndmask_b32_e32 v176, v153, v30, vcc
	v_cmp_lt_i32_e32 vcc, 26, v0
	v_max_f32_e32 v0, v3, v3
	v_max_f32_e32 v0, v174, v0
	v_max3_f32 v0, v0, v4, v5
	v_max3_f32 v0, v0, v6, v7
	v_max3_f32 v0, v0, v8, v9
	v_max3_f32 v0, v0, v10, v11
	s_waitcnt lgkmcnt(1)
	v_mfma_f32_32x32x16_bf16 v[96:111], v[238:241], v[128:131], v[96:111]
	v_add_u32_e32 v246, s40, v169
	ds_read_b128 v[238:241], v246
	s_and_b64 vcc, s[26:27], vcc
	v_max3_f32 v0, v0, v12, v13
	v_cndmask_b32_e32 v177, v153, v31, vcc
	v_max3_f32 v0, v0, v14, v15
	v_max3_f32 v0, v0, v176, v177
	v_mov_b32_e32 v174, v0
	s_nop 1
	v_permlane32_swap_b32_e32 v0, v174
	v_max_f32_e32 v174, v174, v174
	v_max_f32_e32 v0, v0, v0
	v_max_f32_e32 v0, v0, v174
	v_mul_f32_e32 v0, 0x3e0293ee, v0
	v_add_f32_e32 v174, 0x41000000, v175
	v_cmp_gt_f32_e32 vcc, v0, v174
	s_waitcnt lgkmcnt(1)
	v_mfma_f32_32x32x16_bf16 v[96:111], v[242:245], v[132:135], v[96:111]
	v_add_u32_e32 v246, s40, v170
	ds_read_b128 v[242:245], v246
	s_nop 1
	v_cndmask_b32_e32 v174, v175, v0, vcc
	v_max_f32_e32 v0, v174, v174
	v_max_f32_e32 v178, 0xe0ad78ec, v0
	v_fma_f32 v0, v2, s52, -v178
	v_exp_f32_e32 v0, v0
	v_fma_f32 v2, v3, s52, -v178
	v_exp_f32_e32 v2, v2
	v_fma_f32 v3, v4, s52, -v178
	v_exp_f32_e32 v3, v3
	v_fma_f32 v4, v5, s52, -v178
	v_exp_f32_e32 v4, v4
	v_add_f32_e32 v5, 0, v0
	s_waitcnt lgkmcnt(1)
	v_mfma_f32_32x32x16_bf16 v[96:111], v[238:241], v[136:139], v[96:111]
	v_add_f32_e32 v5, v2, v5
	v_add_f32_e32 v5, v3, v5
	v_add_f32_e32 v179, v4, v5
	v_fma_f32 v5, v6, s52, -v178
	v_exp_f32_e32 v5, v5
	v_fma_f32 v6, v7, s52, -v178
	v_exp_f32_e32 v6, v6
	v_fma_f32 v7, v8, s52, -v178
	v_exp_f32_e32 v7, v7
	v_fma_f32 v8, v9, s52, -v178
	v_exp_f32_e32 v8, v8
	v_add_f32_e32 v9, v5, v179
	v_add_f32_e32 v9, v6, v9
	v_add_f32_e32 v9, v7, v9
	s_waitcnt lgkmcnt(0)
	v_mfma_f32_32x32x16_bf16 v[96:111], v[242:245], v[140:143], v[96:111]
	v_add_f32_e32 v179, v8, v9
	v_fma_f32 v9, v10, s52, -v178
	v_exp_f32_e32 v9, v9
	v_fma_f32 v10, v11, s52, -v178
	v_exp_f32_e32 v10, v10
	v_fma_f32 v11, v12, s52, -v178
	v_exp_f32_e32 v11, v11
	v_fma_f32 v12, v13, s52, -v178
	v_exp_f32_e32 v12, v12
	v_add_f32_e32 v13, v9, v179
	v_add_f32_e32 v13, v10, v13
	v_add_f32_e32 v13, v11, v13
	v_add_f32_e32 v179, v12, v13
	v_fma_f32 v13, v14, s52, -v178
	v_exp_f32_e32 v13, v13
	v_fma_f32 v14, v15, s52, -v178
	v_exp_f32_e32 v14, v14
	v_fma_f32 v15, v176, s52, -v178
	v_exp_f32_e32 v15, v15
	v_fma_f32 v176, v177, s52, -v178
	v_exp_f32_e32 v176, v176
	v_add_f32_e32 v177, v13, v179
	v_add_f32_e32 v177, v14, v177
	v_add_f32_e32 v177, v15, v177
	v_add_f32_e32 v177, v176, v177
	v_mov_b32_e32 v178, v177
	s_nop 1
	v_permlane32_swap_b32_e32 v177, v178
	s_cbranch_vccz .Lfs_sel_551
; template <int MODE>
; DI void co_finish(f32x16 S, LAS unsigned char* st, int key_base, AttnState& as, int tq, bool rowsel, int vb_in, int hh) {
;     ...
;     if (__builtin_amdgcn_ballot_w64(need) != 0ull) {
;         const float alpha = __builtin_amdgcn_exp2f(as.m - mnew);
;         as.l *= alpha;
; #pragma unroll
;         for (int dt = 0; dt < 4; ++dt)
; #pragma unroll
;             for (int i = 0; i < 16; ++i) as.acc[dt][i] *= alpha;
;     }
	v_sub_f32_e32 v175, v175, v174
	v_exp_f32_e32 v180, v175
	s_nop 0
	v_mul_f32_e32 v163, v163, v180
	v_mul_f32_e32 v94, v94, v180
	v_mul_f32_e32 v95, v95, v180
	v_mul_f32_e32 v92, v92, v180
	v_mul_f32_e32 v93, v93, v180
	v_mul_f32_e32 v90, v90, v180
	v_mul_f32_e32 v91, v91, v180
	v_mul_f32_e32 v88, v88, v180
	v_mul_f32_e32 v89, v89, v180
	v_mul_f32_e32 v86, v86, v180
	v_mul_f32_e32 v87, v87, v180
	v_mul_f32_e32 v84, v84, v180
	v_mul_f32_e32 v85, v85, v180
	v_mul_f32_e32 v82, v82, v180
	v_mul_f32_e32 v83, v83, v180
	v_mul_f32_e32 v80, v80, v180
	v_mul_f32_e32 v81, v81, v180
	v_mul_f32_e32 v78, v78, v180
	v_mul_f32_e32 v79, v79, v180
	v_mul_f32_e32 v76, v76, v180
	v_mul_f32_e32 v77, v77, v180
	v_mul_f32_e32 v74, v74, v180
	v_mul_f32_e32 v75, v75, v180
	v_mul_f32_e32 v72, v72, v180
	v_mul_f32_e32 v73, v73, v180
	v_mul_f32_e32 v70, v70, v180
	v_mul_f32_e32 v71, v71, v180
	v_mul_f32_e32 v68, v68, v180
	v_mul_f32_e32 v69, v69, v180
	v_mul_f32_e32 v66, v66, v180
	v_mul_f32_e32 v67, v67, v180
	v_mul_f32_e32 v64, v64, v180
	v_mul_f32_e32 v65, v65, v180
	v_mul_f32_e32 v62, v62, v180
	v_mul_f32_e32 v63, v63, v180
	v_mul_f32_e32 v60, v60, v180
	v_mul_f32_e32 v61, v61, v180
	v_mul_f32_e32 v58, v58, v180
	v_mul_f32_e32 v59, v59, v180
	v_mul_f32_e32 v56, v56, v180
	v_mul_f32_e32 v57, v57, v180
	v_mul_f32_e32 v54, v54, v180
	v_mul_f32_e32 v55, v55, v180
	v_mul_f32_e32 v52, v52, v180
	v_mul_f32_e32 v53, v53, v180
	v_mul_f32_e32 v50, v50, v180
	v_mul_f32_e32 v51, v51, v180
	v_mul_f32_e32 v48, v48, v180
	v_mul_f32_e32 v49, v49, v180
	v_mul_f32_e32 v46, v46, v180
	v_mul_f32_e32 v47, v47, v180
	v_mul_f32_e32 v44, v44, v180
	v_mul_f32_e32 v45, v45, v180
	v_mul_f32_e32 v42, v42, v180
	v_mul_f32_e32 v43, v43, v180
	v_mul_f32_e32 v40, v40, v180
	v_mul_f32_e32 v41, v41, v180
	v_mul_f32_e32 v38, v38, v180
	v_mul_f32_e32 v39, v39, v180
	v_mul_f32_e32 v36, v36, v180
	v_mul_f32_e32 v37, v37, v180
	v_mul_f32_e32 v34, v34, v180
	v_mul_f32_e32 v35, v35, v180
	v_mul_f32_e32 v32, v32, v180
	v_mul_f32_e32 v33, v33, v180

; #define LAS __attribute__((address_space(3)))
; DI float xh_max(float x) { const unsigned u = __float_as_uint(x); const auto r = __builtin_amdgcn_permlane32_swap(u, u, false, false); return fmaxf(__uint_as_float(r[0]), __uint_as_float(r[1])); }
; DI float xh_sum(float x) { const unsigned u = __float_as_uint(x); const auto r = __builtin_amdgcn_permlane32_swap(u, u, false, false); return __uint_as_float(r[0]) + __uint_as_float(r[1]); }
; #define MFMA32(a, b, c) __builtin_amdgcn_mfma_f32_32x32x16_bf16((a), (b), (c), 0, 0, 0)
; DI f32x16 co_qk1(LAS unsigned char* st, const bf16x8 (&qf)[8], int ka_in) {
;     const int ka = ka_in;
;     f32x16 S;
; #pragma unroll
;     for (int i = 0; i < 16; ++i) S[i] = 0.f;
;     __builtin_amdgcn_s_setprio(1);
; #pragma unroll
;     for (int ks = 0; ks < 8; ++ks) { const bf16x8 a = *(const LAS bf16x8*)(st + (ka ^ (32 * ks))); S = MFMA32(a, qf[ks], S); }
;     __builtin_amdgcn_s_setprio(0);
;     return S;
; }
; template <int MODE>
; DI void co_finish(f32x16 S, LAS unsigned char* st, int key_base, AttnState& as, int tq, bool rowsel, int vb_in, int hh) {
;     const int vb = vb_in;
;     {
;         const int base = key_base + 4 * hh;
;         const int hi = (MODE == 0) ? (((tq - 31) >> 4) - base) : (tq - base);
;         const int lo = hi - 512;
; #pragma unroll
;         for (int i = 0; i < 16; ++i) { const int c = (i & 3) + 8 * (i >> 2); bool ok = (c <= hi); if (MODE == 2) ok = ok && (c > lo); if (MODE == 1) ok = ok && rowsel; S[i] = ok ? S[i] : -1e30f; }
;     }
;     float mx = S[0];
; #pragma unroll
;     for (int i = 1; i < 16; ++i) mx = fmaxf(mx, S[i]);
;     mx = xh_max(mx);
;     const float mxs = mx * SM_SCALE; const bool need = mxs > as.m + 8.f;
;     const float mnew = need ? mxs : as.m, muse = -fmaxf(mnew, -1e20f); float ps = 0.f;
; #pragma unroll
;     for (int i = 0; i < 16; ++i) { const float p = __builtin_amdgcn_exp2f(__builtin_fmaf(S[i], SM_SCALE, muse)); S[i] = p; ps += p; }
;     ps = xh_sum(ps);
;     if (__builtin_amdgcn_ballot_w64(need) != 0ull) {
;         const float alpha = __builtin_amdgcn_exp2f(as.m - mnew);
;         as.l *= alpha;
; #pragma unroll
;         for (int dt = 0; dt < 4; ++dt)
; #pragma unroll
;             for (int i = 0; i < 16; ++i) as.acc[dt][i] *= alpha;
;     }
.Lfs_win:
	v_add_u32_e32 v246, s16, v162
	ds_read_b128 v[238:241], v246
	v_add_u32_e32 v246, s16, v164
	ds_read_b128 v[242:245], v246
	v_add_u32_e32 v0, s79, v145
	v_cmp_gt_u32_e32 vcc, s53, v0
	v_add_u32_e32 v3, -1, v0
	v_add_u32_e32 v4, -2, v0
	v_cndmask_b32_e32 v2, v153, v16, vcc
	v_cmp_gt_u32_e32 vcc, s53, v3
	v_add_u32_e32 v5, -3, v0
	v_add_u32_e32 v6, -8, v0
	v_cndmask_b32_e32 v3, v153, v17, vcc
	v_cmp_gt_u32_e32 vcc, s53, v4
	v_add_u32_e32 v7, -9, v0
	v_add_u32_e32 v8, -10, v0
	v_cndmask_b32_e32 v4, v153, v18, vcc
	s_waitcnt lgkmcnt(1)
	v_mfma_f32_32x32x16_bf16 v[96:111], v[238:241], v[112:115], 0
	v_add_u32_e32 v246, s16, v165
	ds_read_b128 v[238:241], v246
	v_cmp_gt_u32_e32 vcc, s53, v5
	v_add_u32_e32 v9, -11, v0
	v_add_u32_e32 v10, -16, v0
	v_cndmask_b32_e32 v5, v153, v19, vcc
	v_cmp_gt_u32_e32 vcc, s53, v6
	v_subrev_u32_e32 v11, 17, v0
	v_subrev_u32_e32 v12, 18, v0
	v_cndmask_b32_e32 v6, v153, v20, vcc
	v_cmp_gt_u32_e32 vcc, s53, v7
	v_subrev_u32_e32 v13, 19, v0
	v_subrev_u32_e32 v14, 24, v0
	v_cndmask_b32_e32 v7, v153, v21, vcc
	v_cmp_gt_u32_e32 vcc, s53, v8
	s_waitcnt lgkmcnt(1)
	v_mfma_f32_32x32x16_bf16 v[96:111], v[242:245], v[116:119], v[96:111]
	v_add_u32_e32 v246, s16, v166
	ds_read_b128 v[242:245], v246
	v_subrev_u32_e32 v15, 25, v0
	v_subrev_u32_e32 v176, 26, v0
	v_cndmask_b32_e32 v8, v153, v22, vcc
	v_cmp_gt_u32_e32 vcc, s53, v9
	v_subrev_u32_e32 v0, 27, v0
	s_nop 0
	v_cndmask_b32_e32 v9, v153, v23, vcc
	v_cmp_gt_u32_e32 vcc, s53, v10
	s_nop 1
	v_cndmask_b32_e32 v10, v153, v24, vcc
	v_cmp_gt_u32_e32 vcc, s53, v11
	s_nop 1
	v_cndmask_b32_e32 v11, v153, v25, vcc
	s_waitcnt lgkmcnt(1)
	v_mfma_f32_32x32x16_bf16 v[96:111], v[238:241], v[120:123], v[96:111]
	v_add_u32_e32 v246, s16, v167
	ds_read_b128 v[238:241], v246
	v_cmp_gt_u32_e32 vcc, s53, v12
	s_nop 1
	v_cndmask_b32_e32 v12, v153, v26, vcc
	v_cmp_gt_u32_e32 vcc, s53, v13
	s_nop 1
	v_cndmask_b32_e32 v13, v153, v27, vcc
	v_cmp_gt_u32_e32 vcc, s53, v14
	s_nop 1
	v_cndmask_b32_e32 v14, v153, v28, vcc
	v_cmp_gt_u32_e32 vcc, s53, v15
	s_nop 1
	v_cndmask_b32_e32 v15, v153, v29, vcc
	v_cmp_gt_u32_e32 vcc, s53, v176
	s_waitcnt lgkmcnt(1)
	v_mfma_f32_32x32x16_bf16 v[96:111], v[242:245], v[124:127], v[96:111]
	v_add_u32_e32 v246, s16, v168
	ds_read_b128 v[242:245], v246
	v_max_f32_e32 v176, v3, v3
	s_nop 0
	v_cndmask_b32_e32 v178, v153, v30, vcc
	v_cmp_gt_u32_e32 vcc, s53, v0
	v_max_f32_e32 v0, v2, v2
	v_max_f32_e32 v0, v0, v176
	v_max3_f32 v0, v0, v4, v5
	v_max3_f32 v0, v0, v6, v7
	v_max3_f32 v0, v0, v8, v9
	v_max3_f32 v0, v0, v10, v11
	v_max3_f32 v0, v0, v12, v13
	v_cndmask_b32_e32 v179, v153, v31, vcc
	v_max3_f32 v0, v0, v14, v15
	s_waitcnt lgkmcnt(1)
	v_mfma_f32_32x32x16_bf16 v[96:111], v[238:241], v[128:131], v[96:111]
	v_add_u32_e32 v246, s16, v169
	ds_read_b128 v[238:241], v246
	v_max3_f32 v0, v0, v178, v179
	v_mov_b32_e32 v176, v0
	s_nop 1
	v_permlane32_swap_b32_e32 v0, v176
	v_max_f32_e32 v176, v176, v176
	v_max_f32_e32 v0, v0, v0
	v_max_f32_e32 v0, v0, v176
	v_mul_f32_e32 v0, 0x3e0293ee, v0
	v_add_f32_e32 v176, 0x41000000, v177
	v_cmp_gt_f32_e32 vcc, v0, v176
	s_nop 1
	v_cndmask_b32_e32 v176, v177, v0, vcc
	v_max_f32_e32 v0, v176, v176
	s_waitcnt lgkmcnt(1)
	v_mfma_f32_32x32x16_bf16 v[96:111], v[242:245], v[132:135], v[96:111]
	v_add_u32_e32 v246, s16, v170
	ds_read_b128 v[242:245], v246
	v_max_f32_e32 v180, 0xe0ad78ec, v0
	v_fma_f32 v0, v2, s52, -v180
	v_exp_f32_e32 v0, v0
	v_fma_f32 v2, v3, s52, -v180
	v_exp_f32_e32 v2, v2
	v_fma_f32 v3, v4, s52, -v180
	v_exp_f32_e32 v3, v3
	v_fma_f32 v4, v5, s52, -v180
	v_exp_f32_e32 v4, v4
	v_add_f32_e32 v5, 0, v0
	v_add_f32_e32 v5, v2, v5
	v_add_f32_e32 v5, v3, v5
	v_add_f32_e32 v181, v4, v5
	s_waitcnt lgkmcnt(1)
	v_mfma_f32_32x32x16_bf16 v[96:111], v[238:241], v[136:139], v[96:111]
	v_fma_f32 v5, v6, s52, -v180
	v_exp_f32_e32 v5, v5
	v_fma_f32 v6, v7, s52, -v180
	v_exp_f32_e32 v6, v6
	v_fma_f32 v7, v8, s52, -v180
	v_exp_f32_e32 v7, v7
	v_fma_f32 v8, v9, s52, -v180
	v_exp_f32_e32 v8, v8
	v_add_f32_e32 v9, v5, v181
	v_add_f32_e32 v9, v6, v9
	v_add_f32_e32 v9, v7, v9
	v_add_f32_e32 v181, v8, v9
	v_fma_f32 v9, v10, s52, -v180
	s_waitcnt lgkmcnt(0)
	v_mfma_f32_32x32x16_bf16 v[96:111], v[242:245], v[140:143], v[96:111]
	v_exp_f32_e32 v9, v9
	v_fma_f32 v10, v11, s52, -v180
	v_exp_f32_e32 v10, v10
	v_fma_f32 v11, v12, s52, -v180
	v_exp_f32_e32 v11, v11
	v_fma_f32 v12, v13, s52, -v180
	v_exp_f32_e32 v12, v12
	v_add_f32_e32 v13, v9, v181
	v_add_f32_e32 v13, v10, v13
	v_add_f32_e32 v13, v11, v13
	v_add_f32_e32 v181, v12, v13
	v_fma_f32 v13, v14, s52, -v180
	v_exp_f32_e32 v13, v13
	v_fma_f32 v14, v15, s52, -v180
	v_exp_f32_e32 v14, v14
	v_fma_f32 v15, v178, s52, -v180
	v_exp_f32_e32 v15, v15
	v_fma_f32 v178, v179, s52, -v180
	v_exp_f32_e32 v178, v178
	v_add_f32_e32 v179, v13, v181
	v_add_f32_e32 v179, v14, v179
	v_add_f32_e32 v179, v15, v179
	v_add_f32_e32 v179, v178, v179
	v_mov_b32_e32 v180, v179
	s_nop 1
	v_permlane32_swap_b32_e32 v179, v180
	s_cbranch_vccz .Lfs_win_520
	v_sub_f32_e32 v177, v177, v176
	v_exp_f32_e32 v182, v177
	s_nop 0
	v_mul_f32_e32 v175, v175, v182
	v_mul_f32_e32 v94, v94, v182
	v_mul_f32_e32 v95, v95, v182
	v_mul_f32_e32 v92, v92, v182
	v_mul_f32_e32 v93, v93, v182
	v_mul_f32_e32 v90, v90, v182
	v_mul_f32_e32 v91, v91, v182
	v_mul_f32_e32 v88, v88, v182
	v_mul_f32_e32 v89, v89, v182
	v_mul_f32_e32 v86, v86, v182
	v_mul_f32_e32 v87, v87, v182
	v_mul_f32_e32 v84, v84, v182
	v_mul_f32_e32 v85, v85, v182
	v_mul_f32_e32 v82, v82, v182
	v_mul_f32_e32 v83, v83, v182
	v_mul_f32_e32 v80, v80, v182
	v_mul_f32_e32 v81, v81, v182
	v_mul_f32_e32 v78, v78, v182
	v_mul_f32_e32 v79, v79, v182
	v_mul_f32_e32 v76, v76, v182
	v_mul_f32_e32 v77, v77, v182
	v_mul_f32_e32 v74, v74, v182
	v_mul_f32_e32 v75, v75, v182
	v_mul_f32_e32 v72, v72, v182
	v_mul_f32_e32 v73, v73, v182
	v_mul_f32_e32 v70, v70, v182
	v_mul_f32_e32 v71, v71, v182
	v_mul_f32_e32 v68, v68, v182
	v_mul_f32_e32 v69, v69, v182
	v_mul_f32_e32 v66, v66, v182
	v_mul_f32_e32 v67, v67, v182
	v_mul_f32_e32 v64, v64, v182
	v_mul_f32_e32 v65, v65, v182
	v_mul_f32_e32 v62, v62, v182
	v_mul_f32_e32 v63, v63, v182
	v_mul_f32_e32 v60, v60, v182
	v_mul_f32_e32 v61, v61, v182
	v_mul_f32_e32 v58, v58, v182
	v_mul_f32_e32 v59, v59, v182
	v_mul_f32_e32 v56, v56, v182
	v_mul_f32_e32 v57, v57, v182
	v_mul_f32_e32 v54, v54, v182
	v_mul_f32_e32 v55, v55, v182
	v_mul_f32_e32 v52, v52, v182
	v_mul_f32_e32 v53, v53, v182
	v_mul_f32_e32 v50, v50, v182
	v_mul_f32_e32 v51, v51, v182
	v_mul_f32_e32 v48, v48, v182
	v_mul_f32_e32 v49, v49, v182
	v_mul_f32_e32 v46, v46, v182
	v_mul_f32_e32 v47, v47, v182
	v_mul_f32_e32 v44, v44, v182
	v_mul_f32_e32 v45, v45, v182
	v_mul_f32_e32 v42, v42, v182
	v_mul_f32_e32 v43, v43, v182
	v_mul_f32_e32 v40, v40, v182
	v_mul_f32_e32 v41, v41, v182
	v_mul_f32_e32 v38, v38, v182
	v_mul_f32_e32 v39, v39, v182
	v_mul_f32_e32 v36, v36, v182
	v_mul_f32_e32 v37, v37, v182
	v_mul_f32_e32 v34, v34, v182
	v_mul_f32_e32 v35, v35, v182
	v_mul_f32_e32 v32, v32, v182
	v_mul_f32_e32 v33, v33, v182

; #define LAS __attribute__((address_space(3)))
; DI float xh_max(float x) { const unsigned u = __float_as_uint(x); const auto r = __builtin_amdgcn_permlane32_swap(u, u, false, false); return fmaxf(__uint_as_float(r[0]), __uint_as_float(r[1])); }
; DI float xh_sum(float x) { const unsigned u = __float_as_uint(x); const auto r = __builtin_amdgcn_permlane32_swap(u, u, false, false); return __uint_as_float(r[0]) + __uint_as_float(r[1]); }
; #define MFMA32(a, b, c) __builtin_amdgcn_mfma_f32_32x32x16_bf16((a), (b), (c), 0, 0, 0)
; DI f32x16 co_qk1(LAS unsigned char* st, const bf16x8 (&qf)[8], int ka_in) {
;     const int ka = ka_in;
;     f32x16 S;
; #pragma unroll
;     for (int i = 0; i < 16; ++i) S[i] = 0.f;
;     __builtin_amdgcn_s_setprio(1);
; #pragma unroll
;     for (int ks = 0; ks < 8; ++ks) { const bf16x8 a = *(const LAS bf16x8*)(st + (ka ^ (32 * ks))); S = MFMA32(a, qf[ks], S); }
;     __builtin_amdgcn_s_setprio(0);
;     return S;
; }
; template <int MODE>
; DI void co_finish(f32x16 S, LAS unsigned char* st, int key_base, AttnState& as, int tq, bool rowsel, int vb_in, int hh) {
;     const int vb = vb_in;
;     {
;         const int base = key_base + 4 * hh;
;         const int hi = (MODE == 0) ? (((tq - 31) >> 4) - base) : (tq - base);
;         const int lo = hi - 512;
; #pragma unroll
;         for (int i = 0; i < 16; ++i) { const int c = (i & 3) + 8 * (i >> 2); bool ok = (c <= hi); if (MODE == 2) ok = ok && (c > lo); if (MODE == 1) ok = ok && rowsel; S[i] = ok ? S[i] : -1e30f; }
;     }
;     float mx = S[0];
; #pragma unroll
;     for (int i = 1; i < 16; ++i) mx = fmaxf(mx, S[i]);
;     mx = xh_max(mx);
;     const float mxs = mx * SM_SCALE; const bool need = mxs > as.m + 8.f;
;     const float mnew = need ? mxs : as.m, muse = -fmaxf(mnew, -1e20f); float ps = 0.f;
; #pragma unroll
;     for (int i = 0; i < 16; ++i) { const float p = __builtin_amdgcn_exp2f(__builtin_fmaf(S[i], SM_SCALE, muse)); S[i] = p; ps += p; }
;     ps = xh_sum(ps);
;     if (__builtin_amdgcn_ballot_w64(need) != 0ull) {
;         const float alpha = __builtin_amdgcn_exp2f(as.m - mnew);
;         as.l *= alpha;
; #pragma unroll
;         for (int dt = 0; dt < 4; ++dt)
; #pragma unroll
;             for (int i = 0; i < 16; ++i) as.acc[dt][i] *= alpha;
;     }
.Lfast_sel:
	v_add_u32_e32 v252, s40, v162
	ds_read_b128 v[216:219], v252
	v_add_u32_e32 v252, s40, v164
	ds_read_b128 v[220:223], v252
	v_add_u32_e32 v252, s40, v165
	ds_read_b128 v[224:227], v252
	v_add_u32_e32 v252, s40, v166
	ds_read_b128 v[228:231], v252
	v_add_u32_e32 v252, s40, v167
	ds_read_b128 v[232:235], v252
	v_add_u32_e32 v252, s40, v168
	ds_read_b128 v[240:243], v252
	v_add_u32_e32 v252, s40, v169
	ds_read_b128 v[244:247], v252
	v_add_u32_e32 v252, s40, v170
	ds_read_b128 v[248:251], v252
	v_max_f32_e32 v0, v16, v17
	v_max3_f32 v0, v0, v18, v19
	v_max3_f32 v0, v0, v20, v21
	v_max3_f32 v0, v0, v22, v23
	s_waitcnt lgkmcnt(7)
	v_mfma_f32_32x32x16_bf16 v[96:111], v[216:219], v[112:115], 0
	v_max3_f32 v0, v0, v24, v25
	v_max3_f32 v0, v0, v26, v27
	v_max3_f32 v0, v0, v28, v29
	v_max3_f32 v0, v0, v30, v31
	v_mov_b32_e32 v15, v0
	v_add_u32_e32 v253, s62, v156
	v_add_u32_e32 v254, s62, v171
	v_permlane32_swap_b32_e32 v0, v15
	ds_read_b64 v[180:181], v253 offset:8192
	ds_read_b64 v[182:183], v254 offset:8192
	ds_read_b64 v[184:185], v253 offset:10240
	ds_read_b64 v[186:187], v254 offset:10240
	ds_read_b64 v[188:189], v253 offset:12288
	ds_read_b64 v[190:191], v254 offset:12288
	ds_read_b64 v[192:193], v253 offset:14336
	ds_read_b64 v[194:195], v254 offset:14336
	v_max_f32_e32 v0, v0, v15
	s_waitcnt lgkmcnt(14)
	v_mfma_f32_32x32x16_bf16 v[96:111], v[220:223], v[116:119], v[96:111]
	v_cndmask_b32_e64 v0, v153, v0, s[26:27]
	v_mul_f32_e32 v0, 0x3e0293ee, v0
	v_add_f32_e32 v15, 0x41000000, v175
	v_cmp_gt_f32_e32 vcc, v0, v15
	v_add_u32_e32 v255, s62, v172
	v_add_u32_e32 v214, s62, v173
	v_cndmask_b32_e32 v174, v175, v0, vcc
	v_max_f32_e32 v14, 0xe0ad78ec, v174
	v_mov_b32_e32 v13, 0x7149f2ca
	v_cndmask_b32_e64 v14, v13, v14, s[26:27]
	s_waitcnt lgkmcnt(13)
	v_mfma_f32_32x32x16_bf16 v[96:111], v[224:227], v[120:123], v[96:111]
	s_cbranch_vccz .Lfast_sel_nr
	v_sub_f32_e32 v175, v175, v174
	v_exp_f32_e32 v12, v175
	s_nop 0
	v_mul_f32_e32 v163, v163, v12
	v_mul_f32_e32 v94, v94, v12
	v_mul_f32_e32 v95, v95, v12
	v_mul_f32_e32 v92, v92, v12
	v_mul_f32_e32 v93, v93, v12
	v_mul_f32_e32 v90, v90, v12
	v_mul_f32_e32 v91, v91, v12
	v_mul_f32_e32 v88, v88, v12
	v_mul_f32_e32 v89, v89, v12
	v_mul_f32_e32 v86, v86, v12
	v_mul_f32_e32 v87, v87, v12
	v_mul_f32_e32 v84, v84, v12
	v_mul_f32_e32 v85, v85, v12
	v_mul_f32_e32 v82, v82, v12
	v_mul_f32_e32 v83, v83, v12
	v_mul_f32_e32 v80, v80, v12
	v_mul_f32_e32 v81, v81, v12
	v_mul_f32_e32 v78, v78, v12
	v_mul_f32_e32 v79, v79, v12
	v_mul_f32_e32 v76, v76, v12
	v_mul_f32_e32 v77, v77, v12
	v_mul_f32_e32 v74, v74, v12
	v_mul_f32_e32 v75, v75, v12
	v_mul_f32_e32 v72, v72, v12
	v_mul_f32_e32 v73, v73, v12
	v_mul_f32_e32 v70, v70, v12
	v_mul_f32_e32 v71, v71, v12
	v_mul_f32_e32 v68, v68, v12
	v_mul_f32_e32 v69, v69, v12
	v_mul_f32_e32 v66, v66, v12
	v_mul_f32_e32 v67, v67, v12
	v_mul_f32_e32 v64, v64, v12
	v_mul_f32_e32 v65, v65, v12
	v_mul_f32_e32 v62, v62, v12
	v_mul_f32_e32 v63, v63, v12
	v_mul_f32_e32 v60, v60, v12
	v_mul_f32_e32 v61, v61, v12
	v_mul_f32_e32 v58, v58, v12
	v_mul_f32_e32 v59, v59, v12
	v_mul_f32_e32 v56, v56, v12
	v_mul_f32_e32 v57, v57, v12
	v_mul_f32_e32 v54, v54, v12
	v_mul_f32_e32 v55, v55, v12
	v_mul_f32_e32 v52, v52, v12
	v_mul_f32_e32 v53, v53, v12
	v_mul_f32_e32 v50, v50, v12
	v_mul_f32_e32 v51, v51, v12
	v_mul_f32_e32 v48, v48, v12
	v_mul_f32_e32 v49, v49, v12
	v_mul_f32_e32 v46, v46, v12
	v_mul_f32_e32 v47, v47, v12
	v_mul_f32_e32 v44, v44, v12
	v_mul_f32_e32 v45, v45, v12
	v_mul_f32_e32 v42, v42, v12
	v_mul_f32_e32 v43, v43, v12
	v_mul_f32_e32 v40, v40, v12
	v_mul_f32_e32 v41, v41, v12
	v_mul_f32_e32 v38, v38, v12
	v_mul_f32_e32 v39, v39, v12
	v_mul_f32_e32 v36, v36, v12
	v_mul_f32_e32 v37, v37, v12
	v_mul_f32_e32 v34, v34, v12
	v_mul_f32_e32 v35, v35, v12
	v_mul_f32_e32 v32, v32, v12
	v_mul_f32_e32 v33, v33, v12

; #define LAS __attribute__((address_space(3)))
; DI float xh_max(float x) { const unsigned u = __float_as_uint(x); const auto r = __builtin_amdgcn_permlane32_swap(u, u, false, false); return fmaxf(__uint_as_float(r[0]), __uint_as_float(r[1])); }
; DI float xh_sum(float x) { const unsigned u = __float_as_uint(x); const auto r = __builtin_amdgcn_permlane32_swap(u, u, false, false); return __uint_as_float(r[0]) + __uint_as_float(r[1]); }
; #define MFMA32(a, b, c) __builtin_amdgcn_mfma_f32_32x32x16_bf16((a), (b), (c), 0, 0, 0)
; DI f32x16 co_qk1(LAS unsigned char* st, const bf16x8 (&qf)[8], int ka_in) {
;     const int ka = ka_in;
;     f32x16 S;
; #pragma unroll
;     for (int i = 0; i < 16; ++i) S[i] = 0.f;
;     __builtin_amdgcn_s_setprio(1);
; #pragma unroll
;     for (int ks = 0; ks < 8; ++ks) { const bf16x8 a = *(const LAS bf16x8*)(st + (ka ^ (32 * ks))); S = MFMA32(a, qf[ks], S); }
;     __builtin_amdgcn_s_setprio(0);
;     return S;
; }
; template <int MODE>
; DI void co_finish(f32x16 S, LAS unsigned char* st, int key_base, AttnState& as, int tq, bool rowsel, int vb_in, int hh) {
;     const int vb = vb_in;
;     {
;         const int base = key_base + 4 * hh;
;         const int hi = (MODE == 0) ? (((tq - 31) >> 4) - base) : (tq - base);
;         const int lo = hi - 512;
; #pragma unroll
;         for (int i = 0; i < 16; ++i) { const int c = (i & 3) + 8 * (i >> 2); bool ok = (c <= hi); if (MODE == 2) ok = ok && (c > lo); if (MODE == 1) ok = ok && rowsel; S[i] = ok ? S[i] : -1e30f; }
;     }
;     float mx = S[0];
; #pragma unroll
;     for (int i = 1; i < 16; ++i) mx = fmaxf(mx, S[i]);
;     mx = xh_max(mx);
;     const float mxs = mx * SM_SCALE; const bool need = mxs > as.m + 8.f;
;     const float mnew = need ? mxs : as.m, muse = -fmaxf(mnew, -1e20f); float ps = 0.f;
; #pragma unroll
;     for (int i = 0; i < 16; ++i) { const float p = __builtin_amdgcn_exp2f(__builtin_fmaf(S[i], SM_SCALE, muse)); S[i] = p; ps += p; }
;     ps = xh_sum(ps);
;     if (__builtin_amdgcn_ballot_w64(need) != 0ull) {
;         const float alpha = __builtin_amdgcn_exp2f(as.m - mnew);
;         as.l *= alpha;
; #pragma unroll
;         for (int dt = 0; dt < 4; ++dt)
; #pragma unroll
;             for (int i = 0; i < 16; ++i) as.acc[dt][i] *= alpha;
;     }
.Lfast_win:
	v_add_u32_e32 v252, s16, v162
	ds_read_b128 v[216:219], v252
	v_add_u32_e32 v252, s16, v164
	ds_read_b128 v[220:223], v252
	v_add_u32_e32 v252, s16, v165
	ds_read_b128 v[224:227], v252
	v_add_u32_e32 v252, s16, v166
	ds_read_b128 v[228:231], v252
	v_add_u32_e32 v252, s16, v167
	ds_read_b128 v[232:235], v252
	v_add_u32_e32 v252, s16, v168
	ds_read_b128 v[240:243], v252
	v_add_u32_e32 v252, s16, v169
	ds_read_b128 v[244:247], v252
	v_add_u32_e32 v252, s16, v170
	ds_read_b128 v[248:251], v252
	v_max_f32_e32 v0, v16, v17
	v_max3_f32 v0, v0, v18, v19
	v_max3_f32 v0, v0, v20, v21
	v_max3_f32 v0, v0, v22, v23
	s_waitcnt lgkmcnt(7)
	v_mfma_f32_32x32x16_bf16 v[96:111], v[216:219], v[112:115], 0
	v_max3_f32 v0, v0, v24, v25
	v_max3_f32 v0, v0, v26, v27
	v_max3_f32 v0, v0, v28, v29
	v_max3_f32 v0, v0, v30, v31
	v_mov_b32_e32 v15, v0
	v_add_u32_e32 v253, s62, v156
	v_add_u32_e32 v254, s62, v171
	v_permlane32_swap_b32_e32 v0, v15
	ds_read_b64 v[180:181], v253 offset:8192
	ds_read_b64 v[182:183], v254 offset:8192
	ds_read_b64 v[184:185], v253 offset:10240
	ds_read_b64 v[186:187], v254 offset:10240
	ds_read_b64 v[188:189], v253 offset:12288
	ds_read_b64 v[190:191], v254 offset:12288
	ds_read_b64 v[192:193], v253 offset:14336
	ds_read_b64 v[194:195], v254 offset:14336
	v_max_f32_e32 v0, v0, v15
	s_waitcnt lgkmcnt(14)
	v_mfma_f32_32x32x16_bf16 v[96:111], v[220:223], v[116:119], v[96:111]
	v_mul_f32_e32 v0, 0x3e0293ee, v0
	v_add_f32_e32 v15, 0x41000000, v177
	v_cmp_gt_f32_e32 vcc, v0, v15
	v_add_u32_e32 v255, s62, v172
	v_add_u32_e32 v214, s62, v173
	v_cndmask_b32_e32 v176, v177, v0, vcc
	v_max_f32_e32 v14, 0xe0ad78ec, v176
	s_waitcnt lgkmcnt(13)
	v_mfma_f32_32x32x16_bf16 v[96:111], v[224:227], v[120:123], v[96:111]
	s_cbranch_vccz .Lfast_win_nr
	v_sub_f32_e32 v177, v177, v176
	v_exp_f32_e32 v12, v177
	s_nop 0
	v_mul_f32_e32 v175, v175, v12
	v_mul_f32_e32 v94, v94, v12
	v_mul_f32_e32 v95, v95, v12
	v_mul_f32_e32 v92, v92, v12
	v_mul_f32_e32 v93, v93, v12
	v_mul_f32_e32 v90, v90, v12
	v_mul_f32_e32 v91, v91, v12
	v_mul_f32_e32 v88, v88, v12
	v_mul_f32_e32 v89, v89, v12
	v_mul_f32_e32 v86, v86, v12
	v_mul_f32_e32 v87, v87, v12
	v_mul_f32_e32 v84, v84, v12
	v_mul_f32_e32 v85, v85, v12
	v_mul_f32_e32 v82, v82, v12
	v_mul_f32_e32 v83, v83, v12
	v_mul_f32_e32 v80, v80, v12
	v_mul_f32_e32 v81, v81, v12
	v_mul_f32_e32 v78, v78, v12
	v_mul_f32_e32 v79, v79, v12
	v_mul_f32_e32 v76, v76, v12
	v_mul_f32_e32 v77, v77, v12
	v_mul_f32_e32 v74, v74, v12
	v_mul_f32_e32 v75, v75, v12
	v_mul_f32_e32 v72, v72, v12
	v_mul_f32_e32 v73, v73, v12
	v_mul_f32_e32 v70, v70, v12
	v_mul_f32_e32 v71, v71, v12
	v_mul_f32_e32 v68, v68, v12
	v_mul_f32_e32 v69, v69, v12
	v_mul_f32_e32 v66, v66, v12
	v_mul_f32_e32 v67, v67, v12
	v_mul_f32_e32 v64, v64, v12
	v_mul_f32_e32 v65, v65, v12
	v_mul_f32_e32 v62, v62, v12
	v_mul_f32_e32 v63, v63, v12
	v_mul_f32_e32 v60, v60, v12
	v_mul_f32_e32 v61, v61, v12
	v_mul_f32_e32 v58, v58, v12
	v_mul_f32_e32 v59, v59, v12
	v_mul_f32_e32 v56, v56, v12
	v_mul_f32_e32 v57, v57, v12
	v_mul_f32_e32 v54, v54, v12
	v_mul_f32_e32 v55, v55, v12
	v_mul_f32_e32 v52, v52, v12
	v_mul_f32_e32 v53, v53, v12
	v_mul_f32_e32 v50, v50, v12
	v_mul_f32_e32 v51, v51, v12
	v_mul_f32_e32 v48, v48, v12
	v_mul_f32_e32 v49, v49, v12
	v_mul_f32_e32 v46, v46, v12
	v_mul_f32_e32 v47, v47, v12
	v_mul_f32_e32 v44, v44, v12
	v_mul_f32_e32 v45, v45, v12
	v_mul_f32_e32 v42, v42, v12
	v_mul_f32_e32 v43, v43, v12
	v_mul_f32_e32 v40, v40, v12
	v_mul_f32_e32 v41, v41, v12
	v_mul_f32_e32 v38, v38, v12
	v_mul_f32_e32 v39, v39, v12
	v_mul_f32_e32 v36, v36, v12
	v_mul_f32_e32 v37, v37, v12
	v_mul_f32_e32 v34, v34, v12
	v_mul_f32_e32 v35, v35, v12
	v_mul_f32_e32 v32, v32, v12
	v_mul_f32_e32 v33, v33, v12

; DI float xh_max(float x) { const unsigned u = __float_as_uint(x); const auto r = __builtin_amdgcn_permlane32_swap(u, u, false, false); return fmaxf(__uint_as_float(r[0]), __uint_as_float(r[1])); }
; DI float xh_sum(float x) { const unsigned u = __float_as_uint(x); const auto r = __builtin_amdgcn_permlane32_swap(u, u, false, false); return __uint_as_float(r[0]) + __uint_as_float(r[1]); }
; template <int MODE>
; DI void co_finish(f32x16 S, LAS unsigned char* st, int key_base, AttnState& as, int tq, bool rowsel, int vb_in, int hh) {
;     ...
;     float mx = S[0];
; #pragma unroll
;     for (int i = 1; i < 16; ++i) mx = fmaxf(mx, S[i]);
;     mx = xh_max(mx);
;     const float mxs = mx * SM_SCALE; const bool need = mxs > as.m + 8.f;
;     const float mnew = need ? mxs : as.m, muse = -fmaxf(mnew, -1e20f); float ps = 0.f;
; #pragma unroll
;     for (int i = 0; i < 16; ++i) { const float p = __builtin_amdgcn_exp2f(__builtin_fmaf(S[i], SM_SCALE, muse)); S[i] = p; ps += p; }
;     ps = xh_sum(ps);
;     if (__builtin_amdgcn_ballot_w64(need) != 0ull) {
;         const float alpha = __builtin_amdgcn_exp2f(as.m - mnew);
;         as.l *= alpha;
; #pragma unroll
;         for (int dt = 0; dt < 4; ++dt)
; #pragma unroll
;             for (int i = 0; i < 16; ++i) as.acc[dt][i] *= alpha;
;     }
.Lfastf_sel:
	v_max_f32_e32 v0, v16, v17
	v_max3_f32 v0, v0, v18, v19
	v_max3_f32 v0, v0, v20, v21
	v_max3_f32 v0, v0, v22, v23
	v_max3_f32 v0, v0, v24, v25
	v_max3_f32 v0, v0, v26, v27
	v_max3_f32 v0, v0, v28, v29
	v_max3_f32 v0, v0, v30, v31
	v_mov_b32_e32 v15, v0
	v_add_u32_e32 v253, s62, v156
	v_add_u32_e32 v254, s62, v171
	v_permlane32_swap_b32_e32 v0, v15
	ds_read_b64 v[180:181], v253 offset:8192
	ds_read_b64 v[182:183], v254 offset:8192
	ds_read_b64 v[184:185], v253 offset:10240
	ds_read_b64 v[186:187], v254 offset:10240
	ds_read_b64 v[188:189], v253 offset:12288
	ds_read_b64 v[190:191], v254 offset:12288
	ds_read_b64 v[192:193], v253 offset:14336
	ds_read_b64 v[194:195], v254 offset:14336
	v_max_f32_e32 v0, v0, v15
	v_cndmask_b32_e64 v0, v153, v0, s[26:27]
	v_mul_f32_e32 v0, 0x3e0293ee, v0
	v_add_f32_e32 v15, 0x41000000, v175
	v_cmp_gt_f32_e32 vcc, v0, v15
	v_add_u32_e32 v255, s62, v172
	v_add_u32_e32 v214, s62, v173
	v_cndmask_b32_e32 v174, v175, v0, vcc
	v_max_f32_e32 v14, 0xe0ad78ec, v174
	v_mov_b32_e32 v13, 0x7149f2ca
	v_cndmask_b32_e64 v14, v13, v14, s[26:27]
	s_cbranch_vccz .Lfastf_sel_nr
	v_sub_f32_e32 v175, v175, v174
	v_exp_f32_e32 v12, v175
	s_nop 0
	v_mul_f32_e32 v163, v163, v12
	v_mul_f32_e32 v94, v94, v12
	v_mul_f32_e32 v95, v95, v12
	v_mul_f32_e32 v92, v92, v12
	v_mul_f32_e32 v93, v93, v12
	v_mul_f32_e32 v90, v90, v12
	v_mul_f32_e32 v91, v91, v12
	v_mul_f32_e32 v88, v88, v12
	v_mul_f32_e32 v89, v89, v12
	v_mul_f32_e32 v86, v86, v12
	v_mul_f32_e32 v87, v87, v12
	v_mul_f32_e32 v84, v84, v12
	v_mul_f32_e32 v85, v85, v12
	v_mul_f32_e32 v82, v82, v12
	v_mul_f32_e32 v83, v83, v12
	v_mul_f32_e32 v80, v80, v12
	v_mul_f32_e32 v81, v81, v12
	v_mul_f32_e32 v78, v78, v12
	v_mul_f32_e32 v79, v79, v12
	v_mul_f32_e32 v76, v76, v12
	v_mul_f32_e32 v77, v77, v12
	v_mul_f32_e32 v74, v74, v12
	v_mul_f32_e32 v75, v75, v12
	v_mul_f32_e32 v72, v72, v12
	v_mul_f32_e32 v73, v73, v12
	v_mul_f32_e32 v70, v70, v12
	v_mul_f32_e32 v71, v71, v12
	v_mul_f32_e32 v68, v68, v12
	v_mul_f32_e32 v69, v69, v12
	v_mul_f32_e32 v66, v66, v12
	v_mul_f32_e32 v67, v67, v12
	v_mul_f32_e32 v64, v64, v12
	v_mul_f32_e32 v65, v65, v12
	v_mul_f32_e32 v62, v62, v12
	v_mul_f32_e32 v63, v63, v12
	v_mul_f32_e32 v60, v60, v12
	v_mul_f32_e32 v61, v61, v12
	v_mul_f32_e32 v58, v58, v12
	v_mul_f32_e32 v59, v59, v12
	v_mul_f32_e32 v56, v56, v12
	v_mul_f32_e32 v57, v57, v12
	v_mul_f32_e32 v54, v54, v12
	v_mul_f32_e32 v55, v55, v12
	v_mul_f32_e32 v52, v52, v12
	v_mul_f32_e32 v53, v53, v12
	v_mul_f32_e32 v50, v50, v12
	v_mul_f32_e32 v51, v51, v12
	v_mul_f32_e32 v48, v48, v12
	v_mul_f32_e32 v49, v49, v12
	v_mul_f32_e32 v46, v46, v12
	v_mul_f32_e32 v47, v47, v12
	v_mul_f32_e32 v44, v44, v12
	v_mul_f32_e32 v45, v45, v12
	v_mul_f32_e32 v42, v42, v12
	v_mul_f32_e32 v43, v43, v12
	v_mul_f32_e32 v40, v40, v12
	v_mul_f32_e32 v41, v41, v12
	v_mul_f32_e32 v38, v38, v12
	v_mul_f32_e32 v39, v39, v12
	v_mul_f32_e32 v36, v36, v12
	v_mul_f32_e32 v37, v37, v12
	v_mul_f32_e32 v34, v34, v12
	v_mul_f32_e32 v35, v35, v12
	v_mul_f32_e32 v32, v32, v12
	v_mul_f32_e32 v33, v33, v12

; DI float xh_max(float x) { const unsigned u = __float_as_uint(x); const auto r = __builtin_amdgcn_permlane32_swap(u, u, false, false); return fmaxf(__uint_as_float(r[0]), __uint_as_float(r[1])); }
; DI float xh_sum(float x) { const unsigned u = __float_as_uint(x); const auto r = __builtin_amdgcn_permlane32_swap(u, u, false, false); return __uint_as_float(r[0]) + __uint_as_float(r[1]); }
; template <int MODE>
; DI void co_finish(f32x16 S, LAS unsigned char* st, int key_base, AttnState& as, int tq, bool rowsel, int vb_in, int hh) {
;     ...
;     float mx = S[0];
; #pragma unroll
;     for (int i = 1; i < 16; ++i) mx = fmaxf(mx, S[i]);
;     mx = xh_max(mx);
;     const float mxs = mx * SM_SCALE; const bool need = mxs > as.m + 8.f;
;     const float mnew = need ? mxs : as.m, muse = -fmaxf(mnew, -1e20f); float ps = 0.f;
; #pragma unroll
;     for (int i = 0; i < 16; ++i) { const float p = __builtin_amdgcn_exp2f(__builtin_fmaf(S[i], SM_SCALE, muse)); S[i] = p; ps += p; }
;     ps = xh_sum(ps);
;     if (__builtin_amdgcn_ballot_w64(need) != 0ull) {
;         const float alpha = __builtin_amdgcn_exp2f(as.m - mnew);
;         as.l *= alpha;
; #pragma unroll
;         for (int dt = 0; dt < 4; ++dt)
; #pragma unroll
;             for (int i = 0; i < 16; ++i) as.acc[dt][i] *= alpha;
;     }
.Lfastf_win:
	v_max_f32_e32 v0, v16, v17
	v_max3_f32 v0, v0, v18, v19
	v_max3_f32 v0, v0, v20, v21
	v_max3_f32 v0, v0, v22, v23
	v_max3_f32 v0, v0, v24, v25
	v_max3_f32 v0, v0, v26, v27
	v_max3_f32 v0, v0, v28, v29
	v_max3_f32 v0, v0, v30, v31
	v_mov_b32_e32 v15, v0
	v_add_u32_e32 v253, s62, v156
	v_add_u32_e32 v254, s62, v171
	v_permlane32_swap_b32_e32 v0, v15
	ds_read_b64 v[180:181], v253 offset:8192
	ds_read_b64 v[182:183], v254 offset:8192
	ds_read_b64 v[184:185], v253 offset:10240
	ds_read_b64 v[186:187], v254 offset:10240
	ds_read_b64 v[188:189], v253 offset:12288
	ds_read_b64 v[190:191], v254 offset:12288
	ds_read_b64 v[192:193], v253 offset:14336
	ds_read_b64 v[194:195], v254 offset:14336
	v_max_f32_e32 v0, v0, v15
	v_mul_f32_e32 v0, 0x3e0293ee, v0
	v_add_f32_e32 v15, 0x41000000, v177
	v_cmp_gt_f32_e32 vcc, v0, v15
	v_add_u32_e32 v255, s62, v172
	v_add_u32_e32 v214, s62, v173
	v_cndmask_b32_e32 v176, v177, v0, vcc
	v_max_f32_e32 v14, 0xe0ad78ec, v176
	s_cbranch_vccz .Lfastf_win_nr
	v_sub_f32_e32 v177, v177, v176
	v_exp_f32_e32 v12, v177
	s_nop 0
	v_mul_f32_e32 v175, v175, v12
	v_mul_f32_e32 v94, v94, v12
	v_mul_f32_e32 v95, v95, v12
	v_mul_f32_e32 v92, v92, v12
	v_mul_f32_e32 v93, v93, v12
	v_mul_f32_e32 v90, v90, v12
	v_mul_f32_e32 v91, v91, v12
	v_mul_f32_e32 v88, v88, v12
	v_mul_f32_e32 v89, v89, v12
	v_mul_f32_e32 v86, v86, v12
	v_mul_f32_e32 v87, v87, v12
	v_mul_f32_e32 v84, v84, v12
	v_mul_f32_e32 v85, v85, v12
	v_mul_f32_e32 v82, v82, v12
	v_mul_f32_e32 v83, v83, v12
	v_mul_f32_e32 v80, v80, v12
	v_mul_f32_e32 v81, v81, v12
	v_mul_f32_e32 v78, v78, v12
	v_mul_f32_e32 v79, v79, v12
	v_mul_f32_e32 v76, v76, v12
	v_mul_f32_e32 v77, v77, v12
	v_mul_f32_e32 v74, v74, v12
	v_mul_f32_e32 v75, v75, v12
	v_mul_f32_e32 v72, v72, v12
	v_mul_f32_e32 v73, v73, v12
	v_mul_f32_e32 v70, v70, v12
	v_mul_f32_e32 v71, v71, v12
	v_mul_f32_e32 v68, v68, v12
	v_mul_f32_e32 v69, v69, v12
	v_mul_f32_e32 v66, v66, v12
	v_mul_f32_e32 v67, v67, v12
	v_mul_f32_e32 v64, v64, v12
	v_mul_f32_e32 v65, v65, v12
	v_mul_f32_e32 v62, v62, v12
	v_mul_f32_e32 v63, v63, v12
	v_mul_f32_e32 v60, v60, v12
	v_mul_f32_e32 v61, v61, v12
	v_mul_f32_e32 v58, v58, v12
	v_mul_f32_e32 v59, v59, v12
	v_mul_f32_e32 v56, v56, v12
	v_mul_f32_e32 v57, v57, v12
	v_mul_f32_e32 v54, v54, v12
	v_mul_f32_e32 v55, v55, v12
	v_mul_f32_e32 v52, v52, v12
	v_mul_f32_e32 v53, v53, v12
	v_mul_f32_e32 v50, v50, v12
	v_mul_f32_e32 v51, v51, v12
	v_mul_f32_e32 v48, v48, v12
	v_mul_f32_e32 v49, v49, v12
	v_mul_f32_e32 v46, v46, v12
	v_mul_f32_e32 v47, v47, v12
	v_mul_f32_e32 v44, v44, v12
	v_mul_f32_e32 v45, v45, v12
	v_mul_f32_e32 v42, v42, v12
	v_mul_f32_e32 v43, v43, v12
	v_mul_f32_e32 v40, v40, v12
	v_mul_f32_e32 v41, v41, v12
	v_mul_f32_e32 v38, v38, v12
	v_mul_f32_e32 v39, v39, v12
	v_mul_f32_e32 v36, v36, v12
	v_mul_f32_e32 v37, v37, v12
	v_mul_f32_e32 v34, v34, v12
	v_mul_f32_e32 v35, v35, v12
	v_mul_f32_e32 v32, v32, v12
	v_mul_f32_e32 v33, v33, v12

; #define LAS __attribute__((address_space(3)))
; DI float xh_max(float x) { const unsigned u = __float_as_uint(x); const auto r = __builtin_amdgcn_permlane32_swap(u, u, false, false); return fmaxf(__uint_as_float(r[0]), __uint_as_float(r[1])); }
; DI float xh_sum(float x) { const unsigned u = __float_as_uint(x); const auto r = __builtin_amdgcn_permlane32_swap(u, u, false, false); return __uint_as_float(r[0]) + __uint_as_float(r[1]); }
; #define MFMA32(a, b, c) __builtin_amdgcn_mfma_f32_32x32x16_bf16((a), (b), (c), 0, 0, 0)
; DI f32x16 co_qk1(LAS unsigned char* st, const bf16x8 (&qf)[8], int ka_in) {
;     const int ka = ka_in;
;     f32x16 S;
; #pragma unroll
;     for (int i = 0; i < 16; ++i) S[i] = 0.f;
;     __builtin_amdgcn_s_setprio(1);
; #pragma unroll
;     for (int ks = 0; ks < 8; ++ks) { const bf16x8 a = *(const LAS bf16x8*)(st + (ka ^ (32 * ks))); S = MFMA32(a, qf[ks], S); }
;     __builtin_amdgcn_s_setprio(0);
;     return S;
; }
; template <int MODE>
; DI void co_finish(f32x16 S, LAS unsigned char* st, int key_base, AttnState& as, int tq, bool rowsel, int vb_in, int hh) {
;     const int vb = vb_in;
;     {
;         const int base = key_base + 4 * hh;
;         const int hi = (MODE == 0) ? (((tq - 31) >> 4) - base) : (tq - base);
;         const int lo = hi - 512;
; #pragma unroll
;         for (int i = 0; i < 16; ++i) { const int c = (i & 3) + 8 * (i >> 2); bool ok = (c <= hi); if (MODE == 2) ok = ok && (c > lo); if (MODE == 1) ok = ok && rowsel; S[i] = ok ? S[i] : -1e30f; }
;     }
;     float mx = S[0];
; #pragma unroll
;     for (int i = 1; i < 16; ++i) mx = fmaxf(mx, S[i]);
;     mx = xh_max(mx);
;     const float mxs = mx * SM_SCALE; const bool need = mxs > as.m + 8.f;
;     const float mnew = need ? mxs : as.m, muse = -fmaxf(mnew, -1e20f); float ps = 0.f;
; #pragma unroll
;     for (int i = 0; i < 16; ++i) { const float p = __builtin_amdgcn_exp2f(__builtin_fmaf(S[i], SM_SCALE, muse)); S[i] = p; ps += p; }
;     ps = xh_sum(ps);
;     if (__builtin_amdgcn_ballot_w64(need) != 0ull) {
;         const float alpha = __builtin_amdgcn_exp2f(as.m - mnew);
;         as.l *= alpha;
; #pragma unroll
;         for (int dt = 0; dt < 4; ++dt)
; #pragma unroll
;             for (int i = 0; i < 16; ++i) as.acc[dt][i] *= alpha;
;     }
.Lfs_cmp:
	v_add_u32_e32 v246, s16, v162
	ds_read_b128 v[238:241], v246
	v_add_u32_e32 v246, s16, v164
	ds_read_b128 v[242:245], v246
	v_add_u32_e32 v0, s80, v180
	v_cmp_lt_i32_e32 vcc, -1, v0
	s_nop 1
	v_cndmask_b32_e32 v3, v153, v16, vcc
	v_cmp_lt_i32_e32 vcc, 0, v0
	v_max_f32_e32 v2, v3, v3
	s_nop 0
	v_cndmask_b32_e32 v4, v153, v17, vcc
	v_cmp_lt_i32_e32 vcc, 1, v0
	s_nop 1
	v_cndmask_b32_e32 v5, v153, v18, vcc
	v_cmp_lt_i32_e32 vcc, 2, v0
	s_waitcnt lgkmcnt(1)
	v_mfma_f32_32x32x16_bf16 v[96:111], v[238:241], v[112:115], 0
	v_add_u32_e32 v246, s16, v165
	ds_read_b128 v[238:241], v246
	s_nop 1
	v_cndmask_b32_e32 v6, v153, v19, vcc
	v_cmp_lt_i32_e32 vcc, 7, v0
	s_nop 1
	v_cndmask_b32_e32 v7, v153, v20, vcc
	v_cmp_lt_i32_e32 vcc, 8, v0
	s_nop 1
	v_cndmask_b32_e32 v8, v153, v21, vcc
	v_cmp_lt_i32_e32 vcc, 9, v0
	s_nop 1
	v_cndmask_b32_e32 v9, v153, v22, vcc
	v_cmp_lt_i32_e32 vcc, 10, v0
	s_waitcnt lgkmcnt(1)
	v_mfma_f32_32x32x16_bf16 v[96:111], v[242:245], v[116:119], v[96:111]
	v_add_u32_e32 v246, s16, v166
	ds_read_b128 v[242:245], v246
	s_nop 1
	v_cndmask_b32_e32 v10, v153, v23, vcc
	v_cmp_lt_i32_e32 vcc, 15, v0
	s_nop 1
	v_cndmask_b32_e32 v11, v153, v24, vcc
	v_cmp_lt_i32_e32 vcc, 16, v0
	s_nop 1
	v_cndmask_b32_e32 v12, v153, v25, vcc
	v_cmp_lt_i32_e32 vcc, 17, v0
	s_nop 1
	v_cndmask_b32_e32 v13, v153, v26, vcc
	v_cmp_lt_i32_e32 vcc, 18, v0
	s_waitcnt lgkmcnt(1)
	v_mfma_f32_32x32x16_bf16 v[96:111], v[238:241], v[120:123], v[96:111]
	v_add_u32_e32 v246, s16, v167
	ds_read_b128 v[238:241], v246
	s_nop 1
	v_cndmask_b32_e32 v14, v153, v27, vcc
	v_cmp_lt_i32_e32 vcc, 23, v0
	s_nop 1
	v_cndmask_b32_e32 v15, v153, v28, vcc
	v_cmp_lt_i32_e32 vcc, 24, v0
	s_nop 1
	v_cndmask_b32_e32 v182, v153, v29, vcc
	v_cmp_lt_i32_e32 vcc, 25, v0
	s_nop 1
	v_cndmask_b32_e32 v183, v153, v30, vcc
	v_cmp_lt_i32_e32 vcc, 26, v0
	s_waitcnt lgkmcnt(1)
	v_mfma_f32_32x32x16_bf16 v[96:111], v[242:245], v[124:127], v[96:111]
	v_add_u32_e32 v246, s16, v168
	ds_read_b128 v[242:245], v246
	v_max_f32_e32 v0, v4, v4
	v_max_f32_e32 v0, v2, v0
	v_max3_f32 v0, v0, v5, v6
	v_max3_f32 v0, v0, v7, v8
	v_max3_f32 v0, v0, v9, v10
	v_max3_f32 v0, v0, v11, v12
	v_max3_f32 v0, v0, v13, v14
	v_cndmask_b32_e32 v184, v153, v31, vcc
	v_max3_f32 v0, v0, v15, v182
	v_max3_f32 v0, v0, v183, v184
	v_mov_b32_e32 v2, v0
	s_nop 1
	v_permlane32_swap_b32_e32 v0, v2
	s_waitcnt lgkmcnt(1)
	v_mfma_f32_32x32x16_bf16 v[96:111], v[238:241], v[128:131], v[96:111]
	v_add_u32_e32 v246, s16, v169
	ds_read_b128 v[238:241], v246
	v_max_f32_e32 v2, v2, v2
	v_max_f32_e32 v0, v0, v0
	v_max_f32_e32 v0, v0, v2
	v_mul_f32_e32 v0, 0x3e0293ee, v0
	v_add_f32_e32 v2, 0x41000000, v181
	v_cmp_gt_f32_e32 vcc, v0, v2
	s_nop 1
	v_cndmask_b32_e32 v2, v181, v0, vcc
	v_max_f32_e32 v0, v2, v2
	v_max_f32_e32 v185, 0xe0ad78ec, v0
	v_fma_f32 v0, v3, s52, -v185
	v_exp_f32_e32 v0, v0
	s_waitcnt lgkmcnt(1)
	v_mfma_f32_32x32x16_bf16 v[96:111], v[242:245], v[132:135], v[96:111]
	v_add_u32_e32 v246, s16, v170
	ds_read_b128 v[242:245], v246
	v_fma_f32 v3, v4, s52, -v185
	v_exp_f32_e32 v3, v3
	v_fma_f32 v4, v5, s52, -v185
	v_exp_f32_e32 v4, v4
	v_fma_f32 v5, v6, s52, -v185
	v_exp_f32_e32 v5, v5
	v_add_f32_e32 v6, 0, v0
	v_add_f32_e32 v6, v3, v6
	v_add_f32_e32 v6, v4, v6
	v_add_f32_e32 v186, v5, v6
	v_fma_f32 v6, v7, s52, -v185
	v_exp_f32_e32 v6, v6
	s_waitcnt lgkmcnt(1)
	v_mfma_f32_32x32x16_bf16 v[96:111], v[238:241], v[136:139], v[96:111]
	v_fma_f32 v7, v8, s52, -v185
	v_exp_f32_e32 v7, v7
	v_fma_f32 v8, v9, s52, -v185
	v_exp_f32_e32 v8, v8
	v_fma_f32 v9, v10, s52, -v185
	v_exp_f32_e32 v9, v9
	v_add_f32_e32 v10, v6, v186
	v_add_f32_e32 v10, v7, v10
	v_add_f32_e32 v10, v8, v10
	v_add_f32_e32 v186, v9, v10
	v_fma_f32 v10, v11, s52, -v185
	v_exp_f32_e32 v10, v10
	s_waitcnt lgkmcnt(0)
	v_mfma_f32_32x32x16_bf16 v[96:111], v[242:245], v[140:143], v[96:111]
	v_fma_f32 v11, v12, s52, -v185
	v_exp_f32_e32 v11, v11
	v_fma_f32 v12, v13, s52, -v185
	v_exp_f32_e32 v12, v12
	v_fma_f32 v13, v14, s52, -v185
	v_exp_f32_e32 v13, v13
	v_add_f32_e32 v14, v10, v186
	v_add_f32_e32 v14, v11, v14
	v_add_f32_e32 v14, v12, v14
	v_add_f32_e32 v186, v13, v14
	v_fma_f32 v14, v15, s52, -v185
	v_exp_f32_e32 v14, v14
	v_fma_f32 v15, v182, s52, -v185
	v_exp_f32_e32 v15, v15
	v_fma_f32 v182, v183, s52, -v185
	v_exp_f32_e32 v182, v182
	v_fma_f32 v183, v184, s52, -v185
	v_exp_f32_e32 v183, v183
	v_add_f32_e32 v184, v14, v186
	v_add_f32_e32 v184, v15, v184
	v_add_f32_e32 v184, v182, v184
	v_add_f32_e32 v184, v183, v184
	v_mov_b32_e32 v185, v184
	s_nop 1
	v_permlane32_swap_b32_e32 v184, v185
	s_cbranch_vccz .Lfs_cmp_427
	v_sub_f32_e32 v181, v181, v2
	v_exp_f32_e32 v186, v181
	s_nop 0
	v_mul_f32_e32 v179, v179, v186
	v_mul_f32_e32 v94, v94, v186
	v_mul_f32_e32 v95, v95, v186
	v_mul_f32_e32 v92, v92, v186
	v_mul_f32_e32 v93, v93, v186
	v_mul_f32_e32 v90, v90, v186
	v_mul_f32_e32 v91, v91, v186
	v_mul_f32_e32 v88, v88, v186
	v_mul_f32_e32 v89, v89, v186
	v_mul_f32_e32 v86, v86, v186
	v_mul_f32_e32 v87, v87, v186
	v_mul_f32_e32 v84, v84, v186
	v_mul_f32_e32 v85, v85, v186
	v_mul_f32_e32 v82, v82, v186
	v_mul_f32_e32 v83, v83, v186
	v_mul_f32_e32 v80, v80, v186
	v_mul_f32_e32 v81, v81, v186
	v_mul_f32_e32 v78, v78, v186
	v_mul_f32_e32 v79, v79, v186
	v_mul_f32_e32 v76, v76, v186
	v_mul_f32_e32 v77, v77, v186
	v_mul_f32_e32 v74, v74, v186
	v_mul_f32_e32 v75, v75, v186
	v_mul_f32_e32 v72, v72, v186
	v_mul_f32_e32 v73, v73, v186
	v_mul_f32_e32 v70, v70, v186
	v_mul_f32_e32 v71, v71, v186
	v_mul_f32_e32 v68, v68, v186
	v_mul_f32_e32 v69, v69, v186
	v_mul_f32_e32 v66, v66, v186
	v_mul_f32_e32 v67, v67, v186
	v_mul_f32_e32 v64, v64, v186
	v_mul_f32_e32 v65, v65, v186
	v_mul_f32_e32 v62, v62, v186
	v_mul_f32_e32 v63, v63, v186
	v_mul_f32_e32 v60, v60, v186
	v_mul_f32_e32 v61, v61, v186
	v_mul_f32_e32 v58, v58, v186
	v_mul_f32_e32 v59, v59, v186
	v_mul_f32_e32 v56, v56, v186
	v_mul_f32_e32 v57, v57, v186
	v_mul_f32_e32 v54, v54, v186
	v_mul_f32_e32 v55, v55, v186
	v_mul_f32_e32 v52, v52, v186
	v_mul_f32_e32 v53, v53, v186
	v_mul_f32_e32 v50, v50, v186
	v_mul_f32_e32 v51, v51, v186
	v_mul_f32_e32 v48, v48, v186
	v_mul_f32_e32 v49, v49, v186
	v_mul_f32_e32 v46, v46, v186
	v_mul_f32_e32 v47, v47, v186
	v_mul_f32_e32 v44, v44, v186
	v_mul_f32_e32 v45, v45, v186
	v_mul_f32_e32 v42, v42, v186
	v_mul_f32_e32 v43, v43, v186
	v_mul_f32_e32 v40, v40, v186
	v_mul_f32_e32 v41, v41, v186
	v_mul_f32_e32 v38, v38, v186
	v_mul_f32_e32 v39, v39, v186
	v_mul_f32_e32 v36, v36, v186
	v_mul_f32_e32 v37, v37, v186
	v_mul_f32_e32 v34, v34, v186
	v_mul_f32_e32 v35, v35, v186
	v_mul_f32_e32 v32, v32, v186
	v_mul_f32_e32 v33, v33, v186
